# Proj0/Proj1 epilogue rope8: shfl_xor(v,16) via v_permlane16_swap of two copies + select instead of ds_bpermute round trips (248 sites)
# baseline (speedup 1.0000x reference)
; DI void rope8(float (&v)[8], const float* __restrict__ rope, int s, int fq) {
;     const f32x4 c0 = *(const f32x4*)(rope + s * 16), c1 = *(const f32x4*)(rope + s * 16 + 4), s0 = *(const f32x4*)(rope + s * 16 + 8), s1 = *(const f32x4*)(rope + s * 16 + 12);
;     const float cs[8] = {c0[0], c0[1], c0[2], c0[3], c1[0], c1[1], c1[2], c1[3]}, sn[8] = {s0[0], s0[1], s0[2], s0[3], s1[0], s1[1], s1[2], s1[3]};
; #pragma unroll
;     for (int e = 0; e < 8; ++e) {
;         const float other = __shfl_xor(v[e], 16);
;         const float a = v[e] * cs[e], bq = other * sn[e];
;         v[e] = (fq == 0) ? (a - bq) : ((fq == 1) ? (a + bq) : v[e]);
;     }
;     DI void operator()(const pg8::f32x4 (&acc)[2][2][4][2], const pg8::Unit& u, int wr, int wc, int fr, int fq) const {
;     ...
;                         if (region < 2 && (wc & 1) == 0) rope8(v, rope, s, fq);
.LBB0_201:
	s_andn2_b64 vcc, exec, s[6:7]
	s_cbranch_vccnz .LBB0_251
	v_and_b32_e32 v11, 64, v183
	v_xor_b32_e32 v10, 16, v183
	v_add_u32_e32 v11, 64, v11
	v_cmp_lt_i32_e32 vcc, v10, v11
	v_lshlrev_b32_e32 v138, 6, v154
	s_nop 0
	v_cndmask_b32_e32 v10, v183, v10, vcc
	v_lshlrev_b32_e32 v186, 2, v10
	global_load_dwordx4 v[142:145], v138, s[68:69]
	global_load_dwordx4 v[10:13], v138, s[68:69] offset:32
	global_load_dwordx4 v[14:17], v138, s[68:69] offset:48
	s_nop 0
	global_load_dwordx4 v[138:141], v138, s[68:69] offset:16
	v_mov_b32_e32 v224, v2
	v_mov_b32_e32 v225, v2
	v_cmp_eq_u32_e64 s[0:1], 1, v1
	s_nop 0
	v_permlane16_swap_b32_e32 v224, v225
	v_cndmask_b32_e64 v187, v225, v224, s[0:1]
	v_cmp_lt_i32_e32 vcc, 0, v1
	s_waitcnt vmcnt(3)
	v_mul_f32_e32 v142, v2, v142
	s_waitcnt vmcnt(2) lgkmcnt(0)
	v_mul_f32_e32 v187, v10, v187
	v_sub_f32_e32 v10, v142, v187
	v_add_f32_e32 v142, v142, v187
	v_cndmask_b32_e64 v142, v2, v142, s[0:1]
	v_cndmask_b32_e32 v10, v10, v142, vcc
	v_mov_b32_e32 v224, v3
	v_mov_b32_e32 v225, v3
	v_cmp_eq_u32_e64 s[0:1], 1, v1
	s_nop 0
	v_permlane16_swap_b32_e32 v224, v225
	v_cndmask_b32_e64 v187, v225, v224, s[0:1]
	v_mul_f32_e32 v142, v3, v143
	v_cmp_lt_i32_e32 vcc, 0, v1
	s_waitcnt lgkmcnt(0)
	v_mul_f32_e32 v143, v11, v187
	v_sub_f32_e32 v11, v142, v143
	v_add_f32_e32 v142, v142, v143
	v_cndmask_b32_e64 v142, v3, v142, s[0:1]
	v_cndmask_b32_e32 v11, v11, v142, vcc
	v_mov_b32_e32 v224, v4
	v_mov_b32_e32 v225, v4
	v_cmp_eq_u32_e64 s[0:1], 1, v1
	s_nop 0
	v_permlane16_swap_b32_e32 v224, v225
	v_cndmask_b32_e64 v143, v225, v224, s[0:1]
	v_mul_f32_e32 v142, v4, v144
	v_cmp_lt_i32_e32 vcc, 0, v1
	s_waitcnt lgkmcnt(0)
	v_mul_f32_e32 v143, v12, v143
	v_sub_f32_e32 v12, v142, v143
	v_add_f32_e32 v142, v142, v143
	v_cndmask_b32_e64 v142, v4, v142, s[0:1]
	v_cndmask_b32_e32 v12, v12, v142, vcc
	v_mov_b32_e32 v224, v5
	v_mov_b32_e32 v225, v5
	v_cmp_eq_u32_e64 s[0:1], 1, v1
	s_nop 0
	v_permlane16_swap_b32_e32 v224, v225
	v_cndmask_b32_e64 v143, v225, v224, s[0:1]
	v_mul_f32_e32 v142, v5, v145
	v_cmp_lt_i32_e32 vcc, 0, v1
	s_waitcnt lgkmcnt(0)
	v_mul_f32_e32 v143, v13, v143
	v_sub_f32_e32 v13, v142, v143
	v_add_f32_e32 v142, v142, v143
	v_cndmask_b32_e64 v142, v5, v142, s[0:1]
	v_cndmask_b32_e32 v13, v13, v142, vcc
	v_mov_b32_e32 v224, v6
	v_mov_b32_e32 v225, v6
	v_cmp_eq_u32_e64 s[0:1], 1, v1
	s_nop 0
	v_permlane16_swap_b32_e32 v224, v225
	v_cndmask_b32_e64 v142, v225, v224, s[0:1]
	s_waitcnt vmcnt(0)
	v_mul_f32_e32 v138, v6, v138
	v_cmp_lt_i32_e32 vcc, 0, v1
	s_waitcnt lgkmcnt(0)
	v_mul_f32_e32 v142, v14, v142
	v_sub_f32_e32 v14, v138, v142
	v_add_f32_e32 v138, v138, v142
	v_cndmask_b32_e64 v138, v6, v138, s[0:1]
	v_cndmask_b32_e32 v14, v14, v138, vcc
	v_mov_b32_e32 v224, v7
	v_mov_b32_e32 v225, v7
	v_cmp_eq_u32_e64 s[0:1], 1, v1
	s_nop 0
	v_permlane16_swap_b32_e32 v224, v225
	v_cndmask_b32_e64 v142, v225, v224, s[0:1]
	v_mul_f32_e32 v138, v7, v139
	v_cmp_lt_i32_e32 vcc, 0, v1
	s_waitcnt lgkmcnt(0)
	v_mul_f32_e32 v139, v15, v142
	v_sub_f32_e32 v15, v138, v139
	v_add_f32_e32 v138, v138, v139
	v_cndmask_b32_e64 v138, v7, v138, s[0:1]
	v_cndmask_b32_e32 v15, v15, v138, vcc
	v_mov_b32_e32 v224, v8
	v_mov_b32_e32 v225, v8
	v_cmp_eq_u32_e64 s[0:1], 1, v1
	s_nop 0
	v_permlane16_swap_b32_e32 v224, v225
	v_cndmask_b32_e64 v139, v225, v224, s[0:1]
	v_mul_f32_e32 v138, v8, v140
	v_cmp_lt_i32_e32 vcc, 0, v1
	s_waitcnt lgkmcnt(0)
	v_mul_f32_e32 v139, v16, v139
	v_sub_f32_e32 v16, v138, v139
	v_add_f32_e32 v138, v138, v139
	v_cndmask_b32_e64 v138, v8, v138, s[0:1]
	v_cndmask_b32_e32 v16, v16, v138, vcc
	v_mov_b32_e32 v224, v9
	v_mov_b32_e32 v225, v9
	v_cmp_eq_u32_e64 s[0:1], 1, v1
	s_nop 0
	v_permlane16_swap_b32_e32 v224, v225
	v_cndmask_b32_e64 v139, v225, v224, s[0:1]
	v_mul_f32_e32 v138, v9, v141
	v_cmp_lt_i32_e32 vcc, 0, v1
	s_waitcnt lgkmcnt(0)
	v_mul_f32_e32 v139, v17, v139
	v_sub_f32_e32 v17, v138, v139
	v_add_f32_e32 v138, v138, v139
	v_cndmask_b32_e64 v138, v9, v138, s[0:1]
	v_cndmask_b32_e32 v17, v17, v138, vcc

; DI void rope8(float (&v)[8], const float* __restrict__ rope, int s, int fq) {
;     const f32x4 c0 = *(const f32x4*)(rope + s * 16), c1 = *(const f32x4*)(rope + s * 16 + 4), s0 = *(const f32x4*)(rope + s * 16 + 8), s1 = *(const f32x4*)(rope + s * 16 + 12);
;     const float cs[8] = {c0[0], c0[1], c0[2], c0[3], c1[0], c1[1], c1[2], c1[3]}, sn[8] = {s0[0], s0[1], s0[2], s0[3], s1[0], s1[1], s1[2], s1[3]};
; #pragma unroll
;     for (int e = 0; e < 8; ++e) {
;         const float other = __shfl_xor(v[e], 16);
;         const float a = v[e] * cs[e], bq = other * sn[e];
;         v[e] = (fq == 0) ? (a - bq) : ((fq == 1) ? (a + bq) : v[e]);
;     }
;     DI void operator()(const pg8::f32x4 (&acc)[2][2][4][2], const pg8::Unit& u, int wr, int wc, int fr, int fq) const {
;     ...
;                         if (region < 2 && (wc & 1) == 0) rope8(v, rope, s, fq);
.LBB0_267:
	s_andn2_b64 vcc, exec, s[8:9]
	s_cbranch_vccnz .LBB0_317
	v_and_b32_e32 v11, 64, v183
	v_xor_b32_e32 v10, 16, v183
	v_add_u32_e32 v11, 64, v11
	v_cmp_lt_i32_e32 vcc, v10, v11
	v_lshlrev_b32_e32 v130, 6, v140
	s_nop 0
	v_cndmask_b32_e32 v10, v183, v10, vcc
	v_lshlrev_b32_e32 v141, 2, v10
	global_load_dwordx4 v[134:137], v130, s[68:69]
	global_load_dwordx4 v[10:13], v130, s[68:69] offset:32
	global_load_dwordx4 v[14:17], v130, s[68:69] offset:48
	s_nop 0
	global_load_dwordx4 v[130:133], v130, s[68:69] offset:16
	v_mov_b32_e32 v224, v2
	v_mov_b32_e32 v225, v2
	v_cmp_eq_u32_e64 s[0:1], 1, v1
	s_nop 0
	v_permlane16_swap_b32_e32 v224, v225
	v_cndmask_b32_e64 v142, v225, v224, s[0:1]
	v_cmp_lt_i32_e32 vcc, 0, v1
	s_waitcnt vmcnt(3)
	v_mul_f32_e32 v134, v2, v134
	s_waitcnt vmcnt(2) lgkmcnt(0)
	v_mul_f32_e32 v142, v10, v142
	v_sub_f32_e32 v10, v134, v142
	v_add_f32_e32 v134, v134, v142
	v_cndmask_b32_e64 v134, v2, v134, s[0:1]
	v_cndmask_b32_e32 v10, v10, v134, vcc
	v_mov_b32_e32 v224, v3
	v_mov_b32_e32 v225, v3
	v_cmp_eq_u32_e64 s[0:1], 1, v1
	s_nop 0
	v_permlane16_swap_b32_e32 v224, v225
	v_cndmask_b32_e64 v142, v225, v224, s[0:1]
	v_mul_f32_e32 v134, v3, v135
	v_cmp_lt_i32_e32 vcc, 0, v1
	s_waitcnt lgkmcnt(0)
	v_mul_f32_e32 v135, v11, v142
	v_sub_f32_e32 v11, v134, v135
	v_add_f32_e32 v134, v134, v135
	v_cndmask_b32_e64 v134, v3, v134, s[0:1]
	v_cndmask_b32_e32 v11, v11, v134, vcc
	v_mov_b32_e32 v224, v4
	v_mov_b32_e32 v225, v4
	v_cmp_eq_u32_e64 s[0:1], 1, v1
	s_nop 0
	v_permlane16_swap_b32_e32 v224, v225
	v_cndmask_b32_e64 v135, v225, v224, s[0:1]
	v_mul_f32_e32 v134, v4, v136
	v_cmp_lt_i32_e32 vcc, 0, v1
	s_waitcnt lgkmcnt(0)
	v_mul_f32_e32 v135, v12, v135
	v_sub_f32_e32 v12, v134, v135
	v_add_f32_e32 v134, v134, v135
	v_cndmask_b32_e64 v134, v4, v134, s[0:1]
	v_cndmask_b32_e32 v12, v12, v134, vcc
	v_mov_b32_e32 v224, v5
	v_mov_b32_e32 v225, v5
	v_cmp_eq_u32_e64 s[0:1], 1, v1
	s_nop 0
	v_permlane16_swap_b32_e32 v224, v225
	v_cndmask_b32_e64 v135, v225, v224, s[0:1]
	v_mul_f32_e32 v134, v5, v137
	v_cmp_lt_i32_e32 vcc, 0, v1
	s_waitcnt lgkmcnt(0)
	v_mul_f32_e32 v135, v13, v135
	v_sub_f32_e32 v13, v134, v135
	v_add_f32_e32 v134, v134, v135
	v_cndmask_b32_e64 v134, v5, v134, s[0:1]
	v_cndmask_b32_e32 v13, v13, v134, vcc
	v_mov_b32_e32 v224, v6
	v_mov_b32_e32 v225, v6
	v_cmp_eq_u32_e64 s[0:1], 1, v1
	s_nop 0
	v_permlane16_swap_b32_e32 v224, v225
	v_cndmask_b32_e64 v134, v225, v224, s[0:1]
	s_waitcnt vmcnt(0)
	v_mul_f32_e32 v130, v6, v130
	v_cmp_lt_i32_e32 vcc, 0, v1
	s_waitcnt lgkmcnt(0)
	v_mul_f32_e32 v134, v14, v134
	v_sub_f32_e32 v14, v130, v134
	v_add_f32_e32 v130, v130, v134
	v_cndmask_b32_e64 v130, v6, v130, s[0:1]
	v_cndmask_b32_e32 v14, v14, v130, vcc
	v_mov_b32_e32 v224, v7
	v_mov_b32_e32 v225, v7
	v_cmp_eq_u32_e64 s[0:1], 1, v1
	s_nop 0
	v_permlane16_swap_b32_e32 v224, v225
	v_cndmask_b32_e64 v134, v225, v224, s[0:1]
	v_mul_f32_e32 v130, v7, v131
	v_cmp_lt_i32_e32 vcc, 0, v1
	s_waitcnt lgkmcnt(0)
	v_mul_f32_e32 v131, v15, v134
	v_sub_f32_e32 v15, v130, v131
	v_add_f32_e32 v130, v130, v131
	v_cndmask_b32_e64 v130, v7, v130, s[0:1]
	v_cndmask_b32_e32 v15, v15, v130, vcc
	v_mov_b32_e32 v224, v8
	v_mov_b32_e32 v225, v8
	v_cmp_eq_u32_e64 s[0:1], 1, v1
	s_nop 0
	v_permlane16_swap_b32_e32 v224, v225
	v_cndmask_b32_e64 v131, v225, v224, s[0:1]
	v_mul_f32_e32 v130, v8, v132
	v_cmp_lt_i32_e32 vcc, 0, v1
	s_waitcnt lgkmcnt(0)
	v_mul_f32_e32 v131, v16, v131
	v_sub_f32_e32 v16, v130, v131
	v_add_f32_e32 v130, v130, v131
	v_cndmask_b32_e64 v130, v8, v130, s[0:1]
	v_cndmask_b32_e32 v16, v16, v130, vcc
	v_mov_b32_e32 v224, v9
	v_mov_b32_e32 v225, v9
	v_cmp_eq_u32_e64 s[0:1], 1, v1
	s_nop 0
	v_permlane16_swap_b32_e32 v224, v225
	v_cndmask_b32_e64 v131, v225, v224, s[0:1]
	v_mul_f32_e32 v130, v9, v133
	v_cmp_lt_i32_e32 vcc, 0, v1
	s_waitcnt lgkmcnt(0)
	v_mul_f32_e32 v131, v17, v131
	v_sub_f32_e32 v17, v130, v131
	v_add_f32_e32 v130, v130, v131
	v_cndmask_b32_e64 v130, v9, v130, s[0:1]
	v_cndmask_b32_e32 v17, v17, v130, vcc

; DI void rope8(float (&v)[8], const float* __restrict__ rope, int s, int fq) {
;     const f32x4 c0 = *(const f32x4*)(rope + s * 16), c1 = *(const f32x4*)(rope + s * 16 + 4), s0 = *(const f32x4*)(rope + s * 16 + 8), s1 = *(const f32x4*)(rope + s * 16 + 12);
;     const float cs[8] = {c0[0], c0[1], c0[2], c0[3], c1[0], c1[1], c1[2], c1[3]}, sn[8] = {s0[0], s0[1], s0[2], s0[3], s1[0], s1[1], s1[2], s1[3]};
; #pragma unroll
;     for (int e = 0; e < 8; ++e) {
;         const float other = __shfl_xor(v[e], 16);
;         const float a = v[e] * cs[e], bq = other * sn[e];
;         v[e] = (fq == 0) ? (a - bq) : ((fq == 1) ? (a + bq) : v[e]);
;     }
;     DI void operator()(const pg8::f32x4 (&acc)[2][2][4][2], const pg8::Unit& u, int wr, int wc, int fr, int fq) const {
;     ...
;                         if (region < 2 && (wc & 1) == 0) rope8(v, rope, s, fq);
.LBB0_333:
	s_andn2_b64 vcc, exec, s[8:9]
	s_cbranch_vccnz .LBB0_383
	v_and_b32_e32 v11, 64, v183
	v_xor_b32_e32 v10, 16, v183
	v_add_u32_e32 v11, 64, v11
	v_cmp_lt_i32_e32 vcc, v10, v11
	v_lshlrev_b32_e32 v122, 6, v132
	s_nop 0
	v_cndmask_b32_e32 v10, v183, v10, vcc
	v_lshlrev_b32_e32 v133, 2, v10
	global_load_dwordx4 v[126:129], v122, s[68:69]
	global_load_dwordx4 v[10:13], v122, s[68:69] offset:32
	global_load_dwordx4 v[14:17], v122, s[68:69] offset:48
	s_nop 0
	global_load_dwordx4 v[122:125], v122, s[68:69] offset:16
	v_mov_b32_e32 v224, v2
	v_mov_b32_e32 v225, v2
	v_cmp_eq_u32_e64 s[0:1], 1, v1
	s_nop 0
	v_permlane16_swap_b32_e32 v224, v225
	v_cndmask_b32_e64 v134, v225, v224, s[0:1]
	v_cmp_lt_i32_e32 vcc, 0, v1
	s_waitcnt vmcnt(3)
	v_mul_f32_e32 v126, v2, v126
	s_waitcnt vmcnt(2) lgkmcnt(0)
	v_mul_f32_e32 v134, v10, v134
	v_sub_f32_e32 v10, v126, v134
	v_add_f32_e32 v126, v126, v134
	v_cndmask_b32_e64 v126, v2, v126, s[0:1]
	v_cndmask_b32_e32 v10, v10, v126, vcc
	v_mov_b32_e32 v224, v3
	v_mov_b32_e32 v225, v3
	v_cmp_eq_u32_e64 s[0:1], 1, v1
	s_nop 0
	v_permlane16_swap_b32_e32 v224, v225
	v_cndmask_b32_e64 v134, v225, v224, s[0:1]
	v_mul_f32_e32 v126, v3, v127
	v_cmp_lt_i32_e32 vcc, 0, v1
	s_waitcnt lgkmcnt(0)
	v_mul_f32_e32 v127, v11, v134
	v_sub_f32_e32 v11, v126, v127
	v_add_f32_e32 v126, v126, v127
	v_cndmask_b32_e64 v126, v3, v126, s[0:1]
	v_cndmask_b32_e32 v11, v11, v126, vcc
	v_mov_b32_e32 v224, v4
	v_mov_b32_e32 v225, v4
	v_cmp_eq_u32_e64 s[0:1], 1, v1
	s_nop 0
	v_permlane16_swap_b32_e32 v224, v225
	v_cndmask_b32_e64 v127, v225, v224, s[0:1]
	v_mul_f32_e32 v126, v4, v128
	v_cmp_lt_i32_e32 vcc, 0, v1
	s_waitcnt lgkmcnt(0)
	v_mul_f32_e32 v127, v12, v127
	v_sub_f32_e32 v12, v126, v127
	v_add_f32_e32 v126, v126, v127
	v_cndmask_b32_e64 v126, v4, v126, s[0:1]
	v_cndmask_b32_e32 v12, v12, v126, vcc
	v_mov_b32_e32 v224, v5
	v_mov_b32_e32 v225, v5
	v_cmp_eq_u32_e64 s[0:1], 1, v1
	s_nop 0
	v_permlane16_swap_b32_e32 v224, v225
	v_cndmask_b32_e64 v127, v225, v224, s[0:1]
	v_mul_f32_e32 v126, v5, v129
	v_cmp_lt_i32_e32 vcc, 0, v1
	s_waitcnt lgkmcnt(0)
	v_mul_f32_e32 v127, v13, v127
	v_sub_f32_e32 v13, v126, v127
	v_add_f32_e32 v126, v126, v127
	v_cndmask_b32_e64 v126, v5, v126, s[0:1]
	v_cndmask_b32_e32 v13, v13, v126, vcc
	v_mov_b32_e32 v224, v6
	v_mov_b32_e32 v225, v6
	v_cmp_eq_u32_e64 s[0:1], 1, v1
	s_nop 0
	v_permlane16_swap_b32_e32 v224, v225
	v_cndmask_b32_e64 v126, v225, v224, s[0:1]
	s_waitcnt vmcnt(0)
	v_mul_f32_e32 v122, v6, v122
	v_cmp_lt_i32_e32 vcc, 0, v1
	s_waitcnt lgkmcnt(0)
	v_mul_f32_e32 v126, v14, v126
	v_sub_f32_e32 v14, v122, v126
	v_add_f32_e32 v122, v122, v126
	v_cndmask_b32_e64 v122, v6, v122, s[0:1]
	v_cndmask_b32_e32 v14, v14, v122, vcc
	v_mov_b32_e32 v224, v7
	v_mov_b32_e32 v225, v7
	v_cmp_eq_u32_e64 s[0:1], 1, v1
	s_nop 0
	v_permlane16_swap_b32_e32 v224, v225
	v_cndmask_b32_e64 v126, v225, v224, s[0:1]
	v_mul_f32_e32 v122, v7, v123
	v_cmp_lt_i32_e32 vcc, 0, v1
	s_waitcnt lgkmcnt(0)
	v_mul_f32_e32 v123, v15, v126
	v_sub_f32_e32 v15, v122, v123
	v_add_f32_e32 v122, v122, v123
	v_cndmask_b32_e64 v122, v7, v122, s[0:1]
	v_cndmask_b32_e32 v15, v15, v122, vcc
	v_mov_b32_e32 v224, v8
	v_mov_b32_e32 v225, v8
	v_cmp_eq_u32_e64 s[0:1], 1, v1
	s_nop 0
	v_permlane16_swap_b32_e32 v224, v225
	v_cndmask_b32_e64 v123, v225, v224, s[0:1]
	v_mul_f32_e32 v122, v8, v124
	v_cmp_lt_i32_e32 vcc, 0, v1
	s_waitcnt lgkmcnt(0)
	v_mul_f32_e32 v123, v16, v123
	v_sub_f32_e32 v16, v122, v123
	v_add_f32_e32 v122, v122, v123
	v_cndmask_b32_e64 v122, v8, v122, s[0:1]
	v_cndmask_b32_e32 v16, v16, v122, vcc
	v_mov_b32_e32 v224, v9
	v_mov_b32_e32 v225, v9
	v_cmp_eq_u32_e64 s[0:1], 1, v1
	s_nop 0
	v_permlane16_swap_b32_e32 v224, v225
	v_cndmask_b32_e64 v123, v225, v224, s[0:1]
	v_mul_f32_e32 v122, v9, v125
	v_cmp_lt_i32_e32 vcc, 0, v1
	s_waitcnt lgkmcnt(0)
	v_mul_f32_e32 v123, v17, v123
	v_sub_f32_e32 v17, v122, v123
	v_add_f32_e32 v122, v122, v123
	v_cndmask_b32_e64 v122, v9, v122, s[0:1]
	v_cndmask_b32_e32 v17, v17, v122, vcc

; DI void rope8(float (&v)[8], const float* __restrict__ rope, int s, int fq) {
;     const f32x4 c0 = *(const f32x4*)(rope + s * 16), c1 = *(const f32x4*)(rope + s * 16 + 4), s0 = *(const f32x4*)(rope + s * 16 + 8), s1 = *(const f32x4*)(rope + s * 16 + 12);
;     const float cs[8] = {c0[0], c0[1], c0[2], c0[3], c1[0], c1[1], c1[2], c1[3]}, sn[8] = {s0[0], s0[1], s0[2], s0[3], s1[0], s1[1], s1[2], s1[3]};
; #pragma unroll
;     for (int e = 0; e < 8; ++e) {
;         const float other = __shfl_xor(v[e], 16);
;         const float a = v[e] * cs[e], bq = other * sn[e];
;         v[e] = (fq == 0) ? (a - bq) : ((fq == 1) ? (a + bq) : v[e]);
;     }
;     DI void operator()(const pg8::f32x4 (&acc)[2][2][4][2], const pg8::Unit& u, int wr, int wc, int fr, int fq) const {
;     ...
;                         if (region < 2 && (wc & 1) == 0) rope8(v, rope, s, fq);
.LBB0_399:
	s_andn2_b64 vcc, exec, s[8:9]
	s_cbranch_vccnz .LBB0_449
	v_and_b32_e32 v11, 64, v183
	v_xor_b32_e32 v10, 16, v183
	v_add_u32_e32 v11, 64, v11
	v_cmp_lt_i32_e32 vcc, v10, v11
	v_lshlrev_b32_e32 v114, 6, v124
	s_nop 0
	v_cndmask_b32_e32 v10, v183, v10, vcc
	v_lshlrev_b32_e32 v125, 2, v10
	global_load_dwordx4 v[118:121], v114, s[68:69]
	global_load_dwordx4 v[10:13], v114, s[68:69] offset:32
	global_load_dwordx4 v[14:17], v114, s[68:69] offset:48
	s_nop 0
	global_load_dwordx4 v[114:117], v114, s[68:69] offset:16
	v_mov_b32_e32 v224, v2
	v_mov_b32_e32 v225, v2
	v_cmp_eq_u32_e64 s[0:1], 1, v1
	s_nop 0
	v_permlane16_swap_b32_e32 v224, v225
	v_cndmask_b32_e64 v126, v225, v224, s[0:1]
	v_cmp_lt_i32_e32 vcc, 0, v1
	s_waitcnt vmcnt(3)
	v_mul_f32_e32 v118, v2, v118
	s_waitcnt vmcnt(2) lgkmcnt(0)
	v_mul_f32_e32 v126, v10, v126
	v_sub_f32_e32 v10, v118, v126
	v_add_f32_e32 v118, v118, v126
	v_cndmask_b32_e64 v118, v2, v118, s[0:1]
	v_cndmask_b32_e32 v10, v10, v118, vcc
	v_mov_b32_e32 v224, v3
	v_mov_b32_e32 v225, v3
	v_cmp_eq_u32_e64 s[0:1], 1, v1
	s_nop 0
	v_permlane16_swap_b32_e32 v224, v225
	v_cndmask_b32_e64 v126, v225, v224, s[0:1]
	v_mul_f32_e32 v118, v3, v119
	v_cmp_lt_i32_e32 vcc, 0, v1
	s_waitcnt lgkmcnt(0)
	v_mul_f32_e32 v119, v11, v126
	v_sub_f32_e32 v11, v118, v119
	v_add_f32_e32 v118, v118, v119
	v_cndmask_b32_e64 v118, v3, v118, s[0:1]
	v_cndmask_b32_e32 v11, v11, v118, vcc
	v_mov_b32_e32 v224, v4
	v_mov_b32_e32 v225, v4
	v_cmp_eq_u32_e64 s[0:1], 1, v1
	s_nop 0
	v_permlane16_swap_b32_e32 v224, v225
	v_cndmask_b32_e64 v119, v225, v224, s[0:1]
	v_mul_f32_e32 v118, v4, v120
	v_cmp_lt_i32_e32 vcc, 0, v1
	s_waitcnt lgkmcnt(0)
	v_mul_f32_e32 v119, v12, v119
	v_sub_f32_e32 v12, v118, v119
	v_add_f32_e32 v118, v118, v119
	v_cndmask_b32_e64 v118, v4, v118, s[0:1]
	v_cndmask_b32_e32 v12, v12, v118, vcc
	v_mov_b32_e32 v224, v5
	v_mov_b32_e32 v225, v5
	v_cmp_eq_u32_e64 s[0:1], 1, v1
	s_nop 0
	v_permlane16_swap_b32_e32 v224, v225
	v_cndmask_b32_e64 v119, v225, v224, s[0:1]
	v_mul_f32_e32 v118, v5, v121
	v_cmp_lt_i32_e32 vcc, 0, v1
	s_waitcnt lgkmcnt(0)
	v_mul_f32_e32 v119, v13, v119
	v_sub_f32_e32 v13, v118, v119
	v_add_f32_e32 v118, v118, v119
	v_cndmask_b32_e64 v118, v5, v118, s[0:1]
	v_cndmask_b32_e32 v13, v13, v118, vcc
	v_mov_b32_e32 v224, v6
	v_mov_b32_e32 v225, v6
	v_cmp_eq_u32_e64 s[0:1], 1, v1
	s_nop 0
	v_permlane16_swap_b32_e32 v224, v225
	v_cndmask_b32_e64 v118, v225, v224, s[0:1]
	s_waitcnt vmcnt(0)
	v_mul_f32_e32 v114, v6, v114
	v_cmp_lt_i32_e32 vcc, 0, v1
	s_waitcnt lgkmcnt(0)
	v_mul_f32_e32 v118, v14, v118
	v_sub_f32_e32 v14, v114, v118
	v_add_f32_e32 v114, v114, v118
	v_cndmask_b32_e64 v114, v6, v114, s[0:1]
	v_cndmask_b32_e32 v14, v14, v114, vcc
	v_mov_b32_e32 v224, v7
	v_mov_b32_e32 v225, v7
	v_cmp_eq_u32_e64 s[0:1], 1, v1
	s_nop 0
	v_permlane16_swap_b32_e32 v224, v225
	v_cndmask_b32_e64 v118, v225, v224, s[0:1]
	v_mul_f32_e32 v114, v7, v115
	v_cmp_lt_i32_e32 vcc, 0, v1
	s_waitcnt lgkmcnt(0)
	v_mul_f32_e32 v115, v15, v118
	v_sub_f32_e32 v15, v114, v115
	v_add_f32_e32 v114, v114, v115
	v_cndmask_b32_e64 v114, v7, v114, s[0:1]
	v_cndmask_b32_e32 v15, v15, v114, vcc
	v_mov_b32_e32 v224, v8
	v_mov_b32_e32 v225, v8
	v_cmp_eq_u32_e64 s[0:1], 1, v1
	s_nop 0
	v_permlane16_swap_b32_e32 v224, v225
	v_cndmask_b32_e64 v115, v225, v224, s[0:1]
	v_mul_f32_e32 v114, v8, v116
	v_cmp_lt_i32_e32 vcc, 0, v1
	s_waitcnt lgkmcnt(0)
	v_mul_f32_e32 v115, v16, v115
	v_sub_f32_e32 v16, v114, v115
	v_add_f32_e32 v114, v114, v115
	v_cndmask_b32_e64 v114, v8, v114, s[0:1]
	v_cndmask_b32_e32 v16, v16, v114, vcc
	v_mov_b32_e32 v224, v9
	v_mov_b32_e32 v225, v9
	v_cmp_eq_u32_e64 s[0:1], 1, v1
	s_nop 0
	v_permlane16_swap_b32_e32 v224, v225
	v_cndmask_b32_e64 v115, v225, v224, s[0:1]
	v_mul_f32_e32 v114, v9, v117
	v_cmp_lt_i32_e32 vcc, 0, v1
	s_waitcnt lgkmcnt(0)
	v_mul_f32_e32 v115, v17, v115
	v_sub_f32_e32 v17, v114, v115
	v_add_f32_e32 v114, v114, v115
	v_cndmask_b32_e64 v114, v9, v114, s[0:1]
	v_cndmask_b32_e32 v17, v17, v114, vcc

; DI void rope8(float (&v)[8], const float* __restrict__ rope, int s, int fq) {
;     const f32x4 c0 = *(const f32x4*)(rope + s * 16), c1 = *(const f32x4*)(rope + s * 16 + 4), s0 = *(const f32x4*)(rope + s * 16 + 8), s1 = *(const f32x4*)(rope + s * 16 + 12);
;     const float cs[8] = {c0[0], c0[1], c0[2], c0[3], c1[0], c1[1], c1[2], c1[3]}, sn[8] = {s0[0], s0[1], s0[2], s0[3], s1[0], s1[1], s1[2], s1[3]};
; #pragma unroll
;     for (int e = 0; e < 8; ++e) {
;         const float other = __shfl_xor(v[e], 16);
;         const float a = v[e] * cs[e], bq = other * sn[e];
;         v[e] = (fq == 0) ? (a - bq) : ((fq == 1) ? (a + bq) : v[e]);
;     }
;     DI void operator()(const pg8::f32x4 (&acc)[2][2][4][2], const pg8::Unit& u, int wr, int wc, int fr, int fq) const {
;     ...
;                         if (region < 2 && (wc & 1) == 0) rope8(v, rope, s, fq);
.LBB0_465:
	s_andn2_b64 vcc, exec, s[8:9]
	s_cbranch_vccnz .LBB0_515
	v_and_b32_e32 v11, 64, v183
	v_xor_b32_e32 v10, 16, v183
	v_add_u32_e32 v11, 64, v11
	v_cmp_lt_i32_e32 vcc, v10, v11
	v_lshlrev_b32_e32 v106, 6, v118
	s_nop 0
	v_cndmask_b32_e32 v10, v183, v10, vcc
	v_lshlrev_b32_e32 v119, 2, v10
	global_load_dwordx4 v[110:113], v106, s[68:69]
	global_load_dwordx4 v[10:13], v106, s[68:69] offset:32
	global_load_dwordx4 v[14:17], v106, s[68:69] offset:48
	s_nop 0
	global_load_dwordx4 v[106:109], v106, s[68:69] offset:16
	v_mov_b32_e32 v224, v2
	v_mov_b32_e32 v225, v2
	v_cmp_eq_u32_e64 s[0:1], 1, v1
	s_nop 0
	v_permlane16_swap_b32_e32 v224, v225
	v_cndmask_b32_e64 v120, v225, v224, s[0:1]
	v_cmp_lt_i32_e32 vcc, 0, v1
	s_waitcnt vmcnt(3)
	v_mul_f32_e32 v110, v2, v110
	s_waitcnt vmcnt(2) lgkmcnt(0)
	v_mul_f32_e32 v120, v10, v120
	v_sub_f32_e32 v10, v110, v120
	v_add_f32_e32 v110, v110, v120
	v_cndmask_b32_e64 v110, v2, v110, s[0:1]
	v_cndmask_b32_e32 v10, v10, v110, vcc
	v_mov_b32_e32 v224, v3
	v_mov_b32_e32 v225, v3
	v_cmp_eq_u32_e64 s[0:1], 1, v1
	s_nop 0
	v_permlane16_swap_b32_e32 v224, v225
	v_cndmask_b32_e64 v120, v225, v224, s[0:1]
	v_mul_f32_e32 v110, v3, v111
	v_cmp_lt_i32_e32 vcc, 0, v1
	s_waitcnt lgkmcnt(0)
	v_mul_f32_e32 v111, v11, v120
	v_sub_f32_e32 v11, v110, v111
	v_add_f32_e32 v110, v110, v111
	v_cndmask_b32_e64 v110, v3, v110, s[0:1]
	v_cndmask_b32_e32 v11, v11, v110, vcc
	v_mov_b32_e32 v224, v4
	v_mov_b32_e32 v225, v4
	v_cmp_eq_u32_e64 s[0:1], 1, v1
	s_nop 0
	v_permlane16_swap_b32_e32 v224, v225
	v_cndmask_b32_e64 v111, v225, v224, s[0:1]
	v_mul_f32_e32 v110, v4, v112
	v_cmp_lt_i32_e32 vcc, 0, v1
	s_waitcnt lgkmcnt(0)
	v_mul_f32_e32 v111, v12, v111
	v_sub_f32_e32 v12, v110, v111
	v_add_f32_e32 v110, v110, v111
	v_cndmask_b32_e64 v110, v4, v110, s[0:1]
	v_cndmask_b32_e32 v12, v12, v110, vcc
	v_mov_b32_e32 v224, v5
	v_mov_b32_e32 v225, v5
	v_cmp_eq_u32_e64 s[0:1], 1, v1
	s_nop 0
	v_permlane16_swap_b32_e32 v224, v225
	v_cndmask_b32_e64 v111, v225, v224, s[0:1]
	v_mul_f32_e32 v110, v5, v113
	v_cmp_lt_i32_e32 vcc, 0, v1
	s_waitcnt lgkmcnt(0)
	v_mul_f32_e32 v111, v13, v111
	v_sub_f32_e32 v13, v110, v111
	v_add_f32_e32 v110, v110, v111
	v_cndmask_b32_e64 v110, v5, v110, s[0:1]
	v_cndmask_b32_e32 v13, v13, v110, vcc
	v_mov_b32_e32 v224, v6
	v_mov_b32_e32 v225, v6
	v_cmp_eq_u32_e64 s[0:1], 1, v1
	s_nop 0
	v_permlane16_swap_b32_e32 v224, v225
	v_cndmask_b32_e64 v110, v225, v224, s[0:1]
	s_waitcnt vmcnt(0)
	v_mul_f32_e32 v106, v6, v106
	v_cmp_lt_i32_e32 vcc, 0, v1
	s_waitcnt lgkmcnt(0)
	v_mul_f32_e32 v110, v14, v110
	v_sub_f32_e32 v14, v106, v110
	v_add_f32_e32 v106, v106, v110
	v_cndmask_b32_e64 v106, v6, v106, s[0:1]
	v_cndmask_b32_e32 v14, v14, v106, vcc
	v_mov_b32_e32 v224, v7
	v_mov_b32_e32 v225, v7
	v_cmp_eq_u32_e64 s[0:1], 1, v1
	s_nop 0
	v_permlane16_swap_b32_e32 v224, v225
	v_cndmask_b32_e64 v110, v225, v224, s[0:1]
	v_mul_f32_e32 v106, v7, v107
	v_cmp_lt_i32_e32 vcc, 0, v1
	s_waitcnt lgkmcnt(0)
	v_mul_f32_e32 v107, v15, v110
	v_sub_f32_e32 v15, v106, v107
	v_add_f32_e32 v106, v106, v107
	v_cndmask_b32_e64 v106, v7, v106, s[0:1]
	v_cndmask_b32_e32 v15, v15, v106, vcc
	v_mov_b32_e32 v224, v8
	v_mov_b32_e32 v225, v8
	v_cmp_eq_u32_e64 s[0:1], 1, v1
	s_nop 0
	v_permlane16_swap_b32_e32 v224, v225
	v_cndmask_b32_e64 v107, v225, v224, s[0:1]
	v_mul_f32_e32 v106, v8, v108
	v_cmp_lt_i32_e32 vcc, 0, v1
	s_waitcnt lgkmcnt(0)
	v_mul_f32_e32 v107, v16, v107
	v_sub_f32_e32 v16, v106, v107
	v_add_f32_e32 v106, v106, v107
	v_cndmask_b32_e64 v106, v8, v106, s[0:1]
	v_cndmask_b32_e32 v16, v16, v106, vcc
	v_mov_b32_e32 v224, v9
	v_mov_b32_e32 v225, v9
	v_cmp_eq_u32_e64 s[0:1], 1, v1
	s_nop 0
	v_permlane16_swap_b32_e32 v224, v225
	v_cndmask_b32_e64 v107, v225, v224, s[0:1]
	v_mul_f32_e32 v106, v9, v109
	v_cmp_lt_i32_e32 vcc, 0, v1
	s_waitcnt lgkmcnt(0)
	v_mul_f32_e32 v107, v17, v107
	v_sub_f32_e32 v17, v106, v107
	v_add_f32_e32 v106, v106, v107
	v_cndmask_b32_e64 v106, v9, v106, s[0:1]
	v_cndmask_b32_e32 v17, v17, v106, vcc

; DI void rope8(float (&v)[8], const float* __restrict__ rope, int s, int fq) {
;     const f32x4 c0 = *(const f32x4*)(rope + s * 16), c1 = *(const f32x4*)(rope + s * 16 + 4), s0 = *(const f32x4*)(rope + s * 16 + 8), s1 = *(const f32x4*)(rope + s * 16 + 12);
;     const float cs[8] = {c0[0], c0[1], c0[2], c0[3], c1[0], c1[1], c1[2], c1[3]}, sn[8] = {s0[0], s0[1], s0[2], s0[3], s1[0], s1[1], s1[2], s1[3]};
; #pragma unroll
;     for (int e = 0; e < 8; ++e) {
;         const float other = __shfl_xor(v[e], 16);
;         const float a = v[e] * cs[e], bq = other * sn[e];
;         v[e] = (fq == 0) ? (a - bq) : ((fq == 1) ? (a + bq) : v[e]);
;     }
;     DI void operator()(const pg8::f32x4 (&acc)[2][2][4][2], const pg8::Unit& u, int wr, int wc, int fr, int fq) const {
;     ...
;                         if (region < 2 && (wc & 1) == 0) rope8(v, rope, s, fq);
.LBB0_531:
	s_andn2_b64 vcc, exec, s[8:9]
	s_cbranch_vccnz .LBB0_581
	v_and_b32_e32 v11, 64, v183
	v_xor_b32_e32 v10, 16, v183
	v_add_u32_e32 v11, 64, v11
	v_cmp_lt_i32_e32 vcc, v10, v11
	v_lshlrev_b32_e32 v98, 6, v108
	s_nop 0
	v_cndmask_b32_e32 v10, v183, v10, vcc
	v_lshlrev_b32_e32 v109, 2, v10
	global_load_dwordx4 v[102:105], v98, s[68:69]
	global_load_dwordx4 v[10:13], v98, s[68:69] offset:32
	global_load_dwordx4 v[14:17], v98, s[68:69] offset:48
	s_nop 0
	global_load_dwordx4 v[98:101], v98, s[68:69] offset:16
	v_mov_b32_e32 v224, v2
	v_mov_b32_e32 v225, v2
	v_cmp_eq_u32_e64 s[0:1], 1, v1
	s_nop 0
	v_permlane16_swap_b32_e32 v224, v225
	v_cndmask_b32_e64 v110, v225, v224, s[0:1]
	v_cmp_lt_i32_e32 vcc, 0, v1
	s_waitcnt vmcnt(3)
	v_mul_f32_e32 v102, v2, v102
	s_waitcnt vmcnt(2) lgkmcnt(0)
	v_mul_f32_e32 v110, v10, v110
	v_sub_f32_e32 v10, v102, v110
	v_add_f32_e32 v102, v102, v110
	v_cndmask_b32_e64 v102, v2, v102, s[0:1]
	v_cndmask_b32_e32 v10, v10, v102, vcc
	v_mov_b32_e32 v224, v3
	v_mov_b32_e32 v225, v3
	v_cmp_eq_u32_e64 s[0:1], 1, v1
	s_nop 0
	v_permlane16_swap_b32_e32 v224, v225
	v_cndmask_b32_e64 v110, v225, v224, s[0:1]
	v_mul_f32_e32 v102, v3, v103
	v_cmp_lt_i32_e32 vcc, 0, v1
	s_waitcnt lgkmcnt(0)
	v_mul_f32_e32 v103, v11, v110
	v_sub_f32_e32 v11, v102, v103
	v_add_f32_e32 v102, v102, v103
	v_cndmask_b32_e64 v102, v3, v102, s[0:1]
	v_cndmask_b32_e32 v11, v11, v102, vcc
	v_mov_b32_e32 v224, v4
	v_mov_b32_e32 v225, v4
	v_cmp_eq_u32_e64 s[0:1], 1, v1
	s_nop 0
	v_permlane16_swap_b32_e32 v224, v225
	v_cndmask_b32_e64 v103, v225, v224, s[0:1]
	v_mul_f32_e32 v102, v4, v104
	v_cmp_lt_i32_e32 vcc, 0, v1
	s_waitcnt lgkmcnt(0)
	v_mul_f32_e32 v103, v12, v103
	v_sub_f32_e32 v12, v102, v103
	v_add_f32_e32 v102, v102, v103
	v_cndmask_b32_e64 v102, v4, v102, s[0:1]
	v_cndmask_b32_e32 v12, v12, v102, vcc
	v_mov_b32_e32 v224, v5
	v_mov_b32_e32 v225, v5
	v_cmp_eq_u32_e64 s[0:1], 1, v1
	s_nop 0
	v_permlane16_swap_b32_e32 v224, v225
	v_cndmask_b32_e64 v103, v225, v224, s[0:1]
	v_mul_f32_e32 v102, v5, v105
	v_cmp_lt_i32_e32 vcc, 0, v1
	s_waitcnt lgkmcnt(0)
	v_mul_f32_e32 v103, v13, v103
	v_sub_f32_e32 v13, v102, v103
	v_add_f32_e32 v102, v102, v103
	v_cndmask_b32_e64 v102, v5, v102, s[0:1]
	v_cndmask_b32_e32 v13, v13, v102, vcc
	v_mov_b32_e32 v224, v6
	v_mov_b32_e32 v225, v6
	v_cmp_eq_u32_e64 s[0:1], 1, v1
	s_nop 0
	v_permlane16_swap_b32_e32 v224, v225
	v_cndmask_b32_e64 v102, v225, v224, s[0:1]
	s_waitcnt vmcnt(0)
	v_mul_f32_e32 v98, v6, v98
	v_cmp_lt_i32_e32 vcc, 0, v1
	s_waitcnt lgkmcnt(0)
	v_mul_f32_e32 v102, v14, v102
	v_sub_f32_e32 v14, v98, v102
	v_add_f32_e32 v98, v98, v102
	v_cndmask_b32_e64 v98, v6, v98, s[0:1]
	v_cndmask_b32_e32 v14, v14, v98, vcc
	v_mov_b32_e32 v224, v7
	v_mov_b32_e32 v225, v7
	v_cmp_eq_u32_e64 s[0:1], 1, v1
	s_nop 0
	v_permlane16_swap_b32_e32 v224, v225
	v_cndmask_b32_e64 v102, v225, v224, s[0:1]
	v_mul_f32_e32 v98, v7, v99
	v_cmp_lt_i32_e32 vcc, 0, v1
	s_waitcnt lgkmcnt(0)
	v_mul_f32_e32 v99, v15, v102
	v_sub_f32_e32 v15, v98, v99
	v_add_f32_e32 v98, v98, v99
	v_cndmask_b32_e64 v98, v7, v98, s[0:1]
	v_cndmask_b32_e32 v15, v15, v98, vcc
	v_mov_b32_e32 v224, v8
	v_mov_b32_e32 v225, v8
	v_cmp_eq_u32_e64 s[0:1], 1, v1
	s_nop 0
	v_permlane16_swap_b32_e32 v224, v225
	v_cndmask_b32_e64 v99, v225, v224, s[0:1]
	v_mul_f32_e32 v98, v8, v100
	v_cmp_lt_i32_e32 vcc, 0, v1
	s_waitcnt lgkmcnt(0)
	v_mul_f32_e32 v99, v16, v99
	v_sub_f32_e32 v16, v98, v99
	v_add_f32_e32 v98, v98, v99
	v_cndmask_b32_e64 v98, v8, v98, s[0:1]
	v_cndmask_b32_e32 v16, v16, v98, vcc
	v_mov_b32_e32 v224, v9
	v_mov_b32_e32 v225, v9
	v_cmp_eq_u32_e64 s[0:1], 1, v1
	s_nop 0
	v_permlane16_swap_b32_e32 v224, v225
	v_cndmask_b32_e64 v99, v225, v224, s[0:1]
	v_mul_f32_e32 v98, v9, v101
	v_cmp_lt_i32_e32 vcc, 0, v1
	s_waitcnt lgkmcnt(0)
	v_mul_f32_e32 v99, v17, v99
	v_sub_f32_e32 v17, v98, v99
	v_add_f32_e32 v98, v98, v99
	v_cndmask_b32_e64 v98, v9, v98, s[0:1]
	v_cndmask_b32_e32 v17, v17, v98, vcc

; DI void rope8(float (&v)[8], const float* __restrict__ rope, int s, int fq) {
;     const f32x4 c0 = *(const f32x4*)(rope + s * 16), c1 = *(const f32x4*)(rope + s * 16 + 4), s0 = *(const f32x4*)(rope + s * 16 + 8), s1 = *(const f32x4*)(rope + s * 16 + 12);
;     const float cs[8] = {c0[0], c0[1], c0[2], c0[3], c1[0], c1[1], c1[2], c1[3]}, sn[8] = {s0[0], s0[1], s0[2], s0[3], s1[0], s1[1], s1[2], s1[3]};
; #pragma unroll
;     for (int e = 0; e < 8; ++e) {
;         const float other = __shfl_xor(v[e], 16);
;         const float a = v[e] * cs[e], bq = other * sn[e];
;         v[e] = (fq == 0) ? (a - bq) : ((fq == 1) ? (a + bq) : v[e]);
;     }
;     DI void operator()(const pg8::f32x4 (&acc)[2][2][4][2], const pg8::Unit& u, int wr, int wc, int fr, int fq) const {
;     ...
;                         if (region < 2 && (wc & 1) == 0) rope8(v, rope, s, fq);
.LBB0_597:
	s_andn2_b64 vcc, exec, s[8:9]
	s_cbranch_vccnz .LBB0_647
	v_and_b32_e32 v11, 64, v183
	v_xor_b32_e32 v10, 16, v183
	v_add_u32_e32 v11, 64, v11
	v_cmp_lt_i32_e32 vcc, v10, v11
	v_lshlrev_b32_e32 v90, 6, v100
	s_nop 0
	v_cndmask_b32_e32 v10, v183, v10, vcc
	v_lshlrev_b32_e32 v101, 2, v10
	global_load_dwordx4 v[94:97], v90, s[68:69]
	global_load_dwordx4 v[10:13], v90, s[68:69] offset:32
	global_load_dwordx4 v[14:17], v90, s[68:69] offset:48
	s_nop 0
	global_load_dwordx4 v[90:93], v90, s[68:69] offset:16
	v_mov_b32_e32 v224, v2
	v_mov_b32_e32 v225, v2
	v_cmp_eq_u32_e64 s[0:1], 1, v1
	s_nop 0
	v_permlane16_swap_b32_e32 v224, v225
	v_cndmask_b32_e64 v102, v225, v224, s[0:1]
	v_cmp_lt_i32_e32 vcc, 0, v1
	s_waitcnt vmcnt(3)
	v_mul_f32_e32 v94, v2, v94
	s_waitcnt vmcnt(2) lgkmcnt(0)
	v_mul_f32_e32 v102, v10, v102
	v_sub_f32_e32 v10, v94, v102
	v_add_f32_e32 v94, v94, v102
	v_cndmask_b32_e64 v94, v2, v94, s[0:1]
	v_cndmask_b32_e32 v10, v10, v94, vcc
	v_mov_b32_e32 v224, v3
	v_mov_b32_e32 v225, v3
	v_cmp_eq_u32_e64 s[0:1], 1, v1
	s_nop 0
	v_permlane16_swap_b32_e32 v224, v225
	v_cndmask_b32_e64 v102, v225, v224, s[0:1]
	v_mul_f32_e32 v94, v3, v95
	v_cmp_lt_i32_e32 vcc, 0, v1
	s_waitcnt lgkmcnt(0)
	v_mul_f32_e32 v95, v11, v102
	v_sub_f32_e32 v11, v94, v95
	v_add_f32_e32 v94, v94, v95
	v_cndmask_b32_e64 v94, v3, v94, s[0:1]
	v_cndmask_b32_e32 v11, v11, v94, vcc
	v_mov_b32_e32 v224, v4
	v_mov_b32_e32 v225, v4
	v_cmp_eq_u32_e64 s[0:1], 1, v1
	s_nop 0
	v_permlane16_swap_b32_e32 v224, v225
	v_cndmask_b32_e64 v95, v225, v224, s[0:1]
	v_mul_f32_e32 v94, v4, v96
	v_cmp_lt_i32_e32 vcc, 0, v1
	s_waitcnt lgkmcnt(0)
	v_mul_f32_e32 v95, v12, v95
	v_sub_f32_e32 v12, v94, v95
	v_add_f32_e32 v94, v94, v95
	v_cndmask_b32_e64 v94, v4, v94, s[0:1]
	v_cndmask_b32_e32 v12, v12, v94, vcc
	v_mov_b32_e32 v224, v5
	v_mov_b32_e32 v225, v5
	v_cmp_eq_u32_e64 s[0:1], 1, v1
	s_nop 0
	v_permlane16_swap_b32_e32 v224, v225
	v_cndmask_b32_e64 v95, v225, v224, s[0:1]
	v_mul_f32_e32 v94, v5, v97
	v_cmp_lt_i32_e32 vcc, 0, v1
	s_waitcnt lgkmcnt(0)
	v_mul_f32_e32 v95, v13, v95
	v_sub_f32_e32 v13, v94, v95
	v_add_f32_e32 v94, v94, v95
	v_cndmask_b32_e64 v94, v5, v94, s[0:1]
	v_cndmask_b32_e32 v13, v13, v94, vcc
	v_mov_b32_e32 v224, v6
	v_mov_b32_e32 v225, v6
	v_cmp_eq_u32_e64 s[0:1], 1, v1
	s_nop 0
	v_permlane16_swap_b32_e32 v224, v225
	v_cndmask_b32_e64 v94, v225, v224, s[0:1]
	s_waitcnt vmcnt(0)
	v_mul_f32_e32 v90, v6, v90
	v_cmp_lt_i32_e32 vcc, 0, v1
	s_waitcnt lgkmcnt(0)
	v_mul_f32_e32 v94, v14, v94
	v_sub_f32_e32 v14, v90, v94
	v_add_f32_e32 v90, v90, v94
	v_cndmask_b32_e64 v90, v6, v90, s[0:1]
	v_cndmask_b32_e32 v14, v14, v90, vcc
	v_mov_b32_e32 v224, v7
	v_mov_b32_e32 v225, v7
	v_cmp_eq_u32_e64 s[0:1], 1, v1
	s_nop 0
	v_permlane16_swap_b32_e32 v224, v225
	v_cndmask_b32_e64 v94, v225, v224, s[0:1]
	v_mul_f32_e32 v90, v7, v91
	v_cmp_lt_i32_e32 vcc, 0, v1
	s_waitcnt lgkmcnt(0)
	v_mul_f32_e32 v91, v15, v94
	v_sub_f32_e32 v15, v90, v91
	v_add_f32_e32 v90, v90, v91
	v_cndmask_b32_e64 v90, v7, v90, s[0:1]
	v_cndmask_b32_e32 v15, v15, v90, vcc
	v_mov_b32_e32 v224, v8
	v_mov_b32_e32 v225, v8
	v_cmp_eq_u32_e64 s[0:1], 1, v1
	s_nop 0
	v_permlane16_swap_b32_e32 v224, v225
	v_cndmask_b32_e64 v91, v225, v224, s[0:1]
	v_mul_f32_e32 v90, v8, v92
	v_cmp_lt_i32_e32 vcc, 0, v1
	s_waitcnt lgkmcnt(0)
	v_mul_f32_e32 v91, v16, v91
	v_sub_f32_e32 v16, v90, v91
	v_add_f32_e32 v90, v90, v91
	v_cndmask_b32_e64 v90, v8, v90, s[0:1]
	v_cndmask_b32_e32 v16, v16, v90, vcc
	v_mov_b32_e32 v224, v9
	v_mov_b32_e32 v225, v9
	v_cmp_eq_u32_e64 s[0:1], 1, v1
	s_nop 0
	v_permlane16_swap_b32_e32 v224, v225
	v_cndmask_b32_e64 v91, v225, v224, s[0:1]
	v_mul_f32_e32 v90, v9, v93
	v_cmp_lt_i32_e32 vcc, 0, v1
	s_waitcnt lgkmcnt(0)
	v_mul_f32_e32 v91, v17, v91
	v_sub_f32_e32 v17, v90, v91
	v_add_f32_e32 v90, v90, v91
	v_cndmask_b32_e64 v90, v9, v90, s[0:1]
	v_cndmask_b32_e32 v17, v17, v90, vcc

; DI void rope8(float (&v)[8], const float* __restrict__ rope, int s, int fq) {
;     const f32x4 c0 = *(const f32x4*)(rope + s * 16), c1 = *(const f32x4*)(rope + s * 16 + 4), s0 = *(const f32x4*)(rope + s * 16 + 8), s1 = *(const f32x4*)(rope + s * 16 + 12);
;     const float cs[8] = {c0[0], c0[1], c0[2], c0[3], c1[0], c1[1], c1[2], c1[3]}, sn[8] = {s0[0], s0[1], s0[2], s0[3], s1[0], s1[1], s1[2], s1[3]};
; #pragma unroll
;     for (int e = 0; e < 8; ++e) {
;         const float other = __shfl_xor(v[e], 16);
;         const float a = v[e] * cs[e], bq = other * sn[e];
;         v[e] = (fq == 0) ? (a - bq) : ((fq == 1) ? (a + bq) : v[e]);
;     }
;     DI void operator()(const pg8::f32x4 (&acc)[2][2][4][2], const pg8::Unit& u, int wr, int wc, int fr, int fq) const {
;     ...
;                         if (region < 2 && (wc & 1) == 0) rope8(v, rope, s, fq);
.LBB0_667:
	s_andn2_b64 vcc, exec, s[8:9]
	s_cbranch_vccnz .LBB0_717
	v_and_b32_e32 v11, 64, v183
	v_xor_b32_e32 v10, 16, v183
	v_add_u32_e32 v11, 64, v11
	v_cmp_lt_i32_e32 vcc, v10, v11
	v_lshlrev_b32_e32 v74, 6, v83
	s_nop 0
	v_cndmask_b32_e32 v10, v183, v10, vcc
	v_lshlrev_b32_e32 v86, 2, v10
	global_load_dwordx4 v[78:81], v74, s[68:69]
	global_load_dwordx4 v[10:13], v74, s[68:69] offset:32
	global_load_dwordx4 v[14:17], v74, s[68:69] offset:48
	s_nop 0
	global_load_dwordx4 v[74:77], v74, s[68:69] offset:16
	v_mov_b32_e32 v224, v2
	v_mov_b32_e32 v225, v2
	v_cmp_eq_u32_e64 s[0:1], 1, v1
	s_nop 0
	v_permlane16_swap_b32_e32 v224, v225
	v_cndmask_b32_e64 v87, v225, v224, s[0:1]
	v_cmp_lt_i32_e32 vcc, 0, v1
	s_waitcnt vmcnt(3)
	v_mul_f32_e32 v78, v2, v78
	s_waitcnt vmcnt(2) lgkmcnt(0)
	v_mul_f32_e32 v87, v10, v87
	v_sub_f32_e32 v10, v78, v87
	v_add_f32_e32 v78, v78, v87
	v_cndmask_b32_e64 v78, v2, v78, s[0:1]
	v_cndmask_b32_e32 v10, v10, v78, vcc
	v_mov_b32_e32 v224, v3
	v_mov_b32_e32 v225, v3
	v_cmp_eq_u32_e64 s[0:1], 1, v1
	s_nop 0
	v_permlane16_swap_b32_e32 v224, v225
	v_cndmask_b32_e64 v87, v225, v224, s[0:1]
	v_mul_f32_e32 v78, v3, v79
	v_cmp_lt_i32_e32 vcc, 0, v1
	s_waitcnt lgkmcnt(0)
	v_mul_f32_e32 v79, v11, v87
	v_sub_f32_e32 v11, v78, v79
	v_add_f32_e32 v78, v78, v79
	v_cndmask_b32_e64 v78, v3, v78, s[0:1]
	v_cndmask_b32_e32 v11, v11, v78, vcc
	v_mov_b32_e32 v224, v4
	v_mov_b32_e32 v225, v4
	v_cmp_eq_u32_e64 s[0:1], 1, v1
	s_nop 0
	v_permlane16_swap_b32_e32 v224, v225
	v_cndmask_b32_e64 v79, v225, v224, s[0:1]
	v_mul_f32_e32 v78, v4, v80
	v_cmp_lt_i32_e32 vcc, 0, v1
	s_waitcnt lgkmcnt(0)
	v_mul_f32_e32 v79, v12, v79
	v_sub_f32_e32 v12, v78, v79
	v_add_f32_e32 v78, v78, v79
	v_cndmask_b32_e64 v78, v4, v78, s[0:1]
	v_cndmask_b32_e32 v12, v12, v78, vcc
	v_mov_b32_e32 v224, v5
	v_mov_b32_e32 v225, v5
	v_cmp_eq_u32_e64 s[0:1], 1, v1
	s_nop 0
	v_permlane16_swap_b32_e32 v224, v225
	v_cndmask_b32_e64 v79, v225, v224, s[0:1]
	v_mul_f32_e32 v78, v5, v81
	v_cmp_lt_i32_e32 vcc, 0, v1
	s_waitcnt lgkmcnt(0)
	v_mul_f32_e32 v79, v13, v79
	v_sub_f32_e32 v13, v78, v79
	v_add_f32_e32 v78, v78, v79
	v_cndmask_b32_e64 v78, v5, v78, s[0:1]
	v_cndmask_b32_e32 v13, v13, v78, vcc
	v_mov_b32_e32 v224, v6
	v_mov_b32_e32 v225, v6
	v_cmp_eq_u32_e64 s[0:1], 1, v1
	s_nop 0
	v_permlane16_swap_b32_e32 v224, v225
	v_cndmask_b32_e64 v78, v225, v224, s[0:1]
	s_waitcnt vmcnt(0)
	v_mul_f32_e32 v74, v6, v74
	v_cmp_lt_i32_e32 vcc, 0, v1
	s_waitcnt lgkmcnt(0)
	v_mul_f32_e32 v78, v14, v78
	v_sub_f32_e32 v14, v74, v78
	v_add_f32_e32 v74, v74, v78
	v_cndmask_b32_e64 v74, v6, v74, s[0:1]
	v_cndmask_b32_e32 v14, v14, v74, vcc
	v_mov_b32_e32 v224, v7
	v_mov_b32_e32 v225, v7
	v_cmp_eq_u32_e64 s[0:1], 1, v1
	s_nop 0
	v_permlane16_swap_b32_e32 v224, v225
	v_cndmask_b32_e64 v78, v225, v224, s[0:1]
	v_mul_f32_e32 v74, v7, v75
	v_cmp_lt_i32_e32 vcc, 0, v1
	s_waitcnt lgkmcnt(0)
	v_mul_f32_e32 v75, v15, v78
	v_sub_f32_e32 v15, v74, v75
	v_add_f32_e32 v74, v74, v75
	v_cndmask_b32_e64 v74, v7, v74, s[0:1]
	v_cndmask_b32_e32 v15, v15, v74, vcc
	v_mov_b32_e32 v224, v8
	v_mov_b32_e32 v225, v8
	v_cmp_eq_u32_e64 s[0:1], 1, v1
	s_nop 0
	v_permlane16_swap_b32_e32 v224, v225
	v_cndmask_b32_e64 v75, v225, v224, s[0:1]
	v_mul_f32_e32 v74, v8, v76
	v_cmp_lt_i32_e32 vcc, 0, v1
	s_waitcnt lgkmcnt(0)
	v_mul_f32_e32 v75, v16, v75
	v_sub_f32_e32 v16, v74, v75
	v_add_f32_e32 v74, v74, v75
	v_cndmask_b32_e64 v74, v8, v74, s[0:1]
	v_cndmask_b32_e32 v16, v16, v74, vcc
	v_mov_b32_e32 v224, v9
	v_mov_b32_e32 v225, v9
	v_cmp_eq_u32_e64 s[0:1], 1, v1
	s_nop 0
	v_permlane16_swap_b32_e32 v224, v225
	v_cndmask_b32_e64 v75, v225, v224, s[0:1]
	v_mul_f32_e32 v74, v9, v77
	v_cmp_lt_i32_e32 vcc, 0, v1
	s_waitcnt lgkmcnt(0)
	v_mul_f32_e32 v75, v17, v75
	v_sub_f32_e32 v17, v74, v75
	v_add_f32_e32 v74, v74, v75
	v_cndmask_b32_e64 v74, v9, v74, s[0:1]
	v_cndmask_b32_e32 v17, v17, v74, vcc

; DI void rope8(float (&v)[8], const float* __restrict__ rope, int s, int fq) {
;     const f32x4 c0 = *(const f32x4*)(rope + s * 16), c1 = *(const f32x4*)(rope + s * 16 + 4), s0 = *(const f32x4*)(rope + s * 16 + 8), s1 = *(const f32x4*)(rope + s * 16 + 12);
;     const float cs[8] = {c0[0], c0[1], c0[2], c0[3], c1[0], c1[1], c1[2], c1[3]}, sn[8] = {s0[0], s0[1], s0[2], s0[3], s1[0], s1[1], s1[2], s1[3]};
; #pragma unroll
;     for (int e = 0; e < 8; ++e) {
;         const float other = __shfl_xor(v[e], 16);
;         const float a = v[e] * cs[e], bq = other * sn[e];
;         v[e] = (fq == 0) ? (a - bq) : ((fq == 1) ? (a + bq) : v[e]);
;     }
;     DI void operator()(const pg8::f32x4 (&acc)[2][2][4][2], const pg8::Unit& u, int wr, int wc, int fr, int fq) const {
;     ...
;                         if (region < 2 && (wc & 1) == 0) rope8(v, rope, s, fq);
.LBB0_727:
	s_andn2_b64 vcc, exec, s[8:9]
	s_cbranch_vccnz .LBB0_777
	v_and_b32_e32 v11, 64, v183
	v_xor_b32_e32 v10, 16, v183
	v_add_u32_e32 v11, 64, v11
	v_cmp_lt_i32_e32 vcc, v10, v11
	v_lshlrev_b32_e32 v66, 6, v77
	s_nop 0
	v_cndmask_b32_e32 v10, v183, v10, vcc
	v_lshlrev_b32_e32 v79, 2, v10
	global_load_dwordx4 v[70:73], v66, s[68:69]
	global_load_dwordx4 v[10:13], v66, s[68:69] offset:32
	global_load_dwordx4 v[14:17], v66, s[68:69] offset:48
	s_nop 0
	global_load_dwordx4 v[66:69], v66, s[68:69] offset:16
	v_mov_b32_e32 v224, v2
	v_mov_b32_e32 v225, v2
	v_cmp_eq_u32_e64 s[0:1], 1, v1
	s_nop 0
	v_permlane16_swap_b32_e32 v224, v225
	v_cndmask_b32_e64 v80, v225, v224, s[0:1]
	v_cmp_lt_i32_e32 vcc, 0, v1
	s_waitcnt vmcnt(3)
	v_mul_f32_e32 v70, v2, v70
	s_waitcnt vmcnt(2) lgkmcnt(0)
	v_mul_f32_e32 v80, v10, v80
	v_sub_f32_e32 v10, v70, v80
	v_add_f32_e32 v70, v70, v80
	v_cndmask_b32_e64 v70, v2, v70, s[0:1]
	v_cndmask_b32_e32 v10, v10, v70, vcc
	v_mov_b32_e32 v224, v3
	v_mov_b32_e32 v225, v3
	v_cmp_eq_u32_e64 s[0:1], 1, v1
	s_nop 0
	v_permlane16_swap_b32_e32 v224, v225
	v_cndmask_b32_e64 v80, v225, v224, s[0:1]
	v_mul_f32_e32 v70, v3, v71
	v_cmp_lt_i32_e32 vcc, 0, v1
	s_waitcnt lgkmcnt(0)
	v_mul_f32_e32 v71, v11, v80
	v_sub_f32_e32 v11, v70, v71
	v_add_f32_e32 v70, v70, v71
	v_cndmask_b32_e64 v70, v3, v70, s[0:1]
	v_cndmask_b32_e32 v11, v11, v70, vcc
	v_mov_b32_e32 v224, v4
	v_mov_b32_e32 v225, v4
	v_cmp_eq_u32_e64 s[0:1], 1, v1
	s_nop 0
	v_permlane16_swap_b32_e32 v224, v225
	v_cndmask_b32_e64 v71, v225, v224, s[0:1]
	v_mul_f32_e32 v70, v4, v72
	v_cmp_lt_i32_e32 vcc, 0, v1
	s_waitcnt lgkmcnt(0)
	v_mul_f32_e32 v71, v12, v71
	v_sub_f32_e32 v12, v70, v71
	v_add_f32_e32 v70, v70, v71
	v_cndmask_b32_e64 v70, v4, v70, s[0:1]
	v_cndmask_b32_e32 v12, v12, v70, vcc
	v_mov_b32_e32 v224, v5
	v_mov_b32_e32 v225, v5
	v_cmp_eq_u32_e64 s[0:1], 1, v1
	s_nop 0
	v_permlane16_swap_b32_e32 v224, v225
	v_cndmask_b32_e64 v71, v225, v224, s[0:1]
	v_mul_f32_e32 v70, v5, v73
	v_cmp_lt_i32_e32 vcc, 0, v1
	s_waitcnt lgkmcnt(0)
	v_mul_f32_e32 v71, v13, v71
	v_sub_f32_e32 v13, v70, v71
	v_add_f32_e32 v70, v70, v71
	v_cndmask_b32_e64 v70, v5, v70, s[0:1]
	v_cndmask_b32_e32 v13, v13, v70, vcc
	v_mov_b32_e32 v224, v6
	v_mov_b32_e32 v225, v6
	v_cmp_eq_u32_e64 s[0:1], 1, v1
	s_nop 0
	v_permlane16_swap_b32_e32 v224, v225
	v_cndmask_b32_e64 v70, v225, v224, s[0:1]
	s_waitcnt vmcnt(0)
	v_mul_f32_e32 v66, v6, v66
	v_cmp_lt_i32_e32 vcc, 0, v1
	s_waitcnt lgkmcnt(0)
	v_mul_f32_e32 v70, v14, v70
	v_sub_f32_e32 v14, v66, v70
	v_add_f32_e32 v66, v66, v70
	v_cndmask_b32_e64 v66, v6, v66, s[0:1]
	v_cndmask_b32_e32 v14, v14, v66, vcc
	v_mov_b32_e32 v224, v7
	v_mov_b32_e32 v225, v7
	v_cmp_eq_u32_e64 s[0:1], 1, v1
	s_nop 0
	v_permlane16_swap_b32_e32 v224, v225
	v_cndmask_b32_e64 v70, v225, v224, s[0:1]
	v_mul_f32_e32 v66, v7, v67
	v_cmp_lt_i32_e32 vcc, 0, v1
	s_waitcnt lgkmcnt(0)
	v_mul_f32_e32 v67, v15, v70
	v_sub_f32_e32 v15, v66, v67
	v_add_f32_e32 v66, v66, v67
	v_cndmask_b32_e64 v66, v7, v66, s[0:1]
	v_cndmask_b32_e32 v15, v15, v66, vcc
	v_mov_b32_e32 v224, v8
	v_mov_b32_e32 v225, v8
	v_cmp_eq_u32_e64 s[0:1], 1, v1
	s_nop 0
	v_permlane16_swap_b32_e32 v224, v225
	v_cndmask_b32_e64 v67, v225, v224, s[0:1]
	v_mul_f32_e32 v66, v8, v68
	v_cmp_lt_i32_e32 vcc, 0, v1
	s_waitcnt lgkmcnt(0)
	v_mul_f32_e32 v67, v16, v67
	v_sub_f32_e32 v16, v66, v67
	v_add_f32_e32 v66, v66, v67
	v_cndmask_b32_e64 v66, v8, v66, s[0:1]
	v_cndmask_b32_e32 v16, v16, v66, vcc
	v_mov_b32_e32 v224, v9
	v_mov_b32_e32 v225, v9
	v_cmp_eq_u32_e64 s[0:1], 1, v1
	s_nop 0
	v_permlane16_swap_b32_e32 v224, v225
	v_cndmask_b32_e64 v67, v225, v224, s[0:1]
	v_mul_f32_e32 v66, v9, v69
	v_cmp_lt_i32_e32 vcc, 0, v1
	s_waitcnt lgkmcnt(0)
	v_mul_f32_e32 v67, v17, v67
	v_sub_f32_e32 v17, v66, v67
	v_add_f32_e32 v66, v66, v67
	v_cndmask_b32_e64 v66, v9, v66, s[0:1]
	v_cndmask_b32_e32 v17, v17, v66, vcc

; DI void rope8(float (&v)[8], const float* __restrict__ rope, int s, int fq) {
;     const f32x4 c0 = *(const f32x4*)(rope + s * 16), c1 = *(const f32x4*)(rope + s * 16 + 4), s0 = *(const f32x4*)(rope + s * 16 + 8), s1 = *(const f32x4*)(rope + s * 16 + 12);
;     const float cs[8] = {c0[0], c0[1], c0[2], c0[3], c1[0], c1[1], c1[2], c1[3]}, sn[8] = {s0[0], s0[1], s0[2], s0[3], s1[0], s1[1], s1[2], s1[3]};
; #pragma unroll
;     for (int e = 0; e < 8; ++e) {
;         const float other = __shfl_xor(v[e], 16);
;         const float a = v[e] * cs[e], bq = other * sn[e];
;         v[e] = (fq == 0) ? (a - bq) : ((fq == 1) ? (a + bq) : v[e]);
;     }
;     DI void operator()(const pg8::f32x4 (&acc)[2][2][4][2], const pg8::Unit& u, int wr, int wc, int fr, int fq) const {
;     ...
;                         if (region < 2 && (wc & 1) == 0) rope8(v, rope, s, fq);
.LBB0_787:
	s_andn2_b64 vcc, exec, s[8:9]
	s_cbranch_vccnz .LBB0_837
	v_and_b32_e32 v11, 64, v183
	v_xor_b32_e32 v10, 16, v183
	v_add_u32_e32 v11, 64, v11
	v_cmp_lt_i32_e32 vcc, v10, v11
	v_lshlrev_b32_e32 v58, 6, v67
	s_nop 0
	v_cndmask_b32_e32 v10, v183, v10, vcc
	v_lshlrev_b32_e32 v68, 2, v10
	global_load_dwordx4 v[62:65], v58, s[68:69]
	global_load_dwordx4 v[10:13], v58, s[68:69] offset:32
	global_load_dwordx4 v[14:17], v58, s[68:69] offset:48
	s_nop 0
	global_load_dwordx4 v[58:61], v58, s[68:69] offset:16
	v_mov_b32_e32 v224, v2
	v_mov_b32_e32 v225, v2
	v_cmp_eq_u32_e64 s[0:1], 1, v1
	s_nop 0
	v_permlane16_swap_b32_e32 v224, v225
	v_cndmask_b32_e64 v69, v225, v224, s[0:1]
	v_cmp_lt_i32_e32 vcc, 0, v1
	s_waitcnt vmcnt(3)
	v_mul_f32_e32 v62, v2, v62
	s_waitcnt vmcnt(2) lgkmcnt(0)
	v_mul_f32_e32 v69, v10, v69
	v_sub_f32_e32 v10, v62, v69
	v_add_f32_e32 v62, v62, v69
	v_cndmask_b32_e64 v62, v2, v62, s[0:1]
	v_cndmask_b32_e32 v10, v10, v62, vcc
	v_mov_b32_e32 v224, v3
	v_mov_b32_e32 v225, v3
	v_cmp_eq_u32_e64 s[0:1], 1, v1
	s_nop 0
	v_permlane16_swap_b32_e32 v224, v225
	v_cndmask_b32_e64 v69, v225, v224, s[0:1]
	v_mul_f32_e32 v62, v3, v63
	v_cmp_lt_i32_e32 vcc, 0, v1
	s_waitcnt lgkmcnt(0)
	v_mul_f32_e32 v63, v11, v69
	v_sub_f32_e32 v11, v62, v63
	v_add_f32_e32 v62, v62, v63
	v_cndmask_b32_e64 v62, v3, v62, s[0:1]
	v_cndmask_b32_e32 v11, v11, v62, vcc
	v_mov_b32_e32 v224, v4
	v_mov_b32_e32 v225, v4
	v_cmp_eq_u32_e64 s[0:1], 1, v1
	s_nop 0
	v_permlane16_swap_b32_e32 v224, v225
	v_cndmask_b32_e64 v63, v225, v224, s[0:1]
	v_mul_f32_e32 v62, v4, v64
	v_cmp_lt_i32_e32 vcc, 0, v1
	s_waitcnt lgkmcnt(0)
	v_mul_f32_e32 v63, v12, v63
	v_sub_f32_e32 v12, v62, v63
	v_add_f32_e32 v62, v62, v63
	v_cndmask_b32_e64 v62, v4, v62, s[0:1]
	v_cndmask_b32_e32 v12, v12, v62, vcc
	v_mov_b32_e32 v224, v5
	v_mov_b32_e32 v225, v5
	v_cmp_eq_u32_e64 s[0:1], 1, v1
	s_nop 0
	v_permlane16_swap_b32_e32 v224, v225
	v_cndmask_b32_e64 v63, v225, v224, s[0:1]
	v_mul_f32_e32 v62, v5, v65
	v_cmp_lt_i32_e32 vcc, 0, v1
	s_waitcnt lgkmcnt(0)
	v_mul_f32_e32 v63, v13, v63
	v_sub_f32_e32 v13, v62, v63
	v_add_f32_e32 v62, v62, v63
	v_cndmask_b32_e64 v62, v5, v62, s[0:1]
	v_cndmask_b32_e32 v13, v13, v62, vcc
	v_mov_b32_e32 v224, v6
	v_mov_b32_e32 v225, v6
	v_cmp_eq_u32_e64 s[0:1], 1, v1
	s_nop 0
	v_permlane16_swap_b32_e32 v224, v225
	v_cndmask_b32_e64 v62, v225, v224, s[0:1]
	s_waitcnt vmcnt(0)
	v_mul_f32_e32 v58, v6, v58
	v_cmp_lt_i32_e32 vcc, 0, v1
	s_waitcnt lgkmcnt(0)
	v_mul_f32_e32 v62, v14, v62
	v_sub_f32_e32 v14, v58, v62
	v_add_f32_e32 v58, v58, v62
	v_cndmask_b32_e64 v58, v6, v58, s[0:1]
	v_cndmask_b32_e32 v14, v14, v58, vcc
	v_mov_b32_e32 v224, v7
	v_mov_b32_e32 v225, v7
	v_cmp_eq_u32_e64 s[0:1], 1, v1
	s_nop 0
	v_permlane16_swap_b32_e32 v224, v225
	v_cndmask_b32_e64 v62, v225, v224, s[0:1]
	v_mul_f32_e32 v58, v7, v59
	v_cmp_lt_i32_e32 vcc, 0, v1
	s_waitcnt lgkmcnt(0)
	v_mul_f32_e32 v59, v15, v62
	v_sub_f32_e32 v15, v58, v59
	v_add_f32_e32 v58, v58, v59
	v_cndmask_b32_e64 v58, v7, v58, s[0:1]
	v_cndmask_b32_e32 v15, v15, v58, vcc
	v_mov_b32_e32 v224, v8
	v_mov_b32_e32 v225, v8
	v_cmp_eq_u32_e64 s[0:1], 1, v1
	s_nop 0
	v_permlane16_swap_b32_e32 v224, v225
	v_cndmask_b32_e64 v59, v225, v224, s[0:1]
	v_mul_f32_e32 v58, v8, v60
	v_cmp_lt_i32_e32 vcc, 0, v1
	s_waitcnt lgkmcnt(0)
	v_mul_f32_e32 v59, v16, v59
	v_sub_f32_e32 v16, v58, v59
	v_add_f32_e32 v58, v58, v59
	v_cndmask_b32_e64 v58, v8, v58, s[0:1]
	v_cndmask_b32_e32 v16, v16, v58, vcc
	v_mov_b32_e32 v224, v9
	v_mov_b32_e32 v225, v9
	v_cmp_eq_u32_e64 s[0:1], 1, v1
	s_nop 0
	v_permlane16_swap_b32_e32 v224, v225
	v_cndmask_b32_e64 v59, v225, v224, s[0:1]
	v_mul_f32_e32 v58, v9, v61
	v_cmp_lt_i32_e32 vcc, 0, v1
	s_waitcnt lgkmcnt(0)
	v_mul_f32_e32 v59, v17, v59
	v_sub_f32_e32 v17, v58, v59
	v_add_f32_e32 v58, v58, v59
	v_cndmask_b32_e64 v58, v9, v58, s[0:1]
	v_cndmask_b32_e32 v17, v17, v58, vcc

; DI void rope8(float (&v)[8], const float* __restrict__ rope, int s, int fq) {
;     const f32x4 c0 = *(const f32x4*)(rope + s * 16), c1 = *(const f32x4*)(rope + s * 16 + 4), s0 = *(const f32x4*)(rope + s * 16 + 8), s1 = *(const f32x4*)(rope + s * 16 + 12);
;     const float cs[8] = {c0[0], c0[1], c0[2], c0[3], c1[0], c1[1], c1[2], c1[3]}, sn[8] = {s0[0], s0[1], s0[2], s0[3], s1[0], s1[1], s1[2], s1[3]};
; #pragma unroll
;     for (int e = 0; e < 8; ++e) {
;         const float other = __shfl_xor(v[e], 16);
;         const float a = v[e] * cs[e], bq = other * sn[e];
;         v[e] = (fq == 0) ? (a - bq) : ((fq == 1) ? (a + bq) : v[e]);
;     }
;     DI void operator()(const pg8::f32x4 (&acc)[2][2][4][2], const pg8::Unit& u, int wr, int wc, int fr, int fq) const {
;     ...
;                         if (region < 2 && (wc & 1) == 0) rope8(v, rope, s, fq);
.LBB0_847:
	s_andn2_b64 vcc, exec, s[8:9]
	s_cbranch_vccnz .LBB0_897
	v_and_b32_e32 v11, 64, v183
	v_xor_b32_e32 v10, 16, v183
	v_add_u32_e32 v11, 64, v11
	v_cmp_lt_i32_e32 vcc, v10, v11
	v_lshlrev_b32_e32 v50, 6, v59
	s_nop 0
	v_cndmask_b32_e32 v10, v183, v10, vcc
	v_lshlrev_b32_e32 v60, 2, v10
	global_load_dwordx4 v[54:57], v50, s[68:69]
	global_load_dwordx4 v[10:13], v50, s[68:69] offset:32
	global_load_dwordx4 v[14:17], v50, s[68:69] offset:48
	s_nop 0
	global_load_dwordx4 v[50:53], v50, s[68:69] offset:16
	v_mov_b32_e32 v224, v2
	v_mov_b32_e32 v225, v2
	v_cmp_eq_u32_e64 s[0:1], 1, v1
	s_nop 0
	v_permlane16_swap_b32_e32 v224, v225
	v_cndmask_b32_e64 v61, v225, v224, s[0:1]
	v_cmp_lt_i32_e32 vcc, 0, v1
	s_waitcnt vmcnt(3)
	v_mul_f32_e32 v54, v2, v54
	s_waitcnt vmcnt(2) lgkmcnt(0)
	v_mul_f32_e32 v61, v10, v61
	v_sub_f32_e32 v10, v54, v61
	v_add_f32_e32 v54, v54, v61
	v_cndmask_b32_e64 v54, v2, v54, s[0:1]
	v_cndmask_b32_e32 v10, v10, v54, vcc
	v_mov_b32_e32 v224, v3
	v_mov_b32_e32 v225, v3
	v_cmp_eq_u32_e64 s[0:1], 1, v1
	s_nop 0
	v_permlane16_swap_b32_e32 v224, v225
	v_cndmask_b32_e64 v61, v225, v224, s[0:1]
	v_mul_f32_e32 v54, v3, v55
	v_cmp_lt_i32_e32 vcc, 0, v1
	s_waitcnt lgkmcnt(0)
	v_mul_f32_e32 v55, v11, v61
	v_sub_f32_e32 v11, v54, v55
	v_add_f32_e32 v54, v54, v55
	v_cndmask_b32_e64 v54, v3, v54, s[0:1]
	v_cndmask_b32_e32 v11, v11, v54, vcc
	v_mov_b32_e32 v224, v4
	v_mov_b32_e32 v225, v4
	v_cmp_eq_u32_e64 s[0:1], 1, v1
	s_nop 0
	v_permlane16_swap_b32_e32 v224, v225
	v_cndmask_b32_e64 v55, v225, v224, s[0:1]
	v_mul_f32_e32 v54, v4, v56
	v_cmp_lt_i32_e32 vcc, 0, v1
	s_waitcnt lgkmcnt(0)
	v_mul_f32_e32 v55, v12, v55
	v_sub_f32_e32 v12, v54, v55
	v_add_f32_e32 v54, v54, v55
	v_cndmask_b32_e64 v54, v4, v54, s[0:1]
	v_cndmask_b32_e32 v12, v12, v54, vcc
	v_mov_b32_e32 v224, v5
	v_mov_b32_e32 v225, v5
	v_cmp_eq_u32_e64 s[0:1], 1, v1
	s_nop 0
	v_permlane16_swap_b32_e32 v224, v225
	v_cndmask_b32_e64 v55, v225, v224, s[0:1]
	v_mul_f32_e32 v54, v5, v57
	v_cmp_lt_i32_e32 vcc, 0, v1
	s_waitcnt lgkmcnt(0)
	v_mul_f32_e32 v55, v13, v55
	v_sub_f32_e32 v13, v54, v55
	v_add_f32_e32 v54, v54, v55
	v_cndmask_b32_e64 v54, v5, v54, s[0:1]
	v_cndmask_b32_e32 v13, v13, v54, vcc
	v_mov_b32_e32 v224, v6
	v_mov_b32_e32 v225, v6
	v_cmp_eq_u32_e64 s[0:1], 1, v1
	s_nop 0
	v_permlane16_swap_b32_e32 v224, v225
	v_cndmask_b32_e64 v54, v225, v224, s[0:1]
	s_waitcnt vmcnt(0)
	v_mul_f32_e32 v50, v6, v50
	v_cmp_lt_i32_e32 vcc, 0, v1
	s_waitcnt lgkmcnt(0)
	v_mul_f32_e32 v54, v14, v54
	v_sub_f32_e32 v14, v50, v54
	v_add_f32_e32 v50, v50, v54
	v_cndmask_b32_e64 v50, v6, v50, s[0:1]
	v_cndmask_b32_e32 v14, v14, v50, vcc
	v_mov_b32_e32 v224, v7
	v_mov_b32_e32 v225, v7
	v_cmp_eq_u32_e64 s[0:1], 1, v1
	s_nop 0
	v_permlane16_swap_b32_e32 v224, v225
	v_cndmask_b32_e64 v54, v225, v224, s[0:1]
	v_mul_f32_e32 v50, v7, v51
	v_cmp_lt_i32_e32 vcc, 0, v1
	s_waitcnt lgkmcnt(0)
	v_mul_f32_e32 v51, v15, v54
	v_sub_f32_e32 v15, v50, v51
	v_add_f32_e32 v50, v50, v51
	v_cndmask_b32_e64 v50, v7, v50, s[0:1]
	v_cndmask_b32_e32 v15, v15, v50, vcc
	v_mov_b32_e32 v224, v8
	v_mov_b32_e32 v225, v8
	v_cmp_eq_u32_e64 s[0:1], 1, v1
	s_nop 0
	v_permlane16_swap_b32_e32 v224, v225
	v_cndmask_b32_e64 v51, v225, v224, s[0:1]
	v_mul_f32_e32 v50, v8, v52
	v_cmp_lt_i32_e32 vcc, 0, v1
	s_waitcnt lgkmcnt(0)
	v_mul_f32_e32 v51, v16, v51
	v_sub_f32_e32 v16, v50, v51
	v_add_f32_e32 v50, v50, v51
	v_cndmask_b32_e64 v50, v8, v50, s[0:1]
	v_cndmask_b32_e32 v16, v16, v50, vcc
	v_mov_b32_e32 v224, v9
	v_mov_b32_e32 v225, v9
	v_cmp_eq_u32_e64 s[0:1], 1, v1
	s_nop 0
	v_permlane16_swap_b32_e32 v224, v225
	v_cndmask_b32_e64 v51, v225, v224, s[0:1]
	v_mul_f32_e32 v50, v9, v53
	v_cmp_lt_i32_e32 vcc, 0, v1
	s_waitcnt lgkmcnt(0)
	v_mul_f32_e32 v51, v17, v51
	v_sub_f32_e32 v17, v50, v51
	v_add_f32_e32 v50, v50, v51
	v_cndmask_b32_e64 v50, v9, v50, s[0:1]
	v_cndmask_b32_e32 v17, v17, v50, vcc

; DI void rope8(float (&v)[8], const float* __restrict__ rope, int s, int fq) {
;     const f32x4 c0 = *(const f32x4*)(rope + s * 16), c1 = *(const f32x4*)(rope + s * 16 + 4), s0 = *(const f32x4*)(rope + s * 16 + 8), s1 = *(const f32x4*)(rope + s * 16 + 12);
;     const float cs[8] = {c0[0], c0[1], c0[2], c0[3], c1[0], c1[1], c1[2], c1[3]}, sn[8] = {s0[0], s0[1], s0[2], s0[3], s1[0], s1[1], s1[2], s1[3]};
; #pragma unroll
;     for (int e = 0; e < 8; ++e) {
;         const float other = __shfl_xor(v[e], 16);
;         const float a = v[e] * cs[e], bq = other * sn[e];
;         v[e] = (fq == 0) ? (a - bq) : ((fq == 1) ? (a + bq) : v[e]);
;     }
;     DI void operator()(const pg8::f32x4 (&acc)[2][2][4][2], const pg8::Unit& u, int wr, int wc, int fr, int fq) const {
;     ...
;                         if (region < 2 && (wc & 1) == 0) rope8(v, rope, s, fq);
.LBB0_907:
	s_andn2_b64 vcc, exec, s[8:9]
	s_cbranch_vccnz .LBB0_957
	v_and_b32_e32 v11, 64, v183
	v_xor_b32_e32 v10, 16, v183
	v_add_u32_e32 v11, 64, v11
	v_cmp_lt_i32_e32 vcc, v10, v11
	v_lshlrev_b32_e32 v42, 6, v51
	s_nop 0
	v_cndmask_b32_e32 v10, v183, v10, vcc
	v_lshlrev_b32_e32 v52, 2, v10
	global_load_dwordx4 v[46:49], v42, s[68:69]
	global_load_dwordx4 v[10:13], v42, s[68:69] offset:32
	global_load_dwordx4 v[14:17], v42, s[68:69] offset:48
	s_nop 0
	global_load_dwordx4 v[42:45], v42, s[68:69] offset:16
	v_mov_b32_e32 v224, v2
	v_mov_b32_e32 v225, v2
	v_cmp_eq_u32_e64 s[0:1], 1, v1
	s_nop 0
	v_permlane16_swap_b32_e32 v224, v225
	v_cndmask_b32_e64 v53, v225, v224, s[0:1]
	v_cmp_lt_i32_e32 vcc, 0, v1
	s_waitcnt vmcnt(3)
	v_mul_f32_e32 v46, v2, v46
	s_waitcnt vmcnt(2) lgkmcnt(0)
	v_mul_f32_e32 v53, v10, v53
	v_sub_f32_e32 v10, v46, v53
	v_add_f32_e32 v46, v46, v53
	v_cndmask_b32_e64 v46, v2, v46, s[0:1]
	v_cndmask_b32_e32 v10, v10, v46, vcc
	v_mov_b32_e32 v224, v3
	v_mov_b32_e32 v225, v3
	v_cmp_eq_u32_e64 s[0:1], 1, v1
	s_nop 0
	v_permlane16_swap_b32_e32 v224, v225
	v_cndmask_b32_e64 v53, v225, v224, s[0:1]
	v_mul_f32_e32 v46, v3, v47
	v_cmp_lt_i32_e32 vcc, 0, v1
	s_waitcnt lgkmcnt(0)
	v_mul_f32_e32 v47, v11, v53
	v_sub_f32_e32 v11, v46, v47
	v_add_f32_e32 v46, v46, v47
	v_cndmask_b32_e64 v46, v3, v46, s[0:1]
	v_cndmask_b32_e32 v11, v11, v46, vcc
	v_mov_b32_e32 v224, v4
	v_mov_b32_e32 v225, v4
	v_cmp_eq_u32_e64 s[0:1], 1, v1
	s_nop 0
	v_permlane16_swap_b32_e32 v224, v225
	v_cndmask_b32_e64 v47, v225, v224, s[0:1]
	v_mul_f32_e32 v46, v4, v48
	v_cmp_lt_i32_e32 vcc, 0, v1
	s_waitcnt lgkmcnt(0)
	v_mul_f32_e32 v47, v12, v47
	v_sub_f32_e32 v12, v46, v47
	v_add_f32_e32 v46, v46, v47
	v_cndmask_b32_e64 v46, v4, v46, s[0:1]
	v_cndmask_b32_e32 v12, v12, v46, vcc
	v_mov_b32_e32 v224, v5
	v_mov_b32_e32 v225, v5
	v_cmp_eq_u32_e64 s[0:1], 1, v1
	s_nop 0
	v_permlane16_swap_b32_e32 v224, v225
	v_cndmask_b32_e64 v47, v225, v224, s[0:1]
	v_mul_f32_e32 v46, v5, v49
	v_cmp_lt_i32_e32 vcc, 0, v1
	s_waitcnt lgkmcnt(0)
	v_mul_f32_e32 v47, v13, v47
	v_sub_f32_e32 v13, v46, v47
	v_add_f32_e32 v46, v46, v47
	v_cndmask_b32_e64 v46, v5, v46, s[0:1]
	v_cndmask_b32_e32 v13, v13, v46, vcc
	v_mov_b32_e32 v224, v6
	v_mov_b32_e32 v225, v6
	v_cmp_eq_u32_e64 s[0:1], 1, v1
	s_nop 0
	v_permlane16_swap_b32_e32 v224, v225
	v_cndmask_b32_e64 v46, v225, v224, s[0:1]
	s_waitcnt vmcnt(0)
	v_mul_f32_e32 v42, v6, v42
	v_cmp_lt_i32_e32 vcc, 0, v1
	s_waitcnt lgkmcnt(0)
	v_mul_f32_e32 v46, v14, v46
	v_sub_f32_e32 v14, v42, v46
	v_add_f32_e32 v42, v42, v46
	v_cndmask_b32_e64 v42, v6, v42, s[0:1]
	v_cndmask_b32_e32 v14, v14, v42, vcc
	v_mov_b32_e32 v224, v7
	v_mov_b32_e32 v225, v7
	v_cmp_eq_u32_e64 s[0:1], 1, v1
	s_nop 0
	v_permlane16_swap_b32_e32 v224, v225
	v_cndmask_b32_e64 v46, v225, v224, s[0:1]
	v_mul_f32_e32 v42, v7, v43
	v_cmp_lt_i32_e32 vcc, 0, v1
	s_waitcnt lgkmcnt(0)
	v_mul_f32_e32 v43, v15, v46
	v_sub_f32_e32 v15, v42, v43
	v_add_f32_e32 v42, v42, v43
	v_cndmask_b32_e64 v42, v7, v42, s[0:1]
	v_cndmask_b32_e32 v15, v15, v42, vcc
	v_mov_b32_e32 v224, v8
	v_mov_b32_e32 v225, v8
	v_cmp_eq_u32_e64 s[0:1], 1, v1
	s_nop 0
	v_permlane16_swap_b32_e32 v224, v225
	v_cndmask_b32_e64 v43, v225, v224, s[0:1]
	v_mul_f32_e32 v42, v8, v44
	v_cmp_lt_i32_e32 vcc, 0, v1
	s_waitcnt lgkmcnt(0)
	v_mul_f32_e32 v43, v16, v43
	v_sub_f32_e32 v16, v42, v43
	v_add_f32_e32 v42, v42, v43
	v_cndmask_b32_e64 v42, v8, v42, s[0:1]
	v_cndmask_b32_e32 v16, v16, v42, vcc
	v_mov_b32_e32 v224, v9
	v_mov_b32_e32 v225, v9
	v_cmp_eq_u32_e64 s[0:1], 1, v1
	s_nop 0
	v_permlane16_swap_b32_e32 v224, v225
	v_cndmask_b32_e64 v43, v225, v224, s[0:1]
	v_mul_f32_e32 v42, v9, v45
	v_cmp_lt_i32_e32 vcc, 0, v1
	s_waitcnt lgkmcnt(0)
	v_mul_f32_e32 v43, v17, v43
	v_sub_f32_e32 v17, v42, v43
	v_add_f32_e32 v42, v42, v43
	v_cndmask_b32_e64 v42, v9, v42, s[0:1]
	v_cndmask_b32_e32 v17, v17, v42, vcc

; DI void rope8(float (&v)[8], const float* __restrict__ rope, int s, int fq) {
;     const f32x4 c0 = *(const f32x4*)(rope + s * 16), c1 = *(const f32x4*)(rope + s * 16 + 4), s0 = *(const f32x4*)(rope + s * 16 + 8), s1 = *(const f32x4*)(rope + s * 16 + 12);
;     const float cs[8] = {c0[0], c0[1], c0[2], c0[3], c1[0], c1[1], c1[2], c1[3]}, sn[8] = {s0[0], s0[1], s0[2], s0[3], s1[0], s1[1], s1[2], s1[3]};
; #pragma unroll
;     for (int e = 0; e < 8; ++e) {
;         const float other = __shfl_xor(v[e], 16);
;         const float a = v[e] * cs[e], bq = other * sn[e];
;         v[e] = (fq == 0) ? (a - bq) : ((fq == 1) ? (a + bq) : v[e]);
;     }
;     DI void operator()(const pg8::f32x4 (&acc)[2][2][4][2], const pg8::Unit& u, int wr, int wc, int fr, int fq) const {
;     ...
;                         if (region < 2 && (wc & 1) == 0) rope8(v, rope, s, fq);
.LBB0_967:
	s_andn2_b64 vcc, exec, s[8:9]
	s_cbranch_vccnz .LBB0_1017
	v_and_b32_e32 v11, 64, v183
	v_xor_b32_e32 v10, 16, v183
	v_add_u32_e32 v11, 64, v11
	v_cmp_lt_i32_e32 vcc, v10, v11
	v_lshlrev_b32_e32 v34, 6, v45
	s_nop 0
	v_cndmask_b32_e32 v10, v183, v10, vcc
	v_lshlrev_b32_e32 v46, 2, v10
	global_load_dwordx4 v[38:41], v34, s[68:69]
	global_load_dwordx4 v[10:13], v34, s[68:69] offset:32
	global_load_dwordx4 v[14:17], v34, s[68:69] offset:48
	s_nop 0
	global_load_dwordx4 v[34:37], v34, s[68:69] offset:16
	v_mov_b32_e32 v224, v2
	v_mov_b32_e32 v225, v2
	v_cmp_eq_u32_e64 s[0:1], 1, v1
	s_nop 0
	v_permlane16_swap_b32_e32 v224, v225
	v_cndmask_b32_e64 v47, v225, v224, s[0:1]
	v_cmp_lt_i32_e32 vcc, 0, v1
	s_waitcnt vmcnt(3)
	v_mul_f32_e32 v38, v2, v38
	s_waitcnt vmcnt(2) lgkmcnt(0)
	v_mul_f32_e32 v47, v10, v47
	v_sub_f32_e32 v10, v38, v47
	v_add_f32_e32 v38, v38, v47
	v_cndmask_b32_e64 v38, v2, v38, s[0:1]
	v_cndmask_b32_e32 v10, v10, v38, vcc
	v_mov_b32_e32 v224, v3
	v_mov_b32_e32 v225, v3
	v_cmp_eq_u32_e64 s[0:1], 1, v1
	s_nop 0
	v_permlane16_swap_b32_e32 v224, v225
	v_cndmask_b32_e64 v47, v225, v224, s[0:1]
	v_mul_f32_e32 v38, v3, v39
	v_cmp_lt_i32_e32 vcc, 0, v1
	s_waitcnt lgkmcnt(0)
	v_mul_f32_e32 v39, v11, v47
	v_sub_f32_e32 v11, v38, v39
	v_add_f32_e32 v38, v38, v39
	v_cndmask_b32_e64 v38, v3, v38, s[0:1]
	v_cndmask_b32_e32 v11, v11, v38, vcc
	v_mov_b32_e32 v224, v4
	v_mov_b32_e32 v225, v4
	v_cmp_eq_u32_e64 s[0:1], 1, v1
	s_nop 0
	v_permlane16_swap_b32_e32 v224, v225
	v_cndmask_b32_e64 v39, v225, v224, s[0:1]
	v_mul_f32_e32 v38, v4, v40
	v_cmp_lt_i32_e32 vcc, 0, v1
	s_waitcnt lgkmcnt(0)
	v_mul_f32_e32 v39, v12, v39
	v_sub_f32_e32 v12, v38, v39
	v_add_f32_e32 v38, v38, v39
	v_cndmask_b32_e64 v38, v4, v38, s[0:1]
	v_cndmask_b32_e32 v12, v12, v38, vcc
	v_mov_b32_e32 v224, v5
	v_mov_b32_e32 v225, v5
	v_cmp_eq_u32_e64 s[0:1], 1, v1
	s_nop 0
	v_permlane16_swap_b32_e32 v224, v225
	v_cndmask_b32_e64 v39, v225, v224, s[0:1]
	v_mul_f32_e32 v38, v5, v41
	v_cmp_lt_i32_e32 vcc, 0, v1
	s_waitcnt lgkmcnt(0)
	v_mul_f32_e32 v39, v13, v39
	v_sub_f32_e32 v13, v38, v39
	v_add_f32_e32 v38, v38, v39
	v_cndmask_b32_e64 v38, v5, v38, s[0:1]
	v_cndmask_b32_e32 v13, v13, v38, vcc
	v_mov_b32_e32 v224, v6
	v_mov_b32_e32 v225, v6
	v_cmp_eq_u32_e64 s[0:1], 1, v1
	s_nop 0
	v_permlane16_swap_b32_e32 v224, v225
	v_cndmask_b32_e64 v38, v225, v224, s[0:1]
	s_waitcnt vmcnt(0)
	v_mul_f32_e32 v34, v6, v34
	v_cmp_lt_i32_e32 vcc, 0, v1
	s_waitcnt lgkmcnt(0)
	v_mul_f32_e32 v38, v14, v38
	v_sub_f32_e32 v14, v34, v38
	v_add_f32_e32 v34, v34, v38
	v_cndmask_b32_e64 v34, v6, v34, s[0:1]
	v_cndmask_b32_e32 v14, v14, v34, vcc
	v_mov_b32_e32 v224, v7
	v_mov_b32_e32 v225, v7
	v_cmp_eq_u32_e64 s[0:1], 1, v1
	s_nop 0
	v_permlane16_swap_b32_e32 v224, v225
	v_cndmask_b32_e64 v38, v225, v224, s[0:1]
	v_mul_f32_e32 v34, v7, v35
	v_cmp_lt_i32_e32 vcc, 0, v1
	s_waitcnt lgkmcnt(0)
	v_mul_f32_e32 v35, v15, v38
	v_sub_f32_e32 v15, v34, v35
	v_add_f32_e32 v34, v34, v35
	v_cndmask_b32_e64 v34, v7, v34, s[0:1]
	v_cndmask_b32_e32 v15, v15, v34, vcc
	v_mov_b32_e32 v224, v8
	v_mov_b32_e32 v225, v8
	v_cmp_eq_u32_e64 s[0:1], 1, v1
	s_nop 0
	v_permlane16_swap_b32_e32 v224, v225
	v_cndmask_b32_e64 v35, v225, v224, s[0:1]
	v_mul_f32_e32 v34, v8, v36
	v_cmp_lt_i32_e32 vcc, 0, v1
	s_waitcnt lgkmcnt(0)
	v_mul_f32_e32 v35, v16, v35
	v_sub_f32_e32 v16, v34, v35
	v_add_f32_e32 v34, v34, v35
	v_cndmask_b32_e64 v34, v8, v34, s[0:1]
	v_cndmask_b32_e32 v16, v16, v34, vcc
	v_mov_b32_e32 v224, v9
	v_mov_b32_e32 v225, v9
	v_cmp_eq_u32_e64 s[0:1], 1, v1
	s_nop 0
	v_permlane16_swap_b32_e32 v224, v225
	v_cndmask_b32_e64 v35, v225, v224, s[0:1]
	v_mul_f32_e32 v34, v9, v37
	v_cmp_lt_i32_e32 vcc, 0, v1
	s_waitcnt lgkmcnt(0)
	v_mul_f32_e32 v35, v17, v35
	v_sub_f32_e32 v17, v34, v35
	v_add_f32_e32 v34, v34, v35
	v_cndmask_b32_e64 v34, v9, v34, s[0:1]
	v_cndmask_b32_e32 v17, v17, v34, vcc

; DI void rope8(float (&v)[8], const float* __restrict__ rope, int s, int fq) {
;     const f32x4 c0 = *(const f32x4*)(rope + s * 16), c1 = *(const f32x4*)(rope + s * 16 + 4), s0 = *(const f32x4*)(rope + s * 16 + 8), s1 = *(const f32x4*)(rope + s * 16 + 12);
;     const float cs[8] = {c0[0], c0[1], c0[2], c0[3], c1[0], c1[1], c1[2], c1[3]}, sn[8] = {s0[0], s0[1], s0[2], s0[3], s1[0], s1[1], s1[2], s1[3]};
; #pragma unroll
;     for (int e = 0; e < 8; ++e) {
;         const float other = __shfl_xor(v[e], 16);
;         const float a = v[e] * cs[e], bq = other * sn[e];
;         v[e] = (fq == 0) ? (a - bq) : ((fq == 1) ? (a + bq) : v[e]);
;     }
;     DI void operator()(const pg8::f32x4 (&acc)[2][2][4][2], const pg8::Unit& u, int wr, int wc, int fr, int fq) const {
;     ...
;                         if (region < 2 && (wc & 1) == 0) rope8(v, rope, s, fq);
.LBB0_1027:
	s_andn2_b64 vcc, exec, s[8:9]
	s_cbranch_vccnz .LBB0_1077
	v_and_b32_e32 v11, 64, v183
	v_xor_b32_e32 v10, 16, v183
	v_add_u32_e32 v11, 64, v11
	v_cmp_lt_i32_e32 vcc, v10, v11
	v_lshlrev_b32_e32 v26, 6, v35
	s_nop 0
	v_cndmask_b32_e32 v10, v183, v10, vcc
	v_lshlrev_b32_e32 v36, 2, v10
	global_load_dwordx4 v[30:33], v26, s[68:69]
	global_load_dwordx4 v[10:13], v26, s[68:69] offset:32
	global_load_dwordx4 v[14:17], v26, s[68:69] offset:48
	s_nop 0
	global_load_dwordx4 v[26:29], v26, s[68:69] offset:16
	v_mov_b32_e32 v224, v2
	v_mov_b32_e32 v225, v2
	v_cmp_eq_u32_e64 s[0:1], 1, v1
	s_nop 0
	v_permlane16_swap_b32_e32 v224, v225
	v_cndmask_b32_e64 v37, v225, v224, s[0:1]
	v_cmp_lt_i32_e32 vcc, 0, v1
	s_waitcnt vmcnt(3)
	v_mul_f32_e32 v30, v2, v30
	s_waitcnt vmcnt(2) lgkmcnt(0)
	v_mul_f32_e32 v37, v10, v37
	v_sub_f32_e32 v10, v30, v37
	v_add_f32_e32 v30, v30, v37
	v_cndmask_b32_e64 v30, v2, v30, s[0:1]
	v_cndmask_b32_e32 v10, v10, v30, vcc
	v_mov_b32_e32 v224, v3
	v_mov_b32_e32 v225, v3
	v_cmp_eq_u32_e64 s[0:1], 1, v1
	s_nop 0
	v_permlane16_swap_b32_e32 v224, v225
	v_cndmask_b32_e64 v37, v225, v224, s[0:1]
	v_mul_f32_e32 v30, v3, v31
	v_cmp_lt_i32_e32 vcc, 0, v1
	s_waitcnt lgkmcnt(0)
	v_mul_f32_e32 v31, v11, v37
	v_sub_f32_e32 v11, v30, v31
	v_add_f32_e32 v30, v30, v31
	v_cndmask_b32_e64 v30, v3, v30, s[0:1]
	v_cndmask_b32_e32 v11, v11, v30, vcc
	v_mov_b32_e32 v224, v4
	v_mov_b32_e32 v225, v4
	v_cmp_eq_u32_e64 s[0:1], 1, v1
	s_nop 0
	v_permlane16_swap_b32_e32 v224, v225
	v_cndmask_b32_e64 v31, v225, v224, s[0:1]
	v_mul_f32_e32 v30, v4, v32
	v_cmp_lt_i32_e32 vcc, 0, v1
	s_waitcnt lgkmcnt(0)
	v_mul_f32_e32 v31, v12, v31
	v_sub_f32_e32 v12, v30, v31
	v_add_f32_e32 v30, v30, v31
	v_cndmask_b32_e64 v30, v4, v30, s[0:1]
	v_cndmask_b32_e32 v12, v12, v30, vcc
	v_mov_b32_e32 v224, v5
	v_mov_b32_e32 v225, v5
	v_cmp_eq_u32_e64 s[0:1], 1, v1
	s_nop 0
	v_permlane16_swap_b32_e32 v224, v225
	v_cndmask_b32_e64 v31, v225, v224, s[0:1]
	v_mul_f32_e32 v30, v5, v33
	v_cmp_lt_i32_e32 vcc, 0, v1
	s_waitcnt lgkmcnt(0)
	v_mul_f32_e32 v31, v13, v31
	v_sub_f32_e32 v13, v30, v31
	v_add_f32_e32 v30, v30, v31
	v_cndmask_b32_e64 v30, v5, v30, s[0:1]
	v_cndmask_b32_e32 v13, v13, v30, vcc
	v_mov_b32_e32 v224, v6
	v_mov_b32_e32 v225, v6
	v_cmp_eq_u32_e64 s[0:1], 1, v1
	s_nop 0
	v_permlane16_swap_b32_e32 v224, v225
	v_cndmask_b32_e64 v30, v225, v224, s[0:1]
	s_waitcnt vmcnt(0)
	v_mul_f32_e32 v26, v6, v26
	v_cmp_lt_i32_e32 vcc, 0, v1
	s_waitcnt lgkmcnt(0)
	v_mul_f32_e32 v30, v14, v30
	v_sub_f32_e32 v14, v26, v30
	v_add_f32_e32 v26, v26, v30
	v_cndmask_b32_e64 v26, v6, v26, s[0:1]
	v_cndmask_b32_e32 v14, v14, v26, vcc
	v_mov_b32_e32 v224, v7
	v_mov_b32_e32 v225, v7
	v_cmp_eq_u32_e64 s[0:1], 1, v1
	s_nop 0
	v_permlane16_swap_b32_e32 v224, v225
	v_cndmask_b32_e64 v30, v225, v224, s[0:1]
	v_mul_f32_e32 v26, v7, v27
	v_cmp_lt_i32_e32 vcc, 0, v1
	s_waitcnt lgkmcnt(0)
	v_mul_f32_e32 v27, v15, v30
	v_sub_f32_e32 v15, v26, v27
	v_add_f32_e32 v26, v26, v27
	v_cndmask_b32_e64 v26, v7, v26, s[0:1]
	v_cndmask_b32_e32 v15, v15, v26, vcc
	v_mov_b32_e32 v224, v8
	v_mov_b32_e32 v225, v8
	v_cmp_eq_u32_e64 s[0:1], 1, v1
	s_nop 0
	v_permlane16_swap_b32_e32 v224, v225
	v_cndmask_b32_e64 v27, v225, v224, s[0:1]
	v_mul_f32_e32 v26, v8, v28
	v_cmp_lt_i32_e32 vcc, 0, v1
	s_waitcnt lgkmcnt(0)
	v_mul_f32_e32 v27, v16, v27
	v_sub_f32_e32 v16, v26, v27
	v_add_f32_e32 v26, v26, v27
	v_cndmask_b32_e64 v26, v8, v26, s[0:1]
	v_cndmask_b32_e32 v16, v16, v26, vcc
	v_mov_b32_e32 v224, v9
	v_mov_b32_e32 v225, v9
	v_cmp_eq_u32_e64 s[0:1], 1, v1
	s_nop 0
	v_permlane16_swap_b32_e32 v224, v225
	v_cndmask_b32_e64 v27, v225, v224, s[0:1]
	v_mul_f32_e32 v26, v9, v29
	v_cmp_lt_i32_e32 vcc, 0, v1
	s_waitcnt lgkmcnt(0)
	v_mul_f32_e32 v27, v17, v27
	v_sub_f32_e32 v17, v26, v27
	v_add_f32_e32 v26, v26, v27
	v_cndmask_b32_e64 v26, v9, v26, s[0:1]
	v_cndmask_b32_e32 v17, v17, v26, vcc

; DI void rope8(float (&v)[8], const float* __restrict__ rope, int s, int fq) {
;     const f32x4 c0 = *(const f32x4*)(rope + s * 16), c1 = *(const f32x4*)(rope + s * 16 + 4), s0 = *(const f32x4*)(rope + s * 16 + 8), s1 = *(const f32x4*)(rope + s * 16 + 12);
;     const float cs[8] = {c0[0], c0[1], c0[2], c0[3], c1[0], c1[1], c1[2], c1[3]}, sn[8] = {s0[0], s0[1], s0[2], s0[3], s1[0], s1[1], s1[2], s1[3]};
; #pragma unroll
;     for (int e = 0; e < 8; ++e) {
;         const float other = __shfl_xor(v[e], 16);
;         const float a = v[e] * cs[e], bq = other * sn[e];
;         v[e] = (fq == 0) ? (a - bq) : ((fq == 1) ? (a + bq) : v[e]);
;     }
;     DI void operator()(const pg8::f32x4 (&acc)[2][2][4][2], const pg8::Unit& u, int wr, int wc, int fr, int fq) const {
;     ...
;                         if (region < 2 && (wc & 1) == 0) rope8(v, rope, s, fq);
.LBB0_1087:
	s_andn2_b64 vcc, exec, s[6:7]
	s_cbranch_vccnz .LBB0_1137
	v_and_b32_e32 v11, 64, v183
	v_xor_b32_e32 v10, 16, v183
	v_add_u32_e32 v11, 64, v11
	v_cmp_lt_i32_e32 vcc, v10, v11
	v_lshlrev_b32_e32 v18, 6, v27
	s_nop 0
	v_cndmask_b32_e32 v10, v183, v10, vcc
	v_lshlrev_b32_e32 v28, 2, v10
	global_load_dwordx4 v[22:25], v18, s[68:69]
	global_load_dwordx4 v[10:13], v18, s[68:69] offset:32
	global_load_dwordx4 v[14:17], v18, s[68:69] offset:48
	s_nop 0
	global_load_dwordx4 v[18:21], v18, s[68:69] offset:16
	v_mov_b32_e32 v224, v2
	v_mov_b32_e32 v225, v2
	v_cmp_eq_u32_e64 s[0:1], 1, v1
	s_nop 0
	v_permlane16_swap_b32_e32 v224, v225
	v_cndmask_b32_e64 v29, v225, v224, s[0:1]
	v_cmp_lt_i32_e32 vcc, 0, v1
	s_waitcnt vmcnt(3)
	v_mul_f32_e32 v22, v2, v22
	s_waitcnt vmcnt(2) lgkmcnt(0)
	v_mul_f32_e32 v29, v10, v29
	v_sub_f32_e32 v10, v22, v29
	v_add_f32_e32 v22, v22, v29
	v_cndmask_b32_e64 v22, v2, v22, s[0:1]
	v_cndmask_b32_e32 v10, v10, v22, vcc
	v_mov_b32_e32 v224, v3
	v_mov_b32_e32 v225, v3
	v_cmp_eq_u32_e64 s[0:1], 1, v1
	s_nop 0
	v_permlane16_swap_b32_e32 v224, v225
	v_cndmask_b32_e64 v29, v225, v224, s[0:1]
	v_mul_f32_e32 v22, v3, v23
	v_cmp_lt_i32_e32 vcc, 0, v1
	s_waitcnt lgkmcnt(0)
	v_mul_f32_e32 v23, v11, v29
	v_sub_f32_e32 v11, v22, v23
	v_add_f32_e32 v22, v22, v23
	v_cndmask_b32_e64 v22, v3, v22, s[0:1]
	v_cndmask_b32_e32 v11, v11, v22, vcc
	v_mov_b32_e32 v224, v4
	v_mov_b32_e32 v225, v4
	v_cmp_eq_u32_e64 s[0:1], 1, v1
	s_nop 0
	v_permlane16_swap_b32_e32 v224, v225
	v_cndmask_b32_e64 v23, v225, v224, s[0:1]
	v_mul_f32_e32 v22, v4, v24
	v_cmp_lt_i32_e32 vcc, 0, v1
	s_waitcnt lgkmcnt(0)
	v_mul_f32_e32 v23, v12, v23
	v_sub_f32_e32 v12, v22, v23
	v_add_f32_e32 v22, v22, v23
	v_cndmask_b32_e64 v22, v4, v22, s[0:1]
	v_cndmask_b32_e32 v12, v12, v22, vcc
	v_mov_b32_e32 v224, v5
	v_mov_b32_e32 v225, v5
	v_cmp_eq_u32_e64 s[0:1], 1, v1
	s_nop 0
	v_permlane16_swap_b32_e32 v224, v225
	v_cndmask_b32_e64 v23, v225, v224, s[0:1]
	v_mul_f32_e32 v22, v5, v25
	v_cmp_lt_i32_e32 vcc, 0, v1
	s_waitcnt lgkmcnt(0)
	v_mul_f32_e32 v23, v13, v23
	v_sub_f32_e32 v13, v22, v23
	v_add_f32_e32 v22, v22, v23
	v_cndmask_b32_e64 v22, v5, v22, s[0:1]
	v_cndmask_b32_e32 v13, v13, v22, vcc
	v_mov_b32_e32 v224, v6
	v_mov_b32_e32 v225, v6
	v_cmp_eq_u32_e64 s[0:1], 1, v1
	s_nop 0
	v_permlane16_swap_b32_e32 v224, v225
	v_cndmask_b32_e64 v22, v225, v224, s[0:1]
	s_waitcnt vmcnt(0)
	v_mul_f32_e32 v18, v6, v18
	v_cmp_lt_i32_e32 vcc, 0, v1
	s_waitcnt lgkmcnt(0)
	v_mul_f32_e32 v22, v14, v22
	v_sub_f32_e32 v14, v18, v22
	v_add_f32_e32 v18, v18, v22
	v_cndmask_b32_e64 v18, v6, v18, s[0:1]
	v_cndmask_b32_e32 v14, v14, v18, vcc
	v_mov_b32_e32 v224, v7
	v_mov_b32_e32 v225, v7
	v_cmp_eq_u32_e64 s[0:1], 1, v1
	s_nop 0
	v_permlane16_swap_b32_e32 v224, v225
	v_cndmask_b32_e64 v22, v225, v224, s[0:1]
	v_mul_f32_e32 v18, v7, v19
	v_cmp_lt_i32_e32 vcc, 0, v1
	s_waitcnt lgkmcnt(0)
	v_mul_f32_e32 v19, v15, v22
	v_sub_f32_e32 v15, v18, v19
	v_add_f32_e32 v18, v18, v19
	v_cndmask_b32_e64 v18, v7, v18, s[0:1]
	v_cndmask_b32_e32 v15, v15, v18, vcc
	v_mov_b32_e32 v224, v8
	v_mov_b32_e32 v225, v8
	v_cmp_eq_u32_e64 s[0:1], 1, v1
	s_nop 0
	v_permlane16_swap_b32_e32 v224, v225
	v_cndmask_b32_e64 v19, v225, v224, s[0:1]
	v_mul_f32_e32 v18, v8, v20
	v_cmp_lt_i32_e32 vcc, 0, v1
	s_waitcnt lgkmcnt(0)
	v_mul_f32_e32 v19, v16, v19
	v_sub_f32_e32 v16, v18, v19
	v_add_f32_e32 v18, v18, v19
	v_cndmask_b32_e64 v18, v8, v18, s[0:1]
	v_cndmask_b32_e32 v16, v16, v18, vcc
	v_mov_b32_e32 v224, v9
	v_mov_b32_e32 v225, v9
	v_cmp_eq_u32_e64 s[0:1], 1, v1
	s_nop 0
	v_permlane16_swap_b32_e32 v224, v225
	v_cndmask_b32_e64 v19, v225, v224, s[0:1]
	v_mul_f32_e32 v18, v9, v21
	v_cmp_lt_i32_e32 vcc, 0, v1
	s_waitcnt lgkmcnt(0)
	v_mul_f32_e32 v19, v17, v19
	v_sub_f32_e32 v17, v18, v19
	v_add_f32_e32 v18, v18, v19
	v_cndmask_b32_e64 v18, v9, v18, s[0:1]
	v_cndmask_b32_e32 v17, v17, v18, vcc

; DI void rope8(float (&v)[8], const float* __restrict__ rope, int s, int fq) {
;     const f32x4 c0 = *(const f32x4*)(rope + s * 16), c1 = *(const f32x4*)(rope + s * 16 + 4), s0 = *(const f32x4*)(rope + s * 16 + 8), s1 = *(const f32x4*)(rope + s * 16 + 12);
;     const float cs[8] = {c0[0], c0[1], c0[2], c0[3], c1[0], c1[1], c1[2], c1[3]}, sn[8] = {s0[0], s0[1], s0[2], s0[3], s1[0], s1[1], s1[2], s1[3]};
; #pragma unroll
;     for (int e = 0; e < 8; ++e) {
;         const float other = __shfl_xor(v[e], 16);
;         const float a = v[e] * cs[e], bq = other * sn[e];
;         v[e] = (fq == 0) ? (a - bq) : ((fq == 1) ? (a + bq) : v[e]);
;     }
;     DI void operator()(const pg8::f32x4 (&acc)[2][2][4][2], const pg8::Unit& u, int wr, int wc, int fr, int fq) const {
;     ...
;                         if (region < 2 && (wc & 1) == 0) rope8(v, rope, s, fq);
.LBB0_1145:
	s_andn2_b64 vcc, exec, s[6:7]
	s_cbranch_vccnz .LBB0_1195
	v_and_b32_e32 v11, 64, v183
	v_xor_b32_e32 v10, 16, v183
	v_add_u32_e32 v11, 64, v11
	v_cmp_lt_i32_e32 vcc, v10, v11
	v_lshlrev_b32_e32 v82, 6, v92
	s_nop 0
	v_cndmask_b32_e32 v10, v183, v10, vcc
	v_lshlrev_b32_e32 v93, 2, v10
	global_load_dwordx4 v[86:89], v82, s[68:69]
	global_load_dwordx4 v[10:13], v82, s[68:69] offset:32
	global_load_dwordx4 v[14:17], v82, s[68:69] offset:48
	s_nop 0
	global_load_dwordx4 v[82:85], v82, s[68:69] offset:16
	v_mov_b32_e32 v224, v2
	v_mov_b32_e32 v225, v2
	v_cmp_eq_u32_e64 s[0:1], 1, v1
	s_nop 0
	v_permlane16_swap_b32_e32 v224, v225
	v_cndmask_b32_e64 v94, v225, v224, s[0:1]
	v_cmp_lt_i32_e32 vcc, 0, v1
	s_waitcnt vmcnt(3)
	v_mul_f32_e32 v86, v2, v86
	s_waitcnt vmcnt(2) lgkmcnt(0)
	v_mul_f32_e32 v94, v10, v94
	v_sub_f32_e32 v10, v86, v94
	v_add_f32_e32 v86, v86, v94
	v_cndmask_b32_e64 v86, v2, v86, s[0:1]
	v_cndmask_b32_e32 v10, v10, v86, vcc
	v_mov_b32_e32 v224, v3
	v_mov_b32_e32 v225, v3
	v_cmp_eq_u32_e64 s[0:1], 1, v1
	s_nop 0
	v_permlane16_swap_b32_e32 v224, v225
	v_cndmask_b32_e64 v94, v225, v224, s[0:1]
	v_mul_f32_e32 v86, v3, v87
	v_cmp_lt_i32_e32 vcc, 0, v1
	s_waitcnt lgkmcnt(0)
	v_mul_f32_e32 v87, v11, v94
	v_sub_f32_e32 v11, v86, v87
	v_add_f32_e32 v86, v86, v87
	v_cndmask_b32_e64 v86, v3, v86, s[0:1]
	v_cndmask_b32_e32 v11, v11, v86, vcc
	v_mov_b32_e32 v224, v4
	v_mov_b32_e32 v225, v4
	v_cmp_eq_u32_e64 s[0:1], 1, v1
	s_nop 0
	v_permlane16_swap_b32_e32 v224, v225
	v_cndmask_b32_e64 v87, v225, v224, s[0:1]
	v_mul_f32_e32 v86, v4, v88
	v_cmp_lt_i32_e32 vcc, 0, v1
	s_waitcnt lgkmcnt(0)
	v_mul_f32_e32 v87, v12, v87
	v_sub_f32_e32 v12, v86, v87
	v_add_f32_e32 v86, v86, v87
	v_cndmask_b32_e64 v86, v4, v86, s[0:1]
	v_cndmask_b32_e32 v12, v12, v86, vcc
	v_mov_b32_e32 v224, v5
	v_mov_b32_e32 v225, v5
	v_cmp_eq_u32_e64 s[0:1], 1, v1
	s_nop 0
	v_permlane16_swap_b32_e32 v224, v225
	v_cndmask_b32_e64 v87, v225, v224, s[0:1]
	v_mul_f32_e32 v86, v5, v89
	v_cmp_lt_i32_e32 vcc, 0, v1
	s_waitcnt lgkmcnt(0)
	v_mul_f32_e32 v87, v13, v87
	v_sub_f32_e32 v13, v86, v87
	v_add_f32_e32 v86, v86, v87
	v_cndmask_b32_e64 v86, v5, v86, s[0:1]
	v_cndmask_b32_e32 v13, v13, v86, vcc
	v_mov_b32_e32 v224, v6
	v_mov_b32_e32 v225, v6
	v_cmp_eq_u32_e64 s[0:1], 1, v1
	s_nop 0
	v_permlane16_swap_b32_e32 v224, v225
	v_cndmask_b32_e64 v86, v225, v224, s[0:1]
	s_waitcnt vmcnt(0)
	v_mul_f32_e32 v82, v6, v82
	v_cmp_lt_i32_e32 vcc, 0, v1
	s_waitcnt lgkmcnt(0)
	v_mul_f32_e32 v86, v14, v86
	v_sub_f32_e32 v14, v82, v86
	v_add_f32_e32 v82, v82, v86
	v_cndmask_b32_e64 v82, v6, v82, s[0:1]
	v_cndmask_b32_e32 v14, v14, v82, vcc
	v_mov_b32_e32 v224, v7
	v_mov_b32_e32 v225, v7
	v_cmp_eq_u32_e64 s[0:1], 1, v1
	s_nop 0
	v_permlane16_swap_b32_e32 v224, v225
	v_cndmask_b32_e64 v86, v225, v224, s[0:1]
	v_mul_f32_e32 v82, v7, v83
	v_cmp_lt_i32_e32 vcc, 0, v1
	s_waitcnt lgkmcnt(0)
	v_mul_f32_e32 v83, v15, v86
	v_sub_f32_e32 v15, v82, v83
	v_add_f32_e32 v82, v82, v83
	v_cndmask_b32_e64 v82, v7, v82, s[0:1]
	v_cndmask_b32_e32 v15, v15, v82, vcc
	v_mov_b32_e32 v224, v8
	v_mov_b32_e32 v225, v8
	v_cmp_eq_u32_e64 s[0:1], 1, v1
	s_nop 0
	v_permlane16_swap_b32_e32 v224, v225
	v_cndmask_b32_e64 v83, v225, v224, s[0:1]
	v_mul_f32_e32 v82, v8, v84
	v_cmp_lt_i32_e32 vcc, 0, v1
	s_waitcnt lgkmcnt(0)
	v_mul_f32_e32 v83, v16, v83
	v_sub_f32_e32 v16, v82, v83
	v_add_f32_e32 v82, v82, v83
	v_cndmask_b32_e64 v82, v8, v82, s[0:1]
	v_cndmask_b32_e32 v16, v16, v82, vcc
	v_mov_b32_e32 v224, v9
	v_mov_b32_e32 v225, v9
	v_cmp_eq_u32_e64 s[0:1], 1, v1
	s_nop 0
	v_permlane16_swap_b32_e32 v224, v225
	v_cndmask_b32_e64 v83, v225, v224, s[0:1]
	v_mul_f32_e32 v82, v9, v85
	v_cmp_lt_i32_e32 vcc, 0, v1
	s_waitcnt lgkmcnt(0)
	v_mul_f32_e32 v83, v17, v83
	v_sub_f32_e32 v17, v82, v83
	v_add_f32_e32 v82, v82, v83
	v_cndmask_b32_e64 v82, v9, v82, s[0:1]
	v_cndmask_b32_e32 v17, v17, v82, vcc

; DI void rope8(float (&v)[8], const float* __restrict__ rope, int s, int fq) {
;     const f32x4 c0 = *(const f32x4*)(rope + s * 16), c1 = *(const f32x4*)(rope + s * 16 + 4), s0 = *(const f32x4*)(rope + s * 16 + 8), s1 = *(const f32x4*)(rope + s * 16 + 12);
;     const float cs[8] = {c0[0], c0[1], c0[2], c0[3], c1[0], c1[1], c1[2], c1[3]}, sn[8] = {s0[0], s0[1], s0[2], s0[3], s1[0], s1[1], s1[2], s1[3]};
; #pragma unroll
;     for (int e = 0; e < 8; ++e) {
;         const float other = __shfl_xor(v[e], 16);
;         const float a = v[e] * cs[e], bq = other * sn[e];
;         v[e] = (fq == 0) ? (a - bq) : ((fq == 1) ? (a + bq) : v[e]);
;     }
;     DI void operator()(const pg8::f32x4 (&acc)[2][2][4][2], const pg8::Unit& u, int wr, int wc, int fr, int fq) const {
;     ...
;                         if ((wc & 1) == 0) rope8(v, rope, s, fq);
.LBB0_1561:
	s_andn2_b64 vcc, exec, s[6:7]
	s_cbranch_vccnz .LBB0_1611
	v_and_b32_e32 v11, 64, v188
	v_xor_b32_e32 v10, 16, v188
	v_add_u32_e32 v11, 64, v11
	v_cmp_lt_i32_e32 vcc, v10, v11
	v_lshlrev_b32_e32 v11, 6, v158
	global_load_dwordx4 v[146:149], v11, s[68:69]
	global_load_dwordx4 v[142:145], v11, s[68:69] offset:32
	global_load_dwordx4 v[14:17], v11, s[68:69] offset:48
	global_load_dwordx4 v[138:141], v11, s[68:69] offset:16
	v_cndmask_b32_e32 v10, v188, v10, vcc
	v_lshlrev_b32_e32 v190, 2, v10
	v_mov_b32_e32 v224, v2
	v_mov_b32_e32 v225, v2
	v_cmp_eq_u32_e64 s[0:1], 1, v177
	s_nop 0
	v_permlane16_swap_b32_e32 v224, v225
	v_cndmask_b32_e64 v12, v225, v224, s[0:1]
	v_cmp_lt_i32_e32 vcc, 0, v177
	s_waitcnt vmcnt(3)
	v_mul_f32_e32 v11, v2, v146
	s_waitcnt vmcnt(2) lgkmcnt(0)
	v_mul_f32_e32 v12, v142, v12
	v_sub_f32_e32 v10, v11, v12
	v_add_f32_e32 v11, v11, v12
	v_cndmask_b32_e64 v11, v2, v11, s[0:1]
	v_cndmask_b32_e32 v10, v10, v11, vcc
	v_mov_b32_e32 v224, v3
	v_mov_b32_e32 v225, v3
	v_cmp_eq_u32_e64 s[0:1], 1, v177
	s_nop 0
	v_permlane16_swap_b32_e32 v224, v225
	v_cndmask_b32_e64 v11, v225, v224, s[0:1]
	v_mul_f32_e32 v12, v3, v147
	v_cmp_lt_i32_e32 vcc, 0, v177
	s_waitcnt lgkmcnt(0)
	v_mul_f32_e32 v13, v143, v11
	v_sub_f32_e32 v11, v12, v13
	v_add_f32_e32 v12, v12, v13
	v_cndmask_b32_e64 v12, v3, v12, s[0:1]
	v_cndmask_b32_e32 v11, v11, v12, vcc
	v_mov_b32_e32 v224, v4
	v_mov_b32_e32 v225, v4
	v_cmp_eq_u32_e64 s[0:1], 1, v177
	s_nop 0
	v_permlane16_swap_b32_e32 v224, v225
	v_cndmask_b32_e64 v12, v225, v224, s[0:1]
	v_mul_f32_e32 v13, v4, v148
	v_cmp_lt_i32_e32 vcc, 0, v177
	s_waitcnt lgkmcnt(0)
	v_mul_f32_e32 v142, v144, v12
	v_sub_f32_e32 v12, v13, v142
	v_add_f32_e32 v13, v13, v142
	v_cndmask_b32_e64 v13, v4, v13, s[0:1]
	v_cndmask_b32_e32 v12, v12, v13, vcc
	v_mov_b32_e32 v224, v5
	v_mov_b32_e32 v225, v5
	v_cmp_eq_u32_e64 s[0:1], 1, v177
	s_nop 0
	v_permlane16_swap_b32_e32 v224, v225
	v_cndmask_b32_e64 v13, v225, v224, s[0:1]
	v_mul_f32_e32 v142, v5, v149
	v_cmp_lt_i32_e32 vcc, 0, v177
	s_waitcnt lgkmcnt(0)
	v_mul_f32_e32 v143, v145, v13
	v_sub_f32_e32 v13, v142, v143
	v_add_f32_e32 v142, v142, v143
	v_cndmask_b32_e64 v142, v5, v142, s[0:1]
	v_cndmask_b32_e32 v13, v13, v142, vcc
	v_mov_b32_e32 v224, v6
	v_mov_b32_e32 v225, v6
	v_cmp_eq_u32_e64 s[0:1], 1, v177
	s_nop 0
	v_permlane16_swap_b32_e32 v224, v225
	v_cndmask_b32_e64 v142, v225, v224, s[0:1]
	s_waitcnt vmcnt(0)
	v_mul_f32_e32 v138, v6, v138
	v_cmp_lt_i32_e32 vcc, 0, v177
	s_waitcnt lgkmcnt(0)
	v_mul_f32_e32 v142, v14, v142
	v_sub_f32_e32 v14, v138, v142
	v_add_f32_e32 v138, v138, v142
	v_cndmask_b32_e64 v138, v6, v138, s[0:1]
	v_cndmask_b32_e32 v14, v14, v138, vcc
	v_mov_b32_e32 v224, v7
	v_mov_b32_e32 v225, v7
	v_cmp_eq_u32_e64 s[0:1], 1, v177
	s_nop 0
	v_permlane16_swap_b32_e32 v224, v225
	v_cndmask_b32_e64 v142, v225, v224, s[0:1]
	v_mul_f32_e32 v138, v7, v139
	v_cmp_lt_i32_e32 vcc, 0, v177
	s_waitcnt lgkmcnt(0)
	v_mul_f32_e32 v139, v15, v142
	v_sub_f32_e32 v15, v138, v139
	v_add_f32_e32 v138, v138, v139
	v_cndmask_b32_e64 v138, v7, v138, s[0:1]
	v_cndmask_b32_e32 v15, v15, v138, vcc
	v_mov_b32_e32 v224, v8
	v_mov_b32_e32 v225, v8
	v_cmp_eq_u32_e64 s[0:1], 1, v177
	s_nop 0
	v_permlane16_swap_b32_e32 v224, v225
	v_cndmask_b32_e64 v139, v225, v224, s[0:1]
	v_mul_f32_e32 v138, v8, v140
	v_cmp_lt_i32_e32 vcc, 0, v177
	s_waitcnt lgkmcnt(0)
	v_mul_f32_e32 v139, v16, v139
	v_sub_f32_e32 v16, v138, v139
	v_add_f32_e32 v138, v138, v139
	v_cndmask_b32_e64 v138, v8, v138, s[0:1]
	v_cndmask_b32_e32 v16, v16, v138, vcc
	v_mov_b32_e32 v224, v9
	v_mov_b32_e32 v225, v9
	v_cmp_eq_u32_e64 s[0:1], 1, v177
	s_nop 0
	v_permlane16_swap_b32_e32 v224, v225
	v_cndmask_b32_e64 v139, v225, v224, s[0:1]
	v_mul_f32_e32 v138, v9, v141
	v_cmp_lt_i32_e32 vcc, 0, v177
	s_waitcnt lgkmcnt(0)
	v_mul_f32_e32 v139, v17, v139
	v_sub_f32_e32 v17, v138, v139
	v_add_f32_e32 v138, v138, v139
	v_cndmask_b32_e64 v138, v9, v138, s[0:1]
	v_cndmask_b32_e32 v17, v17, v138, vcc

; DI void rope8(float (&v)[8], const float* __restrict__ rope, int s, int fq) {
;     const f32x4 c0 = *(const f32x4*)(rope + s * 16), c1 = *(const f32x4*)(rope + s * 16 + 4), s0 = *(const f32x4*)(rope + s * 16 + 8), s1 = *(const f32x4*)(rope + s * 16 + 12);
;     const float cs[8] = {c0[0], c0[1], c0[2], c0[3], c1[0], c1[1], c1[2], c1[3]}, sn[8] = {s0[0], s0[1], s0[2], s0[3], s1[0], s1[1], s1[2], s1[3]};
; #pragma unroll
;     for (int e = 0; e < 8; ++e) {
;         const float other = __shfl_xor(v[e], 16);
;         const float a = v[e] * cs[e], bq = other * sn[e];
;         v[e] = (fq == 0) ? (a - bq) : ((fq == 1) ? (a + bq) : v[e]);
;     }
;     DI void operator()(const pg8::f32x4 (&acc)[2][2][4][2], const pg8::Unit& u, int wr, int wc, int fr, int fq) const {
;     ...
;                         if ((wc & 1) == 0) rope8(v, rope, s, fq);
.LBB0_1626:
	s_andn2_b64 vcc, exec, s[8:9]
	s_cbranch_vccnz .LBB0_1676
	v_and_b32_e32 v11, 64, v188
	v_xor_b32_e32 v10, 16, v188
	v_add_u32_e32 v11, 64, v11
	v_cmp_lt_i32_e32 vcc, v10, v11
	v_lshlrev_b32_e32 v11, 6, v144
	global_load_dwordx4 v[138:141], v11, s[68:69]
	global_load_dwordx4 v[134:137], v11, s[68:69] offset:32
	global_load_dwordx4 v[14:17], v11, s[68:69] offset:48
	global_load_dwordx4 v[130:133], v11, s[68:69] offset:16
	v_cndmask_b32_e32 v10, v188, v10, vcc
	v_lshlrev_b32_e32 v145, 2, v10
	v_mov_b32_e32 v224, v2
	v_mov_b32_e32 v225, v2
	v_cmp_eq_u32_e64 s[0:1], 1, v177
	s_nop 0
	v_permlane16_swap_b32_e32 v224, v225
	v_cndmask_b32_e64 v12, v225, v224, s[0:1]
	v_cmp_lt_i32_e32 vcc, 0, v177
	s_waitcnt vmcnt(3)
	v_mul_f32_e32 v11, v2, v138
	s_waitcnt vmcnt(2) lgkmcnt(0)
	v_mul_f32_e32 v12, v134, v12
	v_sub_f32_e32 v10, v11, v12
	v_add_f32_e32 v11, v11, v12
	v_cndmask_b32_e64 v11, v2, v11, s[0:1]
	v_cndmask_b32_e32 v10, v10, v11, vcc
	v_mov_b32_e32 v224, v3
	v_mov_b32_e32 v225, v3
	v_cmp_eq_u32_e64 s[0:1], 1, v177
	s_nop 0
	v_permlane16_swap_b32_e32 v224, v225
	v_cndmask_b32_e64 v11, v225, v224, s[0:1]
	v_mul_f32_e32 v12, v3, v139
	v_cmp_lt_i32_e32 vcc, 0, v177
	s_waitcnt lgkmcnt(0)
	v_mul_f32_e32 v13, v135, v11
	v_sub_f32_e32 v11, v12, v13
	v_add_f32_e32 v12, v12, v13
	v_cndmask_b32_e64 v12, v3, v12, s[0:1]
	v_cndmask_b32_e32 v11, v11, v12, vcc
	v_mov_b32_e32 v224, v4
	v_mov_b32_e32 v225, v4
	v_cmp_eq_u32_e64 s[0:1], 1, v177
	s_nop 0
	v_permlane16_swap_b32_e32 v224, v225
	v_cndmask_b32_e64 v12, v225, v224, s[0:1]
	v_mul_f32_e32 v13, v4, v140
	v_cmp_lt_i32_e32 vcc, 0, v177
	s_waitcnt lgkmcnt(0)
	v_mul_f32_e32 v134, v136, v12
	v_sub_f32_e32 v12, v13, v134
	v_add_f32_e32 v13, v13, v134
	v_cndmask_b32_e64 v13, v4, v13, s[0:1]
	v_cndmask_b32_e32 v12, v12, v13, vcc
	v_mov_b32_e32 v224, v5
	v_mov_b32_e32 v225, v5
	v_cmp_eq_u32_e64 s[0:1], 1, v177
	s_nop 0
	v_permlane16_swap_b32_e32 v224, v225
	v_cndmask_b32_e64 v13, v225, v224, s[0:1]
	v_mul_f32_e32 v134, v5, v141
	v_cmp_lt_i32_e32 vcc, 0, v177
	s_waitcnt lgkmcnt(0)
	v_mul_f32_e32 v135, v137, v13
	v_sub_f32_e32 v13, v134, v135
	v_add_f32_e32 v134, v134, v135
	v_cndmask_b32_e64 v134, v5, v134, s[0:1]
	v_cndmask_b32_e32 v13, v13, v134, vcc
	v_mov_b32_e32 v224, v6
	v_mov_b32_e32 v225, v6
	v_cmp_eq_u32_e64 s[0:1], 1, v177
	s_nop 0
	v_permlane16_swap_b32_e32 v224, v225
	v_cndmask_b32_e64 v134, v225, v224, s[0:1]
	s_waitcnt vmcnt(0)
	v_mul_f32_e32 v130, v6, v130
	v_cmp_lt_i32_e32 vcc, 0, v177
	s_waitcnt lgkmcnt(0)
	v_mul_f32_e32 v134, v14, v134
	v_sub_f32_e32 v14, v130, v134
	v_add_f32_e32 v130, v130, v134
	v_cndmask_b32_e64 v130, v6, v130, s[0:1]
	v_cndmask_b32_e32 v14, v14, v130, vcc
	v_mov_b32_e32 v224, v7
	v_mov_b32_e32 v225, v7
	v_cmp_eq_u32_e64 s[0:1], 1, v177
	s_nop 0
	v_permlane16_swap_b32_e32 v224, v225
	v_cndmask_b32_e64 v134, v225, v224, s[0:1]
	v_mul_f32_e32 v130, v7, v131
	v_cmp_lt_i32_e32 vcc, 0, v177
	s_waitcnt lgkmcnt(0)
	v_mul_f32_e32 v131, v15, v134
	v_sub_f32_e32 v15, v130, v131
	v_add_f32_e32 v130, v130, v131
	v_cndmask_b32_e64 v130, v7, v130, s[0:1]
	v_cndmask_b32_e32 v15, v15, v130, vcc
	v_mov_b32_e32 v224, v8
	v_mov_b32_e32 v225, v8
	v_cmp_eq_u32_e64 s[0:1], 1, v177
	s_nop 0
	v_permlane16_swap_b32_e32 v224, v225
	v_cndmask_b32_e64 v131, v225, v224, s[0:1]
	v_mul_f32_e32 v130, v8, v132
	v_cmp_lt_i32_e32 vcc, 0, v177
	s_waitcnt lgkmcnt(0)
	v_mul_f32_e32 v131, v16, v131
	v_sub_f32_e32 v16, v130, v131
	v_add_f32_e32 v130, v130, v131
	v_cndmask_b32_e64 v130, v8, v130, s[0:1]
	v_cndmask_b32_e32 v16, v16, v130, vcc
	v_mov_b32_e32 v224, v9
	v_mov_b32_e32 v225, v9
	v_cmp_eq_u32_e64 s[0:1], 1, v177
	s_nop 0
	v_permlane16_swap_b32_e32 v224, v225
	v_cndmask_b32_e64 v131, v225, v224, s[0:1]
	v_mul_f32_e32 v130, v9, v133
	v_cmp_lt_i32_e32 vcc, 0, v177
	s_waitcnt lgkmcnt(0)
	v_mul_f32_e32 v131, v17, v131
	v_sub_f32_e32 v17, v130, v131
	v_add_f32_e32 v130, v130, v131
	v_cndmask_b32_e64 v130, v9, v130, s[0:1]
	v_cndmask_b32_e32 v17, v17, v130, vcc

; DI void rope8(float (&v)[8], const float* __restrict__ rope, int s, int fq) {
;     const f32x4 c0 = *(const f32x4*)(rope + s * 16), c1 = *(const f32x4*)(rope + s * 16 + 4), s0 = *(const f32x4*)(rope + s * 16 + 8), s1 = *(const f32x4*)(rope + s * 16 + 12);
;     const float cs[8] = {c0[0], c0[1], c0[2], c0[3], c1[0], c1[1], c1[2], c1[3]}, sn[8] = {s0[0], s0[1], s0[2], s0[3], s1[0], s1[1], s1[2], s1[3]};
; #pragma unroll
;     for (int e = 0; e < 8; ++e) {
;         const float other = __shfl_xor(v[e], 16);
;         const float a = v[e] * cs[e], bq = other * sn[e];
;         v[e] = (fq == 0) ? (a - bq) : ((fq == 1) ? (a + bq) : v[e]);
;     }
;     DI void operator()(const pg8::f32x4 (&acc)[2][2][4][2], const pg8::Unit& u, int wr, int wc, int fr, int fq) const {
;     ...
;                         if ((wc & 1) == 0) rope8(v, rope, s, fq);
.LBB0_1691:
	s_andn2_b64 vcc, exec, s[8:9]
	s_cbranch_vccnz .LBB0_1741
	v_and_b32_e32 v11, 64, v188
	v_xor_b32_e32 v10, 16, v188
	v_add_u32_e32 v11, 64, v11
	v_cmp_lt_i32_e32 vcc, v10, v11
	v_lshlrev_b32_e32 v11, 6, v136
	global_load_dwordx4 v[130:133], v11, s[68:69]
	global_load_dwordx4 v[126:129], v11, s[68:69] offset:32
	global_load_dwordx4 v[14:17], v11, s[68:69] offset:48
	global_load_dwordx4 v[122:125], v11, s[68:69] offset:16
	v_cndmask_b32_e32 v10, v188, v10, vcc
	v_lshlrev_b32_e32 v137, 2, v10
	v_mov_b32_e32 v224, v2
	v_mov_b32_e32 v225, v2
	v_cmp_eq_u32_e64 s[0:1], 1, v177
	s_nop 0
	v_permlane16_swap_b32_e32 v224, v225
	v_cndmask_b32_e64 v12, v225, v224, s[0:1]
	v_cmp_lt_i32_e32 vcc, 0, v177
	s_waitcnt vmcnt(3)
	v_mul_f32_e32 v11, v2, v130
	s_waitcnt vmcnt(2) lgkmcnt(0)
	v_mul_f32_e32 v12, v126, v12
	v_sub_f32_e32 v10, v11, v12
	v_add_f32_e32 v11, v11, v12
	v_cndmask_b32_e64 v11, v2, v11, s[0:1]
	v_cndmask_b32_e32 v10, v10, v11, vcc
	v_mov_b32_e32 v224, v3
	v_mov_b32_e32 v225, v3
	v_cmp_eq_u32_e64 s[0:1], 1, v177
	s_nop 0
	v_permlane16_swap_b32_e32 v224, v225
	v_cndmask_b32_e64 v11, v225, v224, s[0:1]
	v_mul_f32_e32 v12, v3, v131
	v_cmp_lt_i32_e32 vcc, 0, v177
	s_waitcnt lgkmcnt(0)
	v_mul_f32_e32 v13, v127, v11
	v_sub_f32_e32 v11, v12, v13
	v_add_f32_e32 v12, v12, v13
	v_cndmask_b32_e64 v12, v3, v12, s[0:1]
	v_cndmask_b32_e32 v11, v11, v12, vcc
	v_mov_b32_e32 v224, v4
	v_mov_b32_e32 v225, v4
	v_cmp_eq_u32_e64 s[0:1], 1, v177
	s_nop 0
	v_permlane16_swap_b32_e32 v224, v225
	v_cndmask_b32_e64 v12, v225, v224, s[0:1]
	v_mul_f32_e32 v13, v4, v132
	v_cmp_lt_i32_e32 vcc, 0, v177
	s_waitcnt lgkmcnt(0)
	v_mul_f32_e32 v126, v128, v12
	v_sub_f32_e32 v12, v13, v126
	v_add_f32_e32 v13, v13, v126
	v_cndmask_b32_e64 v13, v4, v13, s[0:1]
	v_cndmask_b32_e32 v12, v12, v13, vcc
	v_mov_b32_e32 v224, v5
	v_mov_b32_e32 v225, v5
	v_cmp_eq_u32_e64 s[0:1], 1, v177
	s_nop 0
	v_permlane16_swap_b32_e32 v224, v225
	v_cndmask_b32_e64 v13, v225, v224, s[0:1]
	v_mul_f32_e32 v126, v5, v133
	v_cmp_lt_i32_e32 vcc, 0, v177
	s_waitcnt lgkmcnt(0)
	v_mul_f32_e32 v127, v129, v13
	v_sub_f32_e32 v13, v126, v127
	v_add_f32_e32 v126, v126, v127
	v_cndmask_b32_e64 v126, v5, v126, s[0:1]
	v_cndmask_b32_e32 v13, v13, v126, vcc
	v_mov_b32_e32 v224, v6
	v_mov_b32_e32 v225, v6
	v_cmp_eq_u32_e64 s[0:1], 1, v177
	s_nop 0
	v_permlane16_swap_b32_e32 v224, v225
	v_cndmask_b32_e64 v126, v225, v224, s[0:1]
	s_waitcnt vmcnt(0)
	v_mul_f32_e32 v122, v6, v122
	v_cmp_lt_i32_e32 vcc, 0, v177
	s_waitcnt lgkmcnt(0)
	v_mul_f32_e32 v126, v14, v126
	v_sub_f32_e32 v14, v122, v126
	v_add_f32_e32 v122, v122, v126
	v_cndmask_b32_e64 v122, v6, v122, s[0:1]
	v_cndmask_b32_e32 v14, v14, v122, vcc
	v_mov_b32_e32 v224, v7
	v_mov_b32_e32 v225, v7
	v_cmp_eq_u32_e64 s[0:1], 1, v177
	s_nop 0
	v_permlane16_swap_b32_e32 v224, v225
	v_cndmask_b32_e64 v126, v225, v224, s[0:1]
	v_mul_f32_e32 v122, v7, v123
	v_cmp_lt_i32_e32 vcc, 0, v177
	s_waitcnt lgkmcnt(0)
	v_mul_f32_e32 v123, v15, v126
	v_sub_f32_e32 v15, v122, v123
	v_add_f32_e32 v122, v122, v123
	v_cndmask_b32_e64 v122, v7, v122, s[0:1]
	v_cndmask_b32_e32 v15, v15, v122, vcc
	v_mov_b32_e32 v224, v8
	v_mov_b32_e32 v225, v8
	v_cmp_eq_u32_e64 s[0:1], 1, v177
	s_nop 0
	v_permlane16_swap_b32_e32 v224, v225
	v_cndmask_b32_e64 v123, v225, v224, s[0:1]
	v_mul_f32_e32 v122, v8, v124
	v_cmp_lt_i32_e32 vcc, 0, v177
	s_waitcnt lgkmcnt(0)
	v_mul_f32_e32 v123, v16, v123
	v_sub_f32_e32 v16, v122, v123
	v_add_f32_e32 v122, v122, v123
	v_cndmask_b32_e64 v122, v8, v122, s[0:1]
	v_cndmask_b32_e32 v16, v16, v122, vcc
	v_mov_b32_e32 v224, v9
	v_mov_b32_e32 v225, v9
	v_cmp_eq_u32_e64 s[0:1], 1, v177
	s_nop 0
	v_permlane16_swap_b32_e32 v224, v225
	v_cndmask_b32_e64 v123, v225, v224, s[0:1]
	v_mul_f32_e32 v122, v9, v125
	v_cmp_lt_i32_e32 vcc, 0, v177
	s_waitcnt lgkmcnt(0)
	v_mul_f32_e32 v123, v17, v123
	v_sub_f32_e32 v17, v122, v123
	v_add_f32_e32 v122, v122, v123
	v_cndmask_b32_e64 v122, v9, v122, s[0:1]
	v_cndmask_b32_e32 v17, v17, v122, vcc

; DI void rope8(float (&v)[8], const float* __restrict__ rope, int s, int fq) {
;     const f32x4 c0 = *(const f32x4*)(rope + s * 16), c1 = *(const f32x4*)(rope + s * 16 + 4), s0 = *(const f32x4*)(rope + s * 16 + 8), s1 = *(const f32x4*)(rope + s * 16 + 12);
;     const float cs[8] = {c0[0], c0[1], c0[2], c0[3], c1[0], c1[1], c1[2], c1[3]}, sn[8] = {s0[0], s0[1], s0[2], s0[3], s1[0], s1[1], s1[2], s1[3]};
; #pragma unroll
;     for (int e = 0; e < 8; ++e) {
;         const float other = __shfl_xor(v[e], 16);
;         const float a = v[e] * cs[e], bq = other * sn[e];
;         v[e] = (fq == 0) ? (a - bq) : ((fq == 1) ? (a + bq) : v[e]);
;     }
;     DI void operator()(const pg8::f32x4 (&acc)[2][2][4][2], const pg8::Unit& u, int wr, int wc, int fr, int fq) const {
;     ...
;                         if ((wc & 1) == 0) rope8(v, rope, s, fq);
.LBB0_1756:
	s_andn2_b64 vcc, exec, s[8:9]
	s_cbranch_vccnz .LBB0_1806
	v_and_b32_e32 v11, 64, v188
	v_xor_b32_e32 v10, 16, v188
	v_add_u32_e32 v11, 64, v11
	v_cmp_lt_i32_e32 vcc, v10, v11
	v_lshlrev_b32_e32 v11, 6, v128
	global_load_dwordx4 v[122:125], v11, s[68:69]
	global_load_dwordx4 v[118:121], v11, s[68:69] offset:32
	global_load_dwordx4 v[14:17], v11, s[68:69] offset:48
	global_load_dwordx4 v[114:117], v11, s[68:69] offset:16
	v_cndmask_b32_e32 v10, v188, v10, vcc
	v_lshlrev_b32_e32 v129, 2, v10
	v_mov_b32_e32 v224, v2
	v_mov_b32_e32 v225, v2
	v_cmp_eq_u32_e64 s[0:1], 1, v177
	s_nop 0
	v_permlane16_swap_b32_e32 v224, v225
	v_cndmask_b32_e64 v12, v225, v224, s[0:1]
	v_cmp_lt_i32_e32 vcc, 0, v177
	s_waitcnt vmcnt(3)
	v_mul_f32_e32 v11, v2, v122
	s_waitcnt vmcnt(2) lgkmcnt(0)
	v_mul_f32_e32 v12, v118, v12
	v_sub_f32_e32 v10, v11, v12
	v_add_f32_e32 v11, v11, v12
	v_cndmask_b32_e64 v11, v2, v11, s[0:1]
	v_cndmask_b32_e32 v10, v10, v11, vcc
	v_mov_b32_e32 v224, v3
	v_mov_b32_e32 v225, v3
	v_cmp_eq_u32_e64 s[0:1], 1, v177
	s_nop 0
	v_permlane16_swap_b32_e32 v224, v225
	v_cndmask_b32_e64 v11, v225, v224, s[0:1]
	v_mul_f32_e32 v12, v3, v123
	v_cmp_lt_i32_e32 vcc, 0, v177
	s_waitcnt lgkmcnt(0)
	v_mul_f32_e32 v13, v119, v11
	v_sub_f32_e32 v11, v12, v13
	v_add_f32_e32 v12, v12, v13
	v_cndmask_b32_e64 v12, v3, v12, s[0:1]
	v_cndmask_b32_e32 v11, v11, v12, vcc
	v_mov_b32_e32 v224, v4
	v_mov_b32_e32 v225, v4
	v_cmp_eq_u32_e64 s[0:1], 1, v177
	s_nop 0
	v_permlane16_swap_b32_e32 v224, v225
	v_cndmask_b32_e64 v12, v225, v224, s[0:1]
	v_mul_f32_e32 v13, v4, v124
	v_cmp_lt_i32_e32 vcc, 0, v177
	s_waitcnt lgkmcnt(0)
	v_mul_f32_e32 v118, v120, v12
	v_sub_f32_e32 v12, v13, v118
	v_add_f32_e32 v13, v13, v118
	v_cndmask_b32_e64 v13, v4, v13, s[0:1]
	v_cndmask_b32_e32 v12, v12, v13, vcc
	v_mov_b32_e32 v224, v5
	v_mov_b32_e32 v225, v5
	v_cmp_eq_u32_e64 s[0:1], 1, v177
	s_nop 0
	v_permlane16_swap_b32_e32 v224, v225
	v_cndmask_b32_e64 v13, v225, v224, s[0:1]
	v_mul_f32_e32 v118, v5, v125
	v_cmp_lt_i32_e32 vcc, 0, v177
	s_waitcnt lgkmcnt(0)
	v_mul_f32_e32 v119, v121, v13
	v_sub_f32_e32 v13, v118, v119
	v_add_f32_e32 v118, v118, v119
	v_cndmask_b32_e64 v118, v5, v118, s[0:1]
	v_cndmask_b32_e32 v13, v13, v118, vcc
	v_mov_b32_e32 v224, v6
	v_mov_b32_e32 v225, v6
	v_cmp_eq_u32_e64 s[0:1], 1, v177
	s_nop 0
	v_permlane16_swap_b32_e32 v224, v225
	v_cndmask_b32_e64 v118, v225, v224, s[0:1]
	s_waitcnt vmcnt(0)
	v_mul_f32_e32 v114, v6, v114
	v_cmp_lt_i32_e32 vcc, 0, v177
	s_waitcnt lgkmcnt(0)
	v_mul_f32_e32 v118, v14, v118
	v_sub_f32_e32 v14, v114, v118
	v_add_f32_e32 v114, v114, v118
	v_cndmask_b32_e64 v114, v6, v114, s[0:1]
	v_cndmask_b32_e32 v14, v14, v114, vcc
	v_mov_b32_e32 v224, v7
	v_mov_b32_e32 v225, v7
	v_cmp_eq_u32_e64 s[0:1], 1, v177
	s_nop 0
	v_permlane16_swap_b32_e32 v224, v225
	v_cndmask_b32_e64 v118, v225, v224, s[0:1]
	v_mul_f32_e32 v114, v7, v115
	v_cmp_lt_i32_e32 vcc, 0, v177
	s_waitcnt lgkmcnt(0)
	v_mul_f32_e32 v115, v15, v118
	v_sub_f32_e32 v15, v114, v115
	v_add_f32_e32 v114, v114, v115
	v_cndmask_b32_e64 v114, v7, v114, s[0:1]
	v_cndmask_b32_e32 v15, v15, v114, vcc
	v_mov_b32_e32 v224, v8
	v_mov_b32_e32 v225, v8
	v_cmp_eq_u32_e64 s[0:1], 1, v177
	s_nop 0
	v_permlane16_swap_b32_e32 v224, v225
	v_cndmask_b32_e64 v115, v225, v224, s[0:1]
	v_mul_f32_e32 v114, v8, v116
	v_cmp_lt_i32_e32 vcc, 0, v177
	s_waitcnt lgkmcnt(0)
	v_mul_f32_e32 v115, v16, v115
	v_sub_f32_e32 v16, v114, v115
	v_add_f32_e32 v114, v114, v115
	v_cndmask_b32_e64 v114, v8, v114, s[0:1]
	v_cndmask_b32_e32 v16, v16, v114, vcc
	v_mov_b32_e32 v224, v9
	v_mov_b32_e32 v225, v9
	v_cmp_eq_u32_e64 s[0:1], 1, v177
	s_nop 0
	v_permlane16_swap_b32_e32 v224, v225
	v_cndmask_b32_e64 v115, v225, v224, s[0:1]
	v_mul_f32_e32 v114, v9, v117
	v_cmp_lt_i32_e32 vcc, 0, v177
	s_waitcnt lgkmcnt(0)
	v_mul_f32_e32 v115, v17, v115
	v_sub_f32_e32 v17, v114, v115
	v_add_f32_e32 v114, v114, v115
	v_cndmask_b32_e64 v114, v9, v114, s[0:1]
	v_cndmask_b32_e32 v17, v17, v114, vcc

; DI void rope8(float (&v)[8], const float* __restrict__ rope, int s, int fq) {
;     const f32x4 c0 = *(const f32x4*)(rope + s * 16), c1 = *(const f32x4*)(rope + s * 16 + 4), s0 = *(const f32x4*)(rope + s * 16 + 8), s1 = *(const f32x4*)(rope + s * 16 + 12);
;     const float cs[8] = {c0[0], c0[1], c0[2], c0[3], c1[0], c1[1], c1[2], c1[3]}, sn[8] = {s0[0], s0[1], s0[2], s0[3], s1[0], s1[1], s1[2], s1[3]};
; #pragma unroll
;     for (int e = 0; e < 8; ++e) {
;         const float other = __shfl_xor(v[e], 16);
;         const float a = v[e] * cs[e], bq = other * sn[e];
;         v[e] = (fq == 0) ? (a - bq) : ((fq == 1) ? (a + bq) : v[e]);
;     }
;     DI void operator()(const pg8::f32x4 (&acc)[2][2][4][2], const pg8::Unit& u, int wr, int wc, int fr, int fq) const {
;     ...
;                         if ((wc & 1) == 0) rope8(v, rope, s, fq);
.LBB0_1821:
	s_andn2_b64 vcc, exec, s[8:9]
	s_cbranch_vccnz .LBB0_1871
	v_and_b32_e32 v11, 64, v188
	v_xor_b32_e32 v10, 16, v188
	v_add_u32_e32 v11, 64, v11
	v_cmp_lt_i32_e32 vcc, v10, v11
	v_lshlrev_b32_e32 v11, 6, v122
	global_load_dwordx4 v[114:117], v11, s[68:69]
	global_load_dwordx4 v[110:113], v11, s[68:69] offset:32
	global_load_dwordx4 v[14:17], v11, s[68:69] offset:48
	global_load_dwordx4 v[106:109], v11, s[68:69] offset:16
	v_cndmask_b32_e32 v10, v188, v10, vcc
	v_lshlrev_b32_e32 v123, 2, v10
	v_mov_b32_e32 v224, v2
	v_mov_b32_e32 v225, v2
	v_cmp_eq_u32_e64 s[0:1], 1, v177
	s_nop 0
	v_permlane16_swap_b32_e32 v224, v225
	v_cndmask_b32_e64 v12, v225, v224, s[0:1]
	v_cmp_lt_i32_e32 vcc, 0, v177
	s_waitcnt vmcnt(3)
	v_mul_f32_e32 v11, v2, v114
	s_waitcnt vmcnt(2) lgkmcnt(0)
	v_mul_f32_e32 v12, v110, v12
	v_sub_f32_e32 v10, v11, v12
	v_add_f32_e32 v11, v11, v12
	v_cndmask_b32_e64 v11, v2, v11, s[0:1]
	v_cndmask_b32_e32 v10, v10, v11, vcc
	v_mov_b32_e32 v224, v3
	v_mov_b32_e32 v225, v3
	v_cmp_eq_u32_e64 s[0:1], 1, v177
	s_nop 0
	v_permlane16_swap_b32_e32 v224, v225
	v_cndmask_b32_e64 v11, v225, v224, s[0:1]
	v_mul_f32_e32 v12, v3, v115
	v_cmp_lt_i32_e32 vcc, 0, v177
	s_waitcnt lgkmcnt(0)
	v_mul_f32_e32 v13, v111, v11
	v_sub_f32_e32 v11, v12, v13
	v_add_f32_e32 v12, v12, v13
	v_cndmask_b32_e64 v12, v3, v12, s[0:1]
	v_cndmask_b32_e32 v11, v11, v12, vcc
	v_mov_b32_e32 v224, v4
	v_mov_b32_e32 v225, v4
	v_cmp_eq_u32_e64 s[0:1], 1, v177
	s_nop 0
	v_permlane16_swap_b32_e32 v224, v225
	v_cndmask_b32_e64 v12, v225, v224, s[0:1]
	v_mul_f32_e32 v13, v4, v116
	v_cmp_lt_i32_e32 vcc, 0, v177
	s_waitcnt lgkmcnt(0)
	v_mul_f32_e32 v110, v112, v12
	v_sub_f32_e32 v12, v13, v110
	v_add_f32_e32 v13, v13, v110
	v_cndmask_b32_e64 v13, v4, v13, s[0:1]
	v_cndmask_b32_e32 v12, v12, v13, vcc
	v_mov_b32_e32 v224, v5
	v_mov_b32_e32 v225, v5
	v_cmp_eq_u32_e64 s[0:1], 1, v177
	s_nop 0
	v_permlane16_swap_b32_e32 v224, v225
	v_cndmask_b32_e64 v13, v225, v224, s[0:1]
	v_mul_f32_e32 v110, v5, v117
	v_cmp_lt_i32_e32 vcc, 0, v177
	s_waitcnt lgkmcnt(0)
	v_mul_f32_e32 v111, v113, v13
	v_sub_f32_e32 v13, v110, v111
	v_add_f32_e32 v110, v110, v111
	v_cndmask_b32_e64 v110, v5, v110, s[0:1]
	v_cndmask_b32_e32 v13, v13, v110, vcc
	v_mov_b32_e32 v224, v6
	v_mov_b32_e32 v225, v6
	v_cmp_eq_u32_e64 s[0:1], 1, v177
	s_nop 0
	v_permlane16_swap_b32_e32 v224, v225
	v_cndmask_b32_e64 v110, v225, v224, s[0:1]
	s_waitcnt vmcnt(0)
	v_mul_f32_e32 v106, v6, v106
	v_cmp_lt_i32_e32 vcc, 0, v177
	s_waitcnt lgkmcnt(0)
	v_mul_f32_e32 v110, v14, v110
	v_sub_f32_e32 v14, v106, v110
	v_add_f32_e32 v106, v106, v110
	v_cndmask_b32_e64 v106, v6, v106, s[0:1]
	v_cndmask_b32_e32 v14, v14, v106, vcc
	v_mov_b32_e32 v224, v7
	v_mov_b32_e32 v225, v7
	v_cmp_eq_u32_e64 s[0:1], 1, v177
	s_nop 0
	v_permlane16_swap_b32_e32 v224, v225
	v_cndmask_b32_e64 v110, v225, v224, s[0:1]
	v_mul_f32_e32 v106, v7, v107
	v_cmp_lt_i32_e32 vcc, 0, v177
	s_waitcnt lgkmcnt(0)
	v_mul_f32_e32 v107, v15, v110
	v_sub_f32_e32 v15, v106, v107
	v_add_f32_e32 v106, v106, v107
	v_cndmask_b32_e64 v106, v7, v106, s[0:1]
	v_cndmask_b32_e32 v15, v15, v106, vcc
	v_mov_b32_e32 v224, v8
	v_mov_b32_e32 v225, v8
	v_cmp_eq_u32_e64 s[0:1], 1, v177
	s_nop 0
	v_permlane16_swap_b32_e32 v224, v225
	v_cndmask_b32_e64 v107, v225, v224, s[0:1]
	v_mul_f32_e32 v106, v8, v108
	v_cmp_lt_i32_e32 vcc, 0, v177
	s_waitcnt lgkmcnt(0)
	v_mul_f32_e32 v107, v16, v107
	v_sub_f32_e32 v16, v106, v107
	v_add_f32_e32 v106, v106, v107
	v_cndmask_b32_e64 v106, v8, v106, s[0:1]
	v_cndmask_b32_e32 v16, v16, v106, vcc
	v_mov_b32_e32 v224, v9
	v_mov_b32_e32 v225, v9
	v_cmp_eq_u32_e64 s[0:1], 1, v177
	s_nop 0
	v_permlane16_swap_b32_e32 v224, v225
	v_cndmask_b32_e64 v107, v225, v224, s[0:1]
	v_mul_f32_e32 v106, v9, v109
	v_cmp_lt_i32_e32 vcc, 0, v177
	s_waitcnt lgkmcnt(0)
	v_mul_f32_e32 v107, v17, v107
	v_sub_f32_e32 v17, v106, v107
	v_add_f32_e32 v106, v106, v107
	v_cndmask_b32_e64 v106, v9, v106, s[0:1]
	v_cndmask_b32_e32 v17, v17, v106, vcc

; DI void rope8(float (&v)[8], const float* __restrict__ rope, int s, int fq) {
;     const f32x4 c0 = *(const f32x4*)(rope + s * 16), c1 = *(const f32x4*)(rope + s * 16 + 4), s0 = *(const f32x4*)(rope + s * 16 + 8), s1 = *(const f32x4*)(rope + s * 16 + 12);
;     const float cs[8] = {c0[0], c0[1], c0[2], c0[3], c1[0], c1[1], c1[2], c1[3]}, sn[8] = {s0[0], s0[1], s0[2], s0[3], s1[0], s1[1], s1[2], s1[3]};
; #pragma unroll
;     for (int e = 0; e < 8; ++e) {
;         const float other = __shfl_xor(v[e], 16);
;         const float a = v[e] * cs[e], bq = other * sn[e];
;         v[e] = (fq == 0) ? (a - bq) : ((fq == 1) ? (a + bq) : v[e]);
;     }
;     DI void operator()(const pg8::f32x4 (&acc)[2][2][4][2], const pg8::Unit& u, int wr, int wc, int fr, int fq) const {
;     ...
;                         if ((wc & 1) == 0) rope8(v, rope, s, fq);
.LBB0_1886:
	s_andn2_b64 vcc, exec, s[8:9]
	s_cbranch_vccnz .LBB0_1936
	v_and_b32_e32 v11, 64, v188
	v_xor_b32_e32 v10, 16, v188
	v_add_u32_e32 v11, 64, v11
	v_cmp_lt_i32_e32 vcc, v10, v11
	v_lshlrev_b32_e32 v11, 6, v112
	global_load_dwordx4 v[106:109], v11, s[68:69]
	global_load_dwordx4 v[102:105], v11, s[68:69] offset:32
	global_load_dwordx4 v[14:17], v11, s[68:69] offset:48
	global_load_dwordx4 v[98:101], v11, s[68:69] offset:16
	v_cndmask_b32_e32 v10, v188, v10, vcc
	v_lshlrev_b32_e32 v113, 2, v10
	v_mov_b32_e32 v224, v2
	v_mov_b32_e32 v225, v2
	v_cmp_eq_u32_e64 s[0:1], 1, v177
	s_nop 0
	v_permlane16_swap_b32_e32 v224, v225
	v_cndmask_b32_e64 v12, v225, v224, s[0:1]
	v_cmp_lt_i32_e32 vcc, 0, v177
	s_waitcnt vmcnt(3)
	v_mul_f32_e32 v11, v2, v106
	s_waitcnt vmcnt(2) lgkmcnt(0)
	v_mul_f32_e32 v12, v102, v12
	v_sub_f32_e32 v10, v11, v12
	v_add_f32_e32 v11, v11, v12
	v_cndmask_b32_e64 v11, v2, v11, s[0:1]
	v_cndmask_b32_e32 v10, v10, v11, vcc
	v_mov_b32_e32 v224, v3
	v_mov_b32_e32 v225, v3
	v_cmp_eq_u32_e64 s[0:1], 1, v177
	s_nop 0
	v_permlane16_swap_b32_e32 v224, v225
	v_cndmask_b32_e64 v11, v225, v224, s[0:1]
	v_mul_f32_e32 v12, v3, v107
	v_cmp_lt_i32_e32 vcc, 0, v177
	s_waitcnt lgkmcnt(0)
	v_mul_f32_e32 v13, v103, v11
	v_sub_f32_e32 v11, v12, v13
	v_add_f32_e32 v12, v12, v13
	v_cndmask_b32_e64 v12, v3, v12, s[0:1]
	v_cndmask_b32_e32 v11, v11, v12, vcc
	v_mov_b32_e32 v224, v4
	v_mov_b32_e32 v225, v4
	v_cmp_eq_u32_e64 s[0:1], 1, v177
	s_nop 0
	v_permlane16_swap_b32_e32 v224, v225
	v_cndmask_b32_e64 v12, v225, v224, s[0:1]
	v_mul_f32_e32 v13, v4, v108
	v_cmp_lt_i32_e32 vcc, 0, v177
	s_waitcnt lgkmcnt(0)
	v_mul_f32_e32 v102, v104, v12
	v_sub_f32_e32 v12, v13, v102
	v_add_f32_e32 v13, v13, v102
	v_cndmask_b32_e64 v13, v4, v13, s[0:1]
	v_cndmask_b32_e32 v12, v12, v13, vcc
	v_mov_b32_e32 v224, v5
	v_mov_b32_e32 v225, v5
	v_cmp_eq_u32_e64 s[0:1], 1, v177
	s_nop 0
	v_permlane16_swap_b32_e32 v224, v225
	v_cndmask_b32_e64 v13, v225, v224, s[0:1]
	v_mul_f32_e32 v102, v5, v109
	v_cmp_lt_i32_e32 vcc, 0, v177
	s_waitcnt lgkmcnt(0)
	v_mul_f32_e32 v103, v105, v13
	v_sub_f32_e32 v13, v102, v103
	v_add_f32_e32 v102, v102, v103
	v_cndmask_b32_e64 v102, v5, v102, s[0:1]
	v_cndmask_b32_e32 v13, v13, v102, vcc
	v_mov_b32_e32 v224, v6
	v_mov_b32_e32 v225, v6
	v_cmp_eq_u32_e64 s[0:1], 1, v177
	s_nop 0
	v_permlane16_swap_b32_e32 v224, v225
	v_cndmask_b32_e64 v102, v225, v224, s[0:1]
	s_waitcnt vmcnt(0)
	v_mul_f32_e32 v98, v6, v98
	v_cmp_lt_i32_e32 vcc, 0, v177
	s_waitcnt lgkmcnt(0)
	v_mul_f32_e32 v102, v14, v102
	v_sub_f32_e32 v14, v98, v102
	v_add_f32_e32 v98, v98, v102
	v_cndmask_b32_e64 v98, v6, v98, s[0:1]
	v_cndmask_b32_e32 v14, v14, v98, vcc
	v_mov_b32_e32 v224, v7
	v_mov_b32_e32 v225, v7
	v_cmp_eq_u32_e64 s[0:1], 1, v177
	s_nop 0
	v_permlane16_swap_b32_e32 v224, v225
	v_cndmask_b32_e64 v102, v225, v224, s[0:1]
	v_mul_f32_e32 v98, v7, v99
	v_cmp_lt_i32_e32 vcc, 0, v177
	s_waitcnt lgkmcnt(0)
	v_mul_f32_e32 v99, v15, v102
	v_sub_f32_e32 v15, v98, v99
	v_add_f32_e32 v98, v98, v99
	v_cndmask_b32_e64 v98, v7, v98, s[0:1]
	v_cndmask_b32_e32 v15, v15, v98, vcc
	v_mov_b32_e32 v224, v8
	v_mov_b32_e32 v225, v8
	v_cmp_eq_u32_e64 s[0:1], 1, v177
	s_nop 0
	v_permlane16_swap_b32_e32 v224, v225
	v_cndmask_b32_e64 v99, v225, v224, s[0:1]
	v_mul_f32_e32 v98, v8, v100
	v_cmp_lt_i32_e32 vcc, 0, v177
	s_waitcnt lgkmcnt(0)
	v_mul_f32_e32 v99, v16, v99
	v_sub_f32_e32 v16, v98, v99
	v_add_f32_e32 v98, v98, v99
	v_cndmask_b32_e64 v98, v8, v98, s[0:1]
	v_cndmask_b32_e32 v16, v16, v98, vcc
	v_mov_b32_e32 v224, v9
	v_mov_b32_e32 v225, v9
	v_cmp_eq_u32_e64 s[0:1], 1, v177
	s_nop 0
	v_permlane16_swap_b32_e32 v224, v225
	v_cndmask_b32_e64 v99, v225, v224, s[0:1]
	v_mul_f32_e32 v98, v9, v101
	v_cmp_lt_i32_e32 vcc, 0, v177
	s_waitcnt lgkmcnt(0)
	v_mul_f32_e32 v99, v17, v99
	v_sub_f32_e32 v17, v98, v99
	v_add_f32_e32 v98, v98, v99
	v_cndmask_b32_e64 v98, v9, v98, s[0:1]
	v_cndmask_b32_e32 v17, v17, v98, vcc

; DI void rope8(float (&v)[8], const float* __restrict__ rope, int s, int fq) {
;     const f32x4 c0 = *(const f32x4*)(rope + s * 16), c1 = *(const f32x4*)(rope + s * 16 + 4), s0 = *(const f32x4*)(rope + s * 16 + 8), s1 = *(const f32x4*)(rope + s * 16 + 12);
;     const float cs[8] = {c0[0], c0[1], c0[2], c0[3], c1[0], c1[1], c1[2], c1[3]}, sn[8] = {s0[0], s0[1], s0[2], s0[3], s1[0], s1[1], s1[2], s1[3]};
; #pragma unroll
;     for (int e = 0; e < 8; ++e) {
;         const float other = __shfl_xor(v[e], 16);
;         const float a = v[e] * cs[e], bq = other * sn[e];
;         v[e] = (fq == 0) ? (a - bq) : ((fq == 1) ? (a + bq) : v[e]);
;     }
;     DI void operator()(const pg8::f32x4 (&acc)[2][2][4][2], const pg8::Unit& u, int wr, int wc, int fr, int fq) const {
;     ...
;                         if ((wc & 1) == 0) rope8(v, rope, s, fq);
.LBB0_1951:
	s_andn2_b64 vcc, exec, s[8:9]
	s_cbranch_vccnz .LBB0_2001
	v_and_b32_e32 v11, 64, v188
	v_xor_b32_e32 v10, 16, v188
	v_add_u32_e32 v11, 64, v11
	v_cmp_lt_i32_e32 vcc, v10, v11
	v_lshlrev_b32_e32 v11, 6, v104
	global_load_dwordx4 v[98:101], v11, s[68:69]
	global_load_dwordx4 v[94:97], v11, s[68:69] offset:32
	global_load_dwordx4 v[14:17], v11, s[68:69] offset:48
	global_load_dwordx4 v[90:93], v11, s[68:69] offset:16
	v_cndmask_b32_e32 v10, v188, v10, vcc
	v_lshlrev_b32_e32 v105, 2, v10
	v_mov_b32_e32 v224, v2
	v_mov_b32_e32 v225, v2
	v_cmp_eq_u32_e64 s[0:1], 1, v177
	s_nop 0
	v_permlane16_swap_b32_e32 v224, v225
	v_cndmask_b32_e64 v12, v225, v224, s[0:1]
	v_cmp_lt_i32_e32 vcc, 0, v177
	s_waitcnt vmcnt(3)
	v_mul_f32_e32 v11, v2, v98
	s_waitcnt vmcnt(2) lgkmcnt(0)
	v_mul_f32_e32 v12, v94, v12
	v_sub_f32_e32 v10, v11, v12
	v_add_f32_e32 v11, v11, v12
	v_cndmask_b32_e64 v11, v2, v11, s[0:1]
	v_cndmask_b32_e32 v10, v10, v11, vcc
	v_mov_b32_e32 v224, v3
	v_mov_b32_e32 v225, v3
	v_cmp_eq_u32_e64 s[0:1], 1, v177
	s_nop 0
	v_permlane16_swap_b32_e32 v224, v225
	v_cndmask_b32_e64 v11, v225, v224, s[0:1]
	v_mul_f32_e32 v12, v3, v99
	v_cmp_lt_i32_e32 vcc, 0, v177
	s_waitcnt lgkmcnt(0)
	v_mul_f32_e32 v13, v95, v11
	v_sub_f32_e32 v11, v12, v13
	v_add_f32_e32 v12, v12, v13
	v_cndmask_b32_e64 v12, v3, v12, s[0:1]
	v_cndmask_b32_e32 v11, v11, v12, vcc
	v_mov_b32_e32 v224, v4
	v_mov_b32_e32 v225, v4
	v_cmp_eq_u32_e64 s[0:1], 1, v177
	s_nop 0
	v_permlane16_swap_b32_e32 v224, v225
	v_cndmask_b32_e64 v12, v225, v224, s[0:1]
	v_mul_f32_e32 v13, v4, v100
	v_cmp_lt_i32_e32 vcc, 0, v177
	s_waitcnt lgkmcnt(0)
	v_mul_f32_e32 v94, v96, v12
	v_sub_f32_e32 v12, v13, v94
	v_add_f32_e32 v13, v13, v94
	v_cndmask_b32_e64 v13, v4, v13, s[0:1]
	v_cndmask_b32_e32 v12, v12, v13, vcc
	v_mov_b32_e32 v224, v5
	v_mov_b32_e32 v225, v5
	v_cmp_eq_u32_e64 s[0:1], 1, v177
	s_nop 0
	v_permlane16_swap_b32_e32 v224, v225
	v_cndmask_b32_e64 v13, v225, v224, s[0:1]
	v_mul_f32_e32 v94, v5, v101
	v_cmp_lt_i32_e32 vcc, 0, v177
	s_waitcnt lgkmcnt(0)
	v_mul_f32_e32 v95, v97, v13
	v_sub_f32_e32 v13, v94, v95
	v_add_f32_e32 v94, v94, v95
	v_cndmask_b32_e64 v94, v5, v94, s[0:1]
	v_cndmask_b32_e32 v13, v13, v94, vcc
	v_mov_b32_e32 v224, v6
	v_mov_b32_e32 v225, v6
	v_cmp_eq_u32_e64 s[0:1], 1, v177
	s_nop 0
	v_permlane16_swap_b32_e32 v224, v225
	v_cndmask_b32_e64 v94, v225, v224, s[0:1]
	s_waitcnt vmcnt(0)
	v_mul_f32_e32 v90, v6, v90
	v_cmp_lt_i32_e32 vcc, 0, v177
	s_waitcnt lgkmcnt(0)
	v_mul_f32_e32 v94, v14, v94
	v_sub_f32_e32 v14, v90, v94
	v_add_f32_e32 v90, v90, v94
	v_cndmask_b32_e64 v90, v6, v90, s[0:1]
	v_cndmask_b32_e32 v14, v14, v90, vcc
	v_mov_b32_e32 v224, v7
	v_mov_b32_e32 v225, v7
	v_cmp_eq_u32_e64 s[0:1], 1, v177
	s_nop 0
	v_permlane16_swap_b32_e32 v224, v225
	v_cndmask_b32_e64 v94, v225, v224, s[0:1]
	v_mul_f32_e32 v90, v7, v91
	v_cmp_lt_i32_e32 vcc, 0, v177
	s_waitcnt lgkmcnt(0)
	v_mul_f32_e32 v91, v15, v94
	v_sub_f32_e32 v15, v90, v91
	v_add_f32_e32 v90, v90, v91
	v_cndmask_b32_e64 v90, v7, v90, s[0:1]
	v_cndmask_b32_e32 v15, v15, v90, vcc
	v_mov_b32_e32 v224, v8
	v_mov_b32_e32 v225, v8
	v_cmp_eq_u32_e64 s[0:1], 1, v177
	s_nop 0
	v_permlane16_swap_b32_e32 v224, v225
	v_cndmask_b32_e64 v91, v225, v224, s[0:1]
	v_mul_f32_e32 v90, v8, v92
	v_cmp_lt_i32_e32 vcc, 0, v177
	s_waitcnt lgkmcnt(0)
	v_mul_f32_e32 v91, v16, v91
	v_sub_f32_e32 v16, v90, v91
	v_add_f32_e32 v90, v90, v91
	v_cndmask_b32_e64 v90, v8, v90, s[0:1]
	v_cndmask_b32_e32 v16, v16, v90, vcc
	v_mov_b32_e32 v224, v9
	v_mov_b32_e32 v225, v9
	v_cmp_eq_u32_e64 s[0:1], 1, v177
	s_nop 0
	v_permlane16_swap_b32_e32 v224, v225
	v_cndmask_b32_e64 v91, v225, v224, s[0:1]
	v_mul_f32_e32 v90, v9, v93
	v_cmp_lt_i32_e32 vcc, 0, v177
	s_waitcnt lgkmcnt(0)
	v_mul_f32_e32 v91, v17, v91
	v_sub_f32_e32 v17, v90, v91
	v_add_f32_e32 v90, v90, v91
	v_cndmask_b32_e64 v90, v9, v90, s[0:1]
	v_cndmask_b32_e32 v17, v17, v90, vcc

; DI void rope8(float (&v)[8], const float* __restrict__ rope, int s, int fq) {
;     const f32x4 c0 = *(const f32x4*)(rope + s * 16), c1 = *(const f32x4*)(rope + s * 16 + 4), s0 = *(const f32x4*)(rope + s * 16 + 8), s1 = *(const f32x4*)(rope + s * 16 + 12);
;     const float cs[8] = {c0[0], c0[1], c0[2], c0[3], c1[0], c1[1], c1[2], c1[3]}, sn[8] = {s0[0], s0[1], s0[2], s0[3], s1[0], s1[1], s1[2], s1[3]};
; #pragma unroll
;     for (int e = 0; e < 8; ++e) {
;         const float other = __shfl_xor(v[e], 16);
;         const float a = v[e] * cs[e], bq = other * sn[e];
;         v[e] = (fq == 0) ? (a - bq) : ((fq == 1) ? (a + bq) : v[e]);
;     }
;     DI void operator()(const pg8::f32x4 (&acc)[2][2][4][2], const pg8::Unit& u, int wr, int wc, int fr, int fq) const {
;     ...
;                         if ((wc & 1) == 0) rope8(v, rope, s, fq);
.LBB0_2016:
	s_andn2_b64 vcc, exec, s[6:7]
	s_cbranch_vccnz .LBB0_2066
	v_and_b32_e32 v11, 64, v188
	v_xor_b32_e32 v10, 16, v188
	v_add_u32_e32 v11, 64, v11
	v_cmp_lt_i32_e32 vcc, v10, v11
	v_lshlrev_b32_e32 v11, 6, v96
	global_load_dwordx4 v[90:93], v11, s[68:69]
	global_load_dwordx4 v[86:89], v11, s[68:69] offset:32
	global_load_dwordx4 v[14:17], v11, s[68:69] offset:48
	global_load_dwordx4 v[82:85], v11, s[68:69] offset:16
	v_cndmask_b32_e32 v10, v188, v10, vcc
	v_lshlrev_b32_e32 v97, 2, v10
	v_mov_b32_e32 v224, v2
	v_mov_b32_e32 v225, v2
	v_cmp_eq_u32_e64 s[0:1], 1, v177
	s_nop 0
	v_permlane16_swap_b32_e32 v224, v225
	v_cndmask_b32_e64 v12, v225, v224, s[0:1]
	v_cmp_lt_i32_e32 vcc, 0, v177
	s_waitcnt vmcnt(3)
	v_mul_f32_e32 v11, v2, v90
	s_waitcnt vmcnt(2) lgkmcnt(0)
	v_mul_f32_e32 v12, v86, v12
	v_sub_f32_e32 v10, v11, v12
	v_add_f32_e32 v11, v11, v12
	v_cndmask_b32_e64 v11, v2, v11, s[0:1]
	v_cndmask_b32_e32 v10, v10, v11, vcc
	v_mov_b32_e32 v224, v3
	v_mov_b32_e32 v225, v3
	v_cmp_eq_u32_e64 s[0:1], 1, v177
	s_nop 0
	v_permlane16_swap_b32_e32 v224, v225
	v_cndmask_b32_e64 v11, v225, v224, s[0:1]
	v_mul_f32_e32 v12, v3, v91
	v_cmp_lt_i32_e32 vcc, 0, v177
	s_waitcnt lgkmcnt(0)
	v_mul_f32_e32 v13, v87, v11
	v_sub_f32_e32 v11, v12, v13
	v_add_f32_e32 v12, v12, v13
	v_cndmask_b32_e64 v12, v3, v12, s[0:1]
	v_cndmask_b32_e32 v11, v11, v12, vcc
	v_mov_b32_e32 v224, v4
	v_mov_b32_e32 v225, v4
	v_cmp_eq_u32_e64 s[0:1], 1, v177
	s_nop 0
	v_permlane16_swap_b32_e32 v224, v225
	v_cndmask_b32_e64 v12, v225, v224, s[0:1]
	v_mul_f32_e32 v13, v4, v92
	v_cmp_lt_i32_e32 vcc, 0, v177
	s_waitcnt lgkmcnt(0)
	v_mul_f32_e32 v86, v88, v12
	v_sub_f32_e32 v12, v13, v86
	v_add_f32_e32 v13, v13, v86
	v_cndmask_b32_e64 v13, v4, v13, s[0:1]
	v_cndmask_b32_e32 v12, v12, v13, vcc
	v_mov_b32_e32 v224, v5
	v_mov_b32_e32 v225, v5
	v_cmp_eq_u32_e64 s[0:1], 1, v177
	s_nop 0
	v_permlane16_swap_b32_e32 v224, v225
	v_cndmask_b32_e64 v13, v225, v224, s[0:1]
	v_mul_f32_e32 v86, v5, v93
	v_cmp_lt_i32_e32 vcc, 0, v177
	s_waitcnt lgkmcnt(0)
	v_mul_f32_e32 v87, v89, v13
	v_sub_f32_e32 v13, v86, v87
	v_add_f32_e32 v86, v86, v87
	v_cndmask_b32_e64 v86, v5, v86, s[0:1]
	v_cndmask_b32_e32 v13, v13, v86, vcc
	v_mov_b32_e32 v224, v6
	v_mov_b32_e32 v225, v6
	v_cmp_eq_u32_e64 s[0:1], 1, v177
	s_nop 0
	v_permlane16_swap_b32_e32 v224, v225
	v_cndmask_b32_e64 v86, v225, v224, s[0:1]
	s_waitcnt vmcnt(0)
	v_mul_f32_e32 v82, v6, v82
	v_cmp_lt_i32_e32 vcc, 0, v177
	s_waitcnt lgkmcnt(0)
	v_mul_f32_e32 v86, v14, v86
	v_sub_f32_e32 v14, v82, v86
	v_add_f32_e32 v82, v82, v86
	v_cndmask_b32_e64 v82, v6, v82, s[0:1]
	v_cndmask_b32_e32 v14, v14, v82, vcc
	v_mov_b32_e32 v224, v7
	v_mov_b32_e32 v225, v7
	v_cmp_eq_u32_e64 s[0:1], 1, v177
	s_nop 0
	v_permlane16_swap_b32_e32 v224, v225
	v_cndmask_b32_e64 v86, v225, v224, s[0:1]
	v_mul_f32_e32 v82, v7, v83
	v_cmp_lt_i32_e32 vcc, 0, v177
	s_waitcnt lgkmcnt(0)
	v_mul_f32_e32 v83, v15, v86
	v_sub_f32_e32 v15, v82, v83
	v_add_f32_e32 v82, v82, v83
	v_cndmask_b32_e64 v82, v7, v82, s[0:1]
	v_cndmask_b32_e32 v15, v15, v82, vcc
	v_mov_b32_e32 v224, v8
	v_mov_b32_e32 v225, v8
	v_cmp_eq_u32_e64 s[0:1], 1, v177
	s_nop 0
	v_permlane16_swap_b32_e32 v224, v225
	v_cndmask_b32_e64 v83, v225, v224, s[0:1]
	v_mul_f32_e32 v82, v8, v84
	v_cmp_lt_i32_e32 vcc, 0, v177
	s_waitcnt lgkmcnt(0)
	v_mul_f32_e32 v83, v16, v83
	v_sub_f32_e32 v16, v82, v83
	v_add_f32_e32 v82, v82, v83
	v_cndmask_b32_e64 v82, v8, v82, s[0:1]
	v_cndmask_b32_e32 v16, v16, v82, vcc
	v_mov_b32_e32 v224, v9
	v_mov_b32_e32 v225, v9
	v_cmp_eq_u32_e64 s[0:1], 1, v177
	s_nop 0
	v_permlane16_swap_b32_e32 v224, v225
	v_cndmask_b32_e64 v83, v225, v224, s[0:1]
	v_mul_f32_e32 v82, v9, v85
	v_cmp_lt_i32_e32 vcc, 0, v177
	s_waitcnt lgkmcnt(0)
	v_mul_f32_e32 v83, v17, v83
	v_sub_f32_e32 v17, v82, v83
	v_add_f32_e32 v82, v82, v83
	v_cndmask_b32_e64 v82, v9, v82, s[0:1]
	v_cndmask_b32_e32 v17, v17, v82, vcc

; DI void rope8(float (&v)[8], const float* __restrict__ rope, int s, int fq) {
;     const f32x4 c0 = *(const f32x4*)(rope + s * 16), c1 = *(const f32x4*)(rope + s * 16 + 4), s0 = *(const f32x4*)(rope + s * 16 + 8), s1 = *(const f32x4*)(rope + s * 16 + 12);
;     const float cs[8] = {c0[0], c0[1], c0[2], c0[3], c1[0], c1[1], c1[2], c1[3]}, sn[8] = {s0[0], s0[1], s0[2], s0[3], s1[0], s1[1], s1[2], s1[3]};
; #pragma unroll
;     for (int e = 0; e < 8; ++e) {
;         const float other = __shfl_xor(v[e], 16);
;         const float a = v[e] * cs[e], bq = other * sn[e];
;         v[e] = (fq == 0) ? (a - bq) : ((fq == 1) ? (a + bq) : v[e]);
;     }
;     DI void operator()(const pg8::f32x4 (&acc)[2][2][4][2], const pg8::Unit& u, int wr, int wc, int fr, int fq) const {
;     ...
;                         if ((wc & 1) == 0) rope8(v, rope, s, fq);
.LBB0_2138:
	s_andn2_b64 vcc, exec, s[10:11]
	s_cbranch_vccnz .LBB0_2188
	v_and_b32_e32 v11, 64, v188
	v_xor_b32_e32 v10, 16, v188
	v_add_u32_e32 v11, 64, v11
	v_cmp_lt_i32_e32 vcc, v10, v11
	v_lshlrev_b32_e32 v66, 6, v77
	s_nop 0
	v_cndmask_b32_e32 v10, v188, v10, vcc
	v_lshlrev_b32_e32 v79, 2, v10
	global_load_dwordx4 v[70:73], v66, s[68:69]
	global_load_dwordx4 v[10:13], v66, s[68:69] offset:32
	global_load_dwordx4 v[14:17], v66, s[68:69] offset:48
	s_nop 0
	global_load_dwordx4 v[66:69], v66, s[68:69] offset:16
	v_mov_b32_e32 v224, v2
	v_mov_b32_e32 v225, v2
	v_cmp_eq_u32_e64 s[0:1], 1, v177
	s_nop 0
	v_permlane16_swap_b32_e32 v224, v225
	v_cndmask_b32_e64 v80, v225, v224, s[0:1]
	v_cmp_lt_i32_e32 vcc, 0, v177
	s_waitcnt vmcnt(3)
	v_mul_f32_e32 v70, v2, v70
	s_waitcnt vmcnt(2) lgkmcnt(0)
	v_mul_f32_e32 v80, v10, v80
	v_sub_f32_e32 v10, v70, v80
	v_add_f32_e32 v70, v70, v80
	v_cndmask_b32_e64 v70, v2, v70, s[0:1]
	v_cndmask_b32_e32 v10, v10, v70, vcc
	v_mov_b32_e32 v224, v3
	v_mov_b32_e32 v225, v3
	v_cmp_eq_u32_e64 s[0:1], 1, v177
	s_nop 0
	v_permlane16_swap_b32_e32 v224, v225
	v_cndmask_b32_e64 v80, v225, v224, s[0:1]
	v_mul_f32_e32 v70, v3, v71
	v_cmp_lt_i32_e32 vcc, 0, v177
	s_waitcnt lgkmcnt(0)
	v_mul_f32_e32 v71, v11, v80
	v_sub_f32_e32 v11, v70, v71
	v_add_f32_e32 v70, v70, v71
	v_cndmask_b32_e64 v70, v3, v70, s[0:1]
	v_cndmask_b32_e32 v11, v11, v70, vcc
	v_mov_b32_e32 v224, v4
	v_mov_b32_e32 v225, v4
	v_cmp_eq_u32_e64 s[0:1], 1, v177
	s_nop 0
	v_permlane16_swap_b32_e32 v224, v225
	v_cndmask_b32_e64 v71, v225, v224, s[0:1]
	v_mul_f32_e32 v70, v4, v72
	v_cmp_lt_i32_e32 vcc, 0, v177
	s_waitcnt lgkmcnt(0)
	v_mul_f32_e32 v71, v12, v71
	v_sub_f32_e32 v12, v70, v71
	v_add_f32_e32 v70, v70, v71
	v_cndmask_b32_e64 v70, v4, v70, s[0:1]
	v_cndmask_b32_e32 v12, v12, v70, vcc
	v_mov_b32_e32 v224, v5
	v_mov_b32_e32 v225, v5
	v_cmp_eq_u32_e64 s[0:1], 1, v177
	s_nop 0
	v_permlane16_swap_b32_e32 v224, v225
	v_cndmask_b32_e64 v71, v225, v224, s[0:1]
	v_mul_f32_e32 v70, v5, v73
	v_cmp_lt_i32_e32 vcc, 0, v177
	s_waitcnt lgkmcnt(0)
	v_mul_f32_e32 v71, v13, v71
	v_sub_f32_e32 v13, v70, v71
	v_add_f32_e32 v70, v70, v71
	v_cndmask_b32_e64 v70, v5, v70, s[0:1]
	v_cndmask_b32_e32 v13, v13, v70, vcc
	v_mov_b32_e32 v224, v6
	v_mov_b32_e32 v225, v6
	v_cmp_eq_u32_e64 s[0:1], 1, v177
	s_nop 0
	v_permlane16_swap_b32_e32 v224, v225
	v_cndmask_b32_e64 v70, v225, v224, s[0:1]
	s_waitcnt vmcnt(0)
	v_mul_f32_e32 v66, v6, v66
	v_cmp_lt_i32_e32 vcc, 0, v177
	s_waitcnt lgkmcnt(0)
	v_mul_f32_e32 v70, v14, v70
	v_sub_f32_e32 v14, v66, v70
	v_add_f32_e32 v66, v66, v70
	v_cndmask_b32_e64 v66, v6, v66, s[0:1]
	v_cndmask_b32_e32 v14, v14, v66, vcc
	v_mov_b32_e32 v224, v7
	v_mov_b32_e32 v225, v7
	v_cmp_eq_u32_e64 s[0:1], 1, v177
	s_nop 0
	v_permlane16_swap_b32_e32 v224, v225
	v_cndmask_b32_e64 v70, v225, v224, s[0:1]
	v_mul_f32_e32 v66, v7, v67
	v_cmp_lt_i32_e32 vcc, 0, v177
	s_waitcnt lgkmcnt(0)
	v_mul_f32_e32 v67, v15, v70
	v_sub_f32_e32 v15, v66, v67
	v_add_f32_e32 v66, v66, v67
	v_cndmask_b32_e64 v66, v7, v66, s[0:1]
	v_cndmask_b32_e32 v15, v15, v66, vcc
	v_mov_b32_e32 v224, v8
	v_mov_b32_e32 v225, v8
	v_cmp_eq_u32_e64 s[0:1], 1, v177
	s_nop 0
	v_permlane16_swap_b32_e32 v224, v225
	v_cndmask_b32_e64 v67, v225, v224, s[0:1]
	v_mul_f32_e32 v66, v8, v68
	v_cmp_lt_i32_e32 vcc, 0, v177
	s_waitcnt lgkmcnt(0)
	v_mul_f32_e32 v67, v16, v67
	v_sub_f32_e32 v16, v66, v67
	v_add_f32_e32 v66, v66, v67
	v_cndmask_b32_e64 v66, v8, v66, s[0:1]
	v_cndmask_b32_e32 v16, v16, v66, vcc
	v_mov_b32_e32 v224, v9
	v_mov_b32_e32 v225, v9
	v_cmp_eq_u32_e64 s[0:1], 1, v177
	s_nop 0
	v_permlane16_swap_b32_e32 v224, v225
	v_cndmask_b32_e64 v67, v225, v224, s[0:1]
	v_mul_f32_e32 v66, v9, v69
	v_cmp_lt_i32_e32 vcc, 0, v177
	s_waitcnt lgkmcnt(0)
	v_mul_f32_e32 v67, v17, v67
	v_sub_f32_e32 v17, v66, v67
	v_add_f32_e32 v66, v66, v67
	v_cndmask_b32_e64 v66, v9, v66, s[0:1]
	v_cndmask_b32_e32 v17, v17, v66, vcc

; DI void rope8(float (&v)[8], const float* __restrict__ rope, int s, int fq) {
;     const f32x4 c0 = *(const f32x4*)(rope + s * 16), c1 = *(const f32x4*)(rope + s * 16 + 4), s0 = *(const f32x4*)(rope + s * 16 + 8), s1 = *(const f32x4*)(rope + s * 16 + 12);
;     const float cs[8] = {c0[0], c0[1], c0[2], c0[3], c1[0], c1[1], c1[2], c1[3]}, sn[8] = {s0[0], s0[1], s0[2], s0[3], s1[0], s1[1], s1[2], s1[3]};
; #pragma unroll
;     for (int e = 0; e < 8; ++e) {
;         const float other = __shfl_xor(v[e], 16);
;         const float a = v[e] * cs[e], bq = other * sn[e];
;         v[e] = (fq == 0) ? (a - bq) : ((fq == 1) ? (a + bq) : v[e]);
;     }
;     DI void operator()(const pg8::f32x4 (&acc)[2][2][4][2], const pg8::Unit& u, int wr, int wc, int fr, int fq) const {
;     ...
;                         if ((wc & 1) == 0) rope8(v, rope, s, fq);
.LBB0_2194:
	s_andn2_b64 vcc, exec, s[10:11]
	s_cbranch_vccnz .LBB0_2244
	v_and_b32_e32 v11, 64, v188
	v_xor_b32_e32 v10, 16, v188
	v_add_u32_e32 v11, 64, v11
	v_cmp_lt_i32_e32 vcc, v10, v11
	v_lshlrev_b32_e32 v58, 6, v67
	s_nop 0
	v_cndmask_b32_e32 v10, v188, v10, vcc
	v_lshlrev_b32_e32 v68, 2, v10
	global_load_dwordx4 v[62:65], v58, s[68:69]
	global_load_dwordx4 v[10:13], v58, s[68:69] offset:32
	global_load_dwordx4 v[14:17], v58, s[68:69] offset:48
	s_nop 0
	global_load_dwordx4 v[58:61], v58, s[68:69] offset:16
	v_mov_b32_e32 v224, v2
	v_mov_b32_e32 v225, v2
	v_cmp_eq_u32_e64 s[0:1], 1, v177
	s_nop 0
	v_permlane16_swap_b32_e32 v224, v225
	v_cndmask_b32_e64 v69, v225, v224, s[0:1]
	v_cmp_lt_i32_e32 vcc, 0, v177
	s_waitcnt vmcnt(3)
	v_mul_f32_e32 v62, v2, v62
	s_waitcnt vmcnt(2) lgkmcnt(0)
	v_mul_f32_e32 v69, v10, v69
	v_sub_f32_e32 v10, v62, v69
	v_add_f32_e32 v62, v62, v69
	v_cndmask_b32_e64 v62, v2, v62, s[0:1]
	v_cndmask_b32_e32 v10, v10, v62, vcc
	v_mov_b32_e32 v224, v3
	v_mov_b32_e32 v225, v3
	v_cmp_eq_u32_e64 s[0:1], 1, v177
	s_nop 0
	v_permlane16_swap_b32_e32 v224, v225
	v_cndmask_b32_e64 v69, v225, v224, s[0:1]
	v_mul_f32_e32 v62, v3, v63
	v_cmp_lt_i32_e32 vcc, 0, v177
	s_waitcnt lgkmcnt(0)
	v_mul_f32_e32 v63, v11, v69
	v_sub_f32_e32 v11, v62, v63
	v_add_f32_e32 v62, v62, v63
	v_cndmask_b32_e64 v62, v3, v62, s[0:1]
	v_cndmask_b32_e32 v11, v11, v62, vcc
	v_mov_b32_e32 v224, v4
	v_mov_b32_e32 v225, v4
	v_cmp_eq_u32_e64 s[0:1], 1, v177
	s_nop 0
	v_permlane16_swap_b32_e32 v224, v225
	v_cndmask_b32_e64 v63, v225, v224, s[0:1]
	v_mul_f32_e32 v62, v4, v64
	v_cmp_lt_i32_e32 vcc, 0, v177
	s_waitcnt lgkmcnt(0)
	v_mul_f32_e32 v63, v12, v63
	v_sub_f32_e32 v12, v62, v63
	v_add_f32_e32 v62, v62, v63
	v_cndmask_b32_e64 v62, v4, v62, s[0:1]
	v_cndmask_b32_e32 v12, v12, v62, vcc
	v_mov_b32_e32 v224, v5
	v_mov_b32_e32 v225, v5
	v_cmp_eq_u32_e64 s[0:1], 1, v177
	s_nop 0
	v_permlane16_swap_b32_e32 v224, v225
	v_cndmask_b32_e64 v63, v225, v224, s[0:1]
	v_mul_f32_e32 v62, v5, v65
	v_cmp_lt_i32_e32 vcc, 0, v177
	s_waitcnt lgkmcnt(0)
	v_mul_f32_e32 v63, v13, v63
	v_sub_f32_e32 v13, v62, v63
	v_add_f32_e32 v62, v62, v63
	v_cndmask_b32_e64 v62, v5, v62, s[0:1]
	v_cndmask_b32_e32 v13, v13, v62, vcc
	v_mov_b32_e32 v224, v6
	v_mov_b32_e32 v225, v6
	v_cmp_eq_u32_e64 s[0:1], 1, v177
	s_nop 0
	v_permlane16_swap_b32_e32 v224, v225
	v_cndmask_b32_e64 v62, v225, v224, s[0:1]
	s_waitcnt vmcnt(0)
	v_mul_f32_e32 v58, v6, v58
	v_cmp_lt_i32_e32 vcc, 0, v177
	s_waitcnt lgkmcnt(0)
	v_mul_f32_e32 v62, v14, v62
	v_sub_f32_e32 v14, v58, v62
	v_add_f32_e32 v58, v58, v62
	v_cndmask_b32_e64 v58, v6, v58, s[0:1]
	v_cndmask_b32_e32 v14, v14, v58, vcc
	v_mov_b32_e32 v224, v7
	v_mov_b32_e32 v225, v7
	v_cmp_eq_u32_e64 s[0:1], 1, v177
	s_nop 0
	v_permlane16_swap_b32_e32 v224, v225
	v_cndmask_b32_e64 v62, v225, v224, s[0:1]
	v_mul_f32_e32 v58, v7, v59
	v_cmp_lt_i32_e32 vcc, 0, v177
	s_waitcnt lgkmcnt(0)
	v_mul_f32_e32 v59, v15, v62
	v_sub_f32_e32 v15, v58, v59
	v_add_f32_e32 v58, v58, v59
	v_cndmask_b32_e64 v58, v7, v58, s[0:1]
	v_cndmask_b32_e32 v15, v15, v58, vcc
	v_mov_b32_e32 v224, v8
	v_mov_b32_e32 v225, v8
	v_cmp_eq_u32_e64 s[0:1], 1, v177
	s_nop 0
	v_permlane16_swap_b32_e32 v224, v225
	v_cndmask_b32_e64 v59, v225, v224, s[0:1]
	v_mul_f32_e32 v58, v8, v60
	v_cmp_lt_i32_e32 vcc, 0, v177
	s_waitcnt lgkmcnt(0)
	v_mul_f32_e32 v59, v16, v59
	v_sub_f32_e32 v16, v58, v59
	v_add_f32_e32 v58, v58, v59
	v_cndmask_b32_e64 v58, v8, v58, s[0:1]
	v_cndmask_b32_e32 v16, v16, v58, vcc
	v_mov_b32_e32 v224, v9
	v_mov_b32_e32 v225, v9
	v_cmp_eq_u32_e64 s[0:1], 1, v177
	s_nop 0
	v_permlane16_swap_b32_e32 v224, v225
	v_cndmask_b32_e64 v59, v225, v224, s[0:1]
	v_mul_f32_e32 v58, v9, v61
	v_cmp_lt_i32_e32 vcc, 0, v177
	s_waitcnt lgkmcnt(0)
	v_mul_f32_e32 v59, v17, v59
	v_sub_f32_e32 v17, v58, v59
	v_add_f32_e32 v58, v58, v59
	v_cndmask_b32_e64 v58, v9, v58, s[0:1]
	v_cndmask_b32_e32 v17, v17, v58, vcc

; DI void rope8(float (&v)[8], const float* __restrict__ rope, int s, int fq) {
;     const f32x4 c0 = *(const f32x4*)(rope + s * 16), c1 = *(const f32x4*)(rope + s * 16 + 4), s0 = *(const f32x4*)(rope + s * 16 + 8), s1 = *(const f32x4*)(rope + s * 16 + 12);
;     const float cs[8] = {c0[0], c0[1], c0[2], c0[3], c1[0], c1[1], c1[2], c1[3]}, sn[8] = {s0[0], s0[1], s0[2], s0[3], s1[0], s1[1], s1[2], s1[3]};
; #pragma unroll
;     for (int e = 0; e < 8; ++e) {
;         const float other = __shfl_xor(v[e], 16);
;         const float a = v[e] * cs[e], bq = other * sn[e];
;         v[e] = (fq == 0) ? (a - bq) : ((fq == 1) ? (a + bq) : v[e]);
;     }
;     DI void operator()(const pg8::f32x4 (&acc)[2][2][4][2], const pg8::Unit& u, int wr, int wc, int fr, int fq) const {
;     ...
;                         if ((wc & 1) == 0) rope8(v, rope, s, fq);
.LBB0_2250:
	s_andn2_b64 vcc, exec, s[10:11]
	s_cbranch_vccnz .LBB0_2300
	v_and_b32_e32 v11, 64, v188
	v_xor_b32_e32 v10, 16, v188
	v_add_u32_e32 v11, 64, v11
	v_cmp_lt_i32_e32 vcc, v10, v11
	v_lshlrev_b32_e32 v50, 6, v59
	s_nop 0
	v_cndmask_b32_e32 v10, v188, v10, vcc
	v_lshlrev_b32_e32 v60, 2, v10
	global_load_dwordx4 v[54:57], v50, s[68:69]
	global_load_dwordx4 v[10:13], v50, s[68:69] offset:32
	global_load_dwordx4 v[14:17], v50, s[68:69] offset:48
	s_nop 0
	global_load_dwordx4 v[50:53], v50, s[68:69] offset:16
	v_mov_b32_e32 v224, v2
	v_mov_b32_e32 v225, v2
	v_cmp_eq_u32_e64 s[0:1], 1, v177
	s_nop 0
	v_permlane16_swap_b32_e32 v224, v225
	v_cndmask_b32_e64 v61, v225, v224, s[0:1]
	v_cmp_lt_i32_e32 vcc, 0, v177
	s_waitcnt vmcnt(3)
	v_mul_f32_e32 v54, v2, v54
	s_waitcnt vmcnt(2) lgkmcnt(0)
	v_mul_f32_e32 v61, v10, v61
	v_sub_f32_e32 v10, v54, v61
	v_add_f32_e32 v54, v54, v61
	v_cndmask_b32_e64 v54, v2, v54, s[0:1]
	v_cndmask_b32_e32 v10, v10, v54, vcc
	v_mov_b32_e32 v224, v3
	v_mov_b32_e32 v225, v3
	v_cmp_eq_u32_e64 s[0:1], 1, v177
	s_nop 0
	v_permlane16_swap_b32_e32 v224, v225
	v_cndmask_b32_e64 v61, v225, v224, s[0:1]
	v_mul_f32_e32 v54, v3, v55
	v_cmp_lt_i32_e32 vcc, 0, v177
	s_waitcnt lgkmcnt(0)
	v_mul_f32_e32 v55, v11, v61
	v_sub_f32_e32 v11, v54, v55
	v_add_f32_e32 v54, v54, v55
	v_cndmask_b32_e64 v54, v3, v54, s[0:1]
	v_cndmask_b32_e32 v11, v11, v54, vcc
	v_mov_b32_e32 v224, v4
	v_mov_b32_e32 v225, v4
	v_cmp_eq_u32_e64 s[0:1], 1, v177
	s_nop 0
	v_permlane16_swap_b32_e32 v224, v225
	v_cndmask_b32_e64 v55, v225, v224, s[0:1]
	v_mul_f32_e32 v54, v4, v56
	v_cmp_lt_i32_e32 vcc, 0, v177
	s_waitcnt lgkmcnt(0)
	v_mul_f32_e32 v55, v12, v55
	v_sub_f32_e32 v12, v54, v55
	v_add_f32_e32 v54, v54, v55
	v_cndmask_b32_e64 v54, v4, v54, s[0:1]
	v_cndmask_b32_e32 v12, v12, v54, vcc
	v_mov_b32_e32 v224, v5
	v_mov_b32_e32 v225, v5
	v_cmp_eq_u32_e64 s[0:1], 1, v177
	s_nop 0
	v_permlane16_swap_b32_e32 v224, v225
	v_cndmask_b32_e64 v55, v225, v224, s[0:1]
	v_mul_f32_e32 v54, v5, v57
	v_cmp_lt_i32_e32 vcc, 0, v177
	s_waitcnt lgkmcnt(0)
	v_mul_f32_e32 v55, v13, v55
	v_sub_f32_e32 v13, v54, v55
	v_add_f32_e32 v54, v54, v55
	v_cndmask_b32_e64 v54, v5, v54, s[0:1]
	v_cndmask_b32_e32 v13, v13, v54, vcc
	v_mov_b32_e32 v224, v6
	v_mov_b32_e32 v225, v6
	v_cmp_eq_u32_e64 s[0:1], 1, v177
	s_nop 0
	v_permlane16_swap_b32_e32 v224, v225
	v_cndmask_b32_e64 v54, v225, v224, s[0:1]
	s_waitcnt vmcnt(0)
	v_mul_f32_e32 v50, v6, v50
	v_cmp_lt_i32_e32 vcc, 0, v177
	s_waitcnt lgkmcnt(0)
	v_mul_f32_e32 v54, v14, v54
	v_sub_f32_e32 v14, v50, v54
	v_add_f32_e32 v50, v50, v54
	v_cndmask_b32_e64 v50, v6, v50, s[0:1]
	v_cndmask_b32_e32 v14, v14, v50, vcc
	v_mov_b32_e32 v224, v7
	v_mov_b32_e32 v225, v7
	v_cmp_eq_u32_e64 s[0:1], 1, v177
	s_nop 0
	v_permlane16_swap_b32_e32 v224, v225
	v_cndmask_b32_e64 v54, v225, v224, s[0:1]
	v_mul_f32_e32 v50, v7, v51
	v_cmp_lt_i32_e32 vcc, 0, v177
	s_waitcnt lgkmcnt(0)
	v_mul_f32_e32 v51, v15, v54
	v_sub_f32_e32 v15, v50, v51
	v_add_f32_e32 v50, v50, v51
	v_cndmask_b32_e64 v50, v7, v50, s[0:1]
	v_cndmask_b32_e32 v15, v15, v50, vcc
	v_mov_b32_e32 v224, v8
	v_mov_b32_e32 v225, v8
	v_cmp_eq_u32_e64 s[0:1], 1, v177
	s_nop 0
	v_permlane16_swap_b32_e32 v224, v225
	v_cndmask_b32_e64 v51, v225, v224, s[0:1]
	v_mul_f32_e32 v50, v8, v52
	v_cmp_lt_i32_e32 vcc, 0, v177
	s_waitcnt lgkmcnt(0)
	v_mul_f32_e32 v51, v16, v51
	v_sub_f32_e32 v16, v50, v51
	v_add_f32_e32 v50, v50, v51
	v_cndmask_b32_e64 v50, v8, v50, s[0:1]
	v_cndmask_b32_e32 v16, v16, v50, vcc
	v_mov_b32_e32 v224, v9
	v_mov_b32_e32 v225, v9
	v_cmp_eq_u32_e64 s[0:1], 1, v177
	s_nop 0
	v_permlane16_swap_b32_e32 v224, v225
	v_cndmask_b32_e64 v51, v225, v224, s[0:1]
	v_mul_f32_e32 v50, v9, v53
	v_cmp_lt_i32_e32 vcc, 0, v177
	s_waitcnt lgkmcnt(0)
	v_mul_f32_e32 v51, v17, v51
	v_sub_f32_e32 v17, v50, v51
	v_add_f32_e32 v50, v50, v51
	v_cndmask_b32_e64 v50, v9, v50, s[0:1]
	v_cndmask_b32_e32 v17, v17, v50, vcc

; DI void rope8(float (&v)[8], const float* __restrict__ rope, int s, int fq) {
;     const f32x4 c0 = *(const f32x4*)(rope + s * 16), c1 = *(const f32x4*)(rope + s * 16 + 4), s0 = *(const f32x4*)(rope + s * 16 + 8), s1 = *(const f32x4*)(rope + s * 16 + 12);
;     const float cs[8] = {c0[0], c0[1], c0[2], c0[3], c1[0], c1[1], c1[2], c1[3]}, sn[8] = {s0[0], s0[1], s0[2], s0[3], s1[0], s1[1], s1[2], s1[3]};
; #pragma unroll
;     for (int e = 0; e < 8; ++e) {
;         const float other = __shfl_xor(v[e], 16);
;         const float a = v[e] * cs[e], bq = other * sn[e];
;         v[e] = (fq == 0) ? (a - bq) : ((fq == 1) ? (a + bq) : v[e]);
;     }
;     DI void operator()(const pg8::f32x4 (&acc)[2][2][4][2], const pg8::Unit& u, int wr, int wc, int fr, int fq) const {
;     ...
;                         if ((wc & 1) == 0) rope8(v, rope, s, fq);
.LBB0_2306:
	s_andn2_b64 vcc, exec, s[10:11]
	s_cbranch_vccnz .LBB0_2356
	v_and_b32_e32 v11, 64, v188
	v_xor_b32_e32 v10, 16, v188
	v_add_u32_e32 v11, 64, v11
	v_cmp_lt_i32_e32 vcc, v10, v11
	v_lshlrev_b32_e32 v42, 6, v51
	s_nop 0
	v_cndmask_b32_e32 v10, v188, v10, vcc
	v_lshlrev_b32_e32 v52, 2, v10
	global_load_dwordx4 v[46:49], v42, s[68:69]
	global_load_dwordx4 v[10:13], v42, s[68:69] offset:32
	global_load_dwordx4 v[14:17], v42, s[68:69] offset:48
	s_nop 0
	global_load_dwordx4 v[42:45], v42, s[68:69] offset:16
	v_mov_b32_e32 v224, v2
	v_mov_b32_e32 v225, v2
	v_cmp_eq_u32_e64 s[0:1], 1, v177
	s_nop 0
	v_permlane16_swap_b32_e32 v224, v225
	v_cndmask_b32_e64 v53, v225, v224, s[0:1]
	v_cmp_lt_i32_e32 vcc, 0, v177
	s_waitcnt vmcnt(3)
	v_mul_f32_e32 v46, v2, v46
	s_waitcnt vmcnt(2) lgkmcnt(0)
	v_mul_f32_e32 v53, v10, v53
	v_sub_f32_e32 v10, v46, v53
	v_add_f32_e32 v46, v46, v53
	v_cndmask_b32_e64 v46, v2, v46, s[0:1]
	v_cndmask_b32_e32 v10, v10, v46, vcc
	v_mov_b32_e32 v224, v3
	v_mov_b32_e32 v225, v3
	v_cmp_eq_u32_e64 s[0:1], 1, v177
	s_nop 0
	v_permlane16_swap_b32_e32 v224, v225
	v_cndmask_b32_e64 v53, v225, v224, s[0:1]
	v_mul_f32_e32 v46, v3, v47
	v_cmp_lt_i32_e32 vcc, 0, v177
	s_waitcnt lgkmcnt(0)
	v_mul_f32_e32 v47, v11, v53
	v_sub_f32_e32 v11, v46, v47
	v_add_f32_e32 v46, v46, v47
	v_cndmask_b32_e64 v46, v3, v46, s[0:1]
	v_cndmask_b32_e32 v11, v11, v46, vcc
	v_mov_b32_e32 v224, v4
	v_mov_b32_e32 v225, v4
	v_cmp_eq_u32_e64 s[0:1], 1, v177
	s_nop 0
	v_permlane16_swap_b32_e32 v224, v225
	v_cndmask_b32_e64 v47, v225, v224, s[0:1]
	v_mul_f32_e32 v46, v4, v48
	v_cmp_lt_i32_e32 vcc, 0, v177
	s_waitcnt lgkmcnt(0)
	v_mul_f32_e32 v47, v12, v47
	v_sub_f32_e32 v12, v46, v47
	v_add_f32_e32 v46, v46, v47
	v_cndmask_b32_e64 v46, v4, v46, s[0:1]
	v_cndmask_b32_e32 v12, v12, v46, vcc
	v_mov_b32_e32 v224, v5
	v_mov_b32_e32 v225, v5
	v_cmp_eq_u32_e64 s[0:1], 1, v177
	s_nop 0
	v_permlane16_swap_b32_e32 v224, v225
	v_cndmask_b32_e64 v47, v225, v224, s[0:1]
	v_mul_f32_e32 v46, v5, v49
	v_cmp_lt_i32_e32 vcc, 0, v177
	s_waitcnt lgkmcnt(0)
	v_mul_f32_e32 v47, v13, v47
	v_sub_f32_e32 v13, v46, v47
	v_add_f32_e32 v46, v46, v47
	v_cndmask_b32_e64 v46, v5, v46, s[0:1]
	v_cndmask_b32_e32 v13, v13, v46, vcc
	v_mov_b32_e32 v224, v6
	v_mov_b32_e32 v225, v6
	v_cmp_eq_u32_e64 s[0:1], 1, v177
	s_nop 0
	v_permlane16_swap_b32_e32 v224, v225
	v_cndmask_b32_e64 v46, v225, v224, s[0:1]
	s_waitcnt vmcnt(0)
	v_mul_f32_e32 v42, v6, v42
	v_cmp_lt_i32_e32 vcc, 0, v177
	s_waitcnt lgkmcnt(0)
	v_mul_f32_e32 v46, v14, v46
	v_sub_f32_e32 v14, v42, v46
	v_add_f32_e32 v42, v42, v46
	v_cndmask_b32_e64 v42, v6, v42, s[0:1]
	v_cndmask_b32_e32 v14, v14, v42, vcc
	v_mov_b32_e32 v224, v7
	v_mov_b32_e32 v225, v7
	v_cmp_eq_u32_e64 s[0:1], 1, v177
	s_nop 0
	v_permlane16_swap_b32_e32 v224, v225
	v_cndmask_b32_e64 v46, v225, v224, s[0:1]
	v_mul_f32_e32 v42, v7, v43
	v_cmp_lt_i32_e32 vcc, 0, v177
	s_waitcnt lgkmcnt(0)
	v_mul_f32_e32 v43, v15, v46
	v_sub_f32_e32 v15, v42, v43
	v_add_f32_e32 v42, v42, v43
	v_cndmask_b32_e64 v42, v7, v42, s[0:1]
	v_cndmask_b32_e32 v15, v15, v42, vcc
	v_mov_b32_e32 v224, v8
	v_mov_b32_e32 v225, v8
	v_cmp_eq_u32_e64 s[0:1], 1, v177
	s_nop 0
	v_permlane16_swap_b32_e32 v224, v225
	v_cndmask_b32_e64 v43, v225, v224, s[0:1]
	v_mul_f32_e32 v42, v8, v44
	v_cmp_lt_i32_e32 vcc, 0, v177
	s_waitcnt lgkmcnt(0)
	v_mul_f32_e32 v43, v16, v43
	v_sub_f32_e32 v16, v42, v43
	v_add_f32_e32 v42, v42, v43
	v_cndmask_b32_e64 v42, v8, v42, s[0:1]
	v_cndmask_b32_e32 v16, v16, v42, vcc
	v_mov_b32_e32 v224, v9
	v_mov_b32_e32 v225, v9
	v_cmp_eq_u32_e64 s[0:1], 1, v177
	s_nop 0
	v_permlane16_swap_b32_e32 v224, v225
	v_cndmask_b32_e64 v43, v225, v224, s[0:1]
	v_mul_f32_e32 v42, v9, v45
	v_cmp_lt_i32_e32 vcc, 0, v177
	s_waitcnt lgkmcnt(0)
	v_mul_f32_e32 v43, v17, v43
	v_sub_f32_e32 v17, v42, v43
	v_add_f32_e32 v42, v42, v43
	v_cndmask_b32_e64 v42, v9, v42, s[0:1]
	v_cndmask_b32_e32 v17, v17, v42, vcc

; DI void rope8(float (&v)[8], const float* __restrict__ rope, int s, int fq) {
;     const f32x4 c0 = *(const f32x4*)(rope + s * 16), c1 = *(const f32x4*)(rope + s * 16 + 4), s0 = *(const f32x4*)(rope + s * 16 + 8), s1 = *(const f32x4*)(rope + s * 16 + 12);
;     const float cs[8] = {c0[0], c0[1], c0[2], c0[3], c1[0], c1[1], c1[2], c1[3]}, sn[8] = {s0[0], s0[1], s0[2], s0[3], s1[0], s1[1], s1[2], s1[3]};
; #pragma unroll
;     for (int e = 0; e < 8; ++e) {
;         const float other = __shfl_xor(v[e], 16);
;         const float a = v[e] * cs[e], bq = other * sn[e];
;         v[e] = (fq == 0) ? (a - bq) : ((fq == 1) ? (a + bq) : v[e]);
;     }
;     DI void operator()(const pg8::f32x4 (&acc)[2][2][4][2], const pg8::Unit& u, int wr, int wc, int fr, int fq) const {
;     ...
;                         if ((wc & 1) == 0) rope8(v, rope, s, fq);
.LBB0_2362:
	s_andn2_b64 vcc, exec, s[10:11]
	s_cbranch_vccnz .LBB0_2412
	v_and_b32_e32 v11, 64, v188
	v_xor_b32_e32 v10, 16, v188
	v_add_u32_e32 v11, 64, v11
	v_cmp_lt_i32_e32 vcc, v10, v11
	v_lshlrev_b32_e32 v34, 6, v45
	s_nop 0
	v_cndmask_b32_e32 v10, v188, v10, vcc
	v_lshlrev_b32_e32 v46, 2, v10
	global_load_dwordx4 v[38:41], v34, s[68:69]
	global_load_dwordx4 v[10:13], v34, s[68:69] offset:32
	global_load_dwordx4 v[14:17], v34, s[68:69] offset:48
	s_nop 0
	global_load_dwordx4 v[34:37], v34, s[68:69] offset:16
	v_mov_b32_e32 v224, v2
	v_mov_b32_e32 v225, v2
	v_cmp_eq_u32_e64 s[0:1], 1, v177
	s_nop 0
	v_permlane16_swap_b32_e32 v224, v225
	v_cndmask_b32_e64 v47, v225, v224, s[0:1]
	v_cmp_lt_i32_e32 vcc, 0, v177
	s_waitcnt vmcnt(3)
	v_mul_f32_e32 v38, v2, v38
	s_waitcnt vmcnt(2) lgkmcnt(0)
	v_mul_f32_e32 v47, v10, v47
	v_sub_f32_e32 v10, v38, v47
	v_add_f32_e32 v38, v38, v47
	v_cndmask_b32_e64 v38, v2, v38, s[0:1]
	v_cndmask_b32_e32 v10, v10, v38, vcc
	v_mov_b32_e32 v224, v3
	v_mov_b32_e32 v225, v3
	v_cmp_eq_u32_e64 s[0:1], 1, v177
	s_nop 0
	v_permlane16_swap_b32_e32 v224, v225
	v_cndmask_b32_e64 v47, v225, v224, s[0:1]
	v_mul_f32_e32 v38, v3, v39
	v_cmp_lt_i32_e32 vcc, 0, v177
	s_waitcnt lgkmcnt(0)
	v_mul_f32_e32 v39, v11, v47
	v_sub_f32_e32 v11, v38, v39
	v_add_f32_e32 v38, v38, v39
	v_cndmask_b32_e64 v38, v3, v38, s[0:1]
	v_cndmask_b32_e32 v11, v11, v38, vcc
	v_mov_b32_e32 v224, v4
	v_mov_b32_e32 v225, v4
	v_cmp_eq_u32_e64 s[0:1], 1, v177
	s_nop 0
	v_permlane16_swap_b32_e32 v224, v225
	v_cndmask_b32_e64 v39, v225, v224, s[0:1]
	v_mul_f32_e32 v38, v4, v40
	v_cmp_lt_i32_e32 vcc, 0, v177
	s_waitcnt lgkmcnt(0)
	v_mul_f32_e32 v39, v12, v39
	v_sub_f32_e32 v12, v38, v39
	v_add_f32_e32 v38, v38, v39
	v_cndmask_b32_e64 v38, v4, v38, s[0:1]
	v_cndmask_b32_e32 v12, v12, v38, vcc
	v_mov_b32_e32 v224, v5
	v_mov_b32_e32 v225, v5
	v_cmp_eq_u32_e64 s[0:1], 1, v177
	s_nop 0
	v_permlane16_swap_b32_e32 v224, v225
	v_cndmask_b32_e64 v39, v225, v224, s[0:1]
	v_mul_f32_e32 v38, v5, v41
	v_cmp_lt_i32_e32 vcc, 0, v177
	s_waitcnt lgkmcnt(0)
	v_mul_f32_e32 v39, v13, v39
	v_sub_f32_e32 v13, v38, v39
	v_add_f32_e32 v38, v38, v39
	v_cndmask_b32_e64 v38, v5, v38, s[0:1]
	v_cndmask_b32_e32 v13, v13, v38, vcc
	v_mov_b32_e32 v224, v6
	v_mov_b32_e32 v225, v6
	v_cmp_eq_u32_e64 s[0:1], 1, v177
	s_nop 0
	v_permlane16_swap_b32_e32 v224, v225
	v_cndmask_b32_e64 v38, v225, v224, s[0:1]
	s_waitcnt vmcnt(0)
	v_mul_f32_e32 v34, v6, v34
	v_cmp_lt_i32_e32 vcc, 0, v177
	s_waitcnt lgkmcnt(0)
	v_mul_f32_e32 v38, v14, v38
	v_sub_f32_e32 v14, v34, v38
	v_add_f32_e32 v34, v34, v38
	v_cndmask_b32_e64 v34, v6, v34, s[0:1]
	v_cndmask_b32_e32 v14, v14, v34, vcc
	v_mov_b32_e32 v224, v7
	v_mov_b32_e32 v225, v7
	v_cmp_eq_u32_e64 s[0:1], 1, v177
	s_nop 0
	v_permlane16_swap_b32_e32 v224, v225
	v_cndmask_b32_e64 v38, v225, v224, s[0:1]
	v_mul_f32_e32 v34, v7, v35
	v_cmp_lt_i32_e32 vcc, 0, v177
	s_waitcnt lgkmcnt(0)
	v_mul_f32_e32 v35, v15, v38
	v_sub_f32_e32 v15, v34, v35
	v_add_f32_e32 v34, v34, v35
	v_cndmask_b32_e64 v34, v7, v34, s[0:1]
	v_cndmask_b32_e32 v15, v15, v34, vcc
	v_mov_b32_e32 v224, v8
	v_mov_b32_e32 v225, v8
	v_cmp_eq_u32_e64 s[0:1], 1, v177
	s_nop 0
	v_permlane16_swap_b32_e32 v224, v225
	v_cndmask_b32_e64 v35, v225, v224, s[0:1]
	v_mul_f32_e32 v34, v8, v36
	v_cmp_lt_i32_e32 vcc, 0, v177
	s_waitcnt lgkmcnt(0)
	v_mul_f32_e32 v35, v16, v35
	v_sub_f32_e32 v16, v34, v35
	v_add_f32_e32 v34, v34, v35
	v_cndmask_b32_e64 v34, v8, v34, s[0:1]
	v_cndmask_b32_e32 v16, v16, v34, vcc
	v_mov_b32_e32 v224, v9
	v_mov_b32_e32 v225, v9
	v_cmp_eq_u32_e64 s[0:1], 1, v177
	s_nop 0
	v_permlane16_swap_b32_e32 v224, v225
	v_cndmask_b32_e64 v35, v225, v224, s[0:1]
	v_mul_f32_e32 v34, v9, v37
	v_cmp_lt_i32_e32 vcc, 0, v177
	s_waitcnt lgkmcnt(0)
	v_mul_f32_e32 v35, v17, v35
	v_sub_f32_e32 v17, v34, v35
	v_add_f32_e32 v34, v34, v35
	v_cndmask_b32_e64 v34, v9, v34, s[0:1]
	v_cndmask_b32_e32 v17, v17, v34, vcc

; DI void rope8(float (&v)[8], const float* __restrict__ rope, int s, int fq) {
;     const f32x4 c0 = *(const f32x4*)(rope + s * 16), c1 = *(const f32x4*)(rope + s * 16 + 4), s0 = *(const f32x4*)(rope + s * 16 + 8), s1 = *(const f32x4*)(rope + s * 16 + 12);
;     const float cs[8] = {c0[0], c0[1], c0[2], c0[3], c1[0], c1[1], c1[2], c1[3]}, sn[8] = {s0[0], s0[1], s0[2], s0[3], s1[0], s1[1], s1[2], s1[3]};
; #pragma unroll
;     for (int e = 0; e < 8; ++e) {
;         const float other = __shfl_xor(v[e], 16);
;         const float a = v[e] * cs[e], bq = other * sn[e];
;         v[e] = (fq == 0) ? (a - bq) : ((fq == 1) ? (a + bq) : v[e]);
;     }
;     DI void operator()(const pg8::f32x4 (&acc)[2][2][4][2], const pg8::Unit& u, int wr, int wc, int fr, int fq) const {
;     ...
;                         if ((wc & 1) == 0) rope8(v, rope, s, fq);
.LBB0_2418:
	s_andn2_b64 vcc, exec, s[10:11]
	s_cbranch_vccnz .LBB0_2468
	v_and_b32_e32 v11, 64, v188
	v_xor_b32_e32 v10, 16, v188
	v_add_u32_e32 v11, 64, v11
	v_cmp_lt_i32_e32 vcc, v10, v11
	v_lshlrev_b32_e32 v26, 6, v35
	s_nop 0
	v_cndmask_b32_e32 v10, v188, v10, vcc
	v_lshlrev_b32_e32 v36, 2, v10
	global_load_dwordx4 v[30:33], v26, s[68:69]
	global_load_dwordx4 v[10:13], v26, s[68:69] offset:32
	global_load_dwordx4 v[14:17], v26, s[68:69] offset:48
	s_nop 0
	global_load_dwordx4 v[26:29], v26, s[68:69] offset:16
	v_mov_b32_e32 v224, v2
	v_mov_b32_e32 v225, v2
	v_cmp_eq_u32_e64 s[0:1], 1, v177
	s_nop 0
	v_permlane16_swap_b32_e32 v224, v225
	v_cndmask_b32_e64 v37, v225, v224, s[0:1]
	v_cmp_lt_i32_e32 vcc, 0, v177
	s_waitcnt vmcnt(3)
	v_mul_f32_e32 v30, v2, v30
	s_waitcnt vmcnt(2) lgkmcnt(0)
	v_mul_f32_e32 v37, v10, v37
	v_sub_f32_e32 v10, v30, v37
	v_add_f32_e32 v30, v30, v37
	v_cndmask_b32_e64 v30, v2, v30, s[0:1]
	v_cndmask_b32_e32 v10, v10, v30, vcc
	v_mov_b32_e32 v224, v3
	v_mov_b32_e32 v225, v3
	v_cmp_eq_u32_e64 s[0:1], 1, v177
	s_nop 0
	v_permlane16_swap_b32_e32 v224, v225
	v_cndmask_b32_e64 v37, v225, v224, s[0:1]
	v_mul_f32_e32 v30, v3, v31
	v_cmp_lt_i32_e32 vcc, 0, v177
	s_waitcnt lgkmcnt(0)
	v_mul_f32_e32 v31, v11, v37
	v_sub_f32_e32 v11, v30, v31
	v_add_f32_e32 v30, v30, v31
	v_cndmask_b32_e64 v30, v3, v30, s[0:1]
	v_cndmask_b32_e32 v11, v11, v30, vcc
	v_mov_b32_e32 v224, v4
	v_mov_b32_e32 v225, v4
	v_cmp_eq_u32_e64 s[0:1], 1, v177
	s_nop 0
	v_permlane16_swap_b32_e32 v224, v225
	v_cndmask_b32_e64 v31, v225, v224, s[0:1]
	v_mul_f32_e32 v30, v4, v32
	v_cmp_lt_i32_e32 vcc, 0, v177
	s_waitcnt lgkmcnt(0)
	v_mul_f32_e32 v31, v12, v31
	v_sub_f32_e32 v12, v30, v31
	v_add_f32_e32 v30, v30, v31
	v_cndmask_b32_e64 v30, v4, v30, s[0:1]
	v_cndmask_b32_e32 v12, v12, v30, vcc
	v_mov_b32_e32 v224, v5
	v_mov_b32_e32 v225, v5
	v_cmp_eq_u32_e64 s[0:1], 1, v177
	s_nop 0
	v_permlane16_swap_b32_e32 v224, v225
	v_cndmask_b32_e64 v31, v225, v224, s[0:1]
	v_mul_f32_e32 v30, v5, v33
	v_cmp_lt_i32_e32 vcc, 0, v177
	s_waitcnt lgkmcnt(0)
	v_mul_f32_e32 v31, v13, v31
	v_sub_f32_e32 v13, v30, v31
	v_add_f32_e32 v30, v30, v31
	v_cndmask_b32_e64 v30, v5, v30, s[0:1]
	v_cndmask_b32_e32 v13, v13, v30, vcc
	v_mov_b32_e32 v224, v6
	v_mov_b32_e32 v225, v6
	v_cmp_eq_u32_e64 s[0:1], 1, v177
	s_nop 0
	v_permlane16_swap_b32_e32 v224, v225
	v_cndmask_b32_e64 v30, v225, v224, s[0:1]
	s_waitcnt vmcnt(0)
	v_mul_f32_e32 v26, v6, v26
	v_cmp_lt_i32_e32 vcc, 0, v177
	s_waitcnt lgkmcnt(0)
	v_mul_f32_e32 v30, v14, v30
	v_sub_f32_e32 v14, v26, v30
	v_add_f32_e32 v26, v26, v30
	v_cndmask_b32_e64 v26, v6, v26, s[0:1]
	v_cndmask_b32_e32 v14, v14, v26, vcc
	v_mov_b32_e32 v224, v7
	v_mov_b32_e32 v225, v7
	v_cmp_eq_u32_e64 s[0:1], 1, v177
	s_nop 0
	v_permlane16_swap_b32_e32 v224, v225
	v_cndmask_b32_e64 v30, v225, v224, s[0:1]
	v_mul_f32_e32 v26, v7, v27
	v_cmp_lt_i32_e32 vcc, 0, v177
	s_waitcnt lgkmcnt(0)
	v_mul_f32_e32 v27, v15, v30
	v_sub_f32_e32 v15, v26, v27
	v_add_f32_e32 v26, v26, v27
	v_cndmask_b32_e64 v26, v7, v26, s[0:1]
	v_cndmask_b32_e32 v15, v15, v26, vcc
	v_mov_b32_e32 v224, v8
	v_mov_b32_e32 v225, v8
	v_cmp_eq_u32_e64 s[0:1], 1, v177
	s_nop 0
	v_permlane16_swap_b32_e32 v224, v225
	v_cndmask_b32_e64 v27, v225, v224, s[0:1]
	v_mul_f32_e32 v26, v8, v28
	v_cmp_lt_i32_e32 vcc, 0, v177
	s_waitcnt lgkmcnt(0)
	v_mul_f32_e32 v27, v16, v27
	v_sub_f32_e32 v16, v26, v27
	v_add_f32_e32 v26, v26, v27
	v_cndmask_b32_e64 v26, v8, v26, s[0:1]
	v_cndmask_b32_e32 v16, v16, v26, vcc
	v_mov_b32_e32 v224, v9
	v_mov_b32_e32 v225, v9
	v_cmp_eq_u32_e64 s[0:1], 1, v177
	s_nop 0
	v_permlane16_swap_b32_e32 v224, v225
	v_cndmask_b32_e64 v27, v225, v224, s[0:1]
	v_mul_f32_e32 v26, v9, v29
	v_cmp_lt_i32_e32 vcc, 0, v177
	s_waitcnt lgkmcnt(0)
	v_mul_f32_e32 v27, v17, v27
	v_sub_f32_e32 v17, v26, v27
	v_add_f32_e32 v26, v26, v27
	v_cndmask_b32_e64 v26, v9, v26, s[0:1]
	v_cndmask_b32_e32 v17, v17, v26, vcc

; DI void rope8(float (&v)[8], const float* __restrict__ rope, int s, int fq) {
;     const f32x4 c0 = *(const f32x4*)(rope + s * 16), c1 = *(const f32x4*)(rope + s * 16 + 4), s0 = *(const f32x4*)(rope + s * 16 + 8), s1 = *(const f32x4*)(rope + s * 16 + 12);
;     const float cs[8] = {c0[0], c0[1], c0[2], c0[3], c1[0], c1[1], c1[2], c1[3]}, sn[8] = {s0[0], s0[1], s0[2], s0[3], s1[0], s1[1], s1[2], s1[3]};
; #pragma unroll
;     for (int e = 0; e < 8; ++e) {
;         const float other = __shfl_xor(v[e], 16);
;         const float a = v[e] * cs[e], bq = other * sn[e];
;         v[e] = (fq == 0) ? (a - bq) : ((fq == 1) ? (a + bq) : v[e]);
;     }
;     DI void operator()(const pg8::f32x4 (&acc)[2][2][4][2], const pg8::Unit& u, int wr, int wc, int fr, int fq) const {
;     ...
;                         if ((wc & 1) == 0) rope8(v, rope, s, fq);
.LBB0_2474:
	s_andn2_b64 vcc, exec, s[6:7]
	s_cbranch_vccnz .LBB0_2524
	v_and_b32_e32 v11, 64, v188
	v_xor_b32_e32 v10, 16, v188
	v_add_u32_e32 v11, 64, v11
	v_cmp_lt_i32_e32 vcc, v10, v11
	v_lshlrev_b32_e32 v18, 6, v27
	s_nop 0
	v_cndmask_b32_e32 v10, v188, v10, vcc
	v_lshlrev_b32_e32 v28, 2, v10
	global_load_dwordx4 v[22:25], v18, s[68:69]
	global_load_dwordx4 v[10:13], v18, s[68:69] offset:32
	global_load_dwordx4 v[14:17], v18, s[68:69] offset:48
	s_nop 0
	global_load_dwordx4 v[18:21], v18, s[68:69] offset:16
	v_mov_b32_e32 v224, v2
	v_mov_b32_e32 v225, v2
	v_cmp_eq_u32_e64 s[0:1], 1, v177
	s_nop 0
	v_permlane16_swap_b32_e32 v224, v225
	v_cndmask_b32_e64 v29, v225, v224, s[0:1]
	v_cmp_lt_i32_e32 vcc, 0, v177
	s_waitcnt vmcnt(3)
	v_mul_f32_e32 v22, v2, v22
	s_waitcnt vmcnt(2) lgkmcnt(0)
	v_mul_f32_e32 v29, v10, v29
	v_sub_f32_e32 v10, v22, v29
	v_add_f32_e32 v22, v22, v29
	v_cndmask_b32_e64 v22, v2, v22, s[0:1]
	v_cndmask_b32_e32 v10, v10, v22, vcc
	v_mov_b32_e32 v224, v3
	v_mov_b32_e32 v225, v3
	v_cmp_eq_u32_e64 s[0:1], 1, v177
	s_nop 0
	v_permlane16_swap_b32_e32 v224, v225
	v_cndmask_b32_e64 v29, v225, v224, s[0:1]
	v_mul_f32_e32 v22, v3, v23
	v_cmp_lt_i32_e32 vcc, 0, v177
	s_waitcnt lgkmcnt(0)
	v_mul_f32_e32 v23, v11, v29
	v_sub_f32_e32 v11, v22, v23
	v_add_f32_e32 v22, v22, v23
	v_cndmask_b32_e64 v22, v3, v22, s[0:1]
	v_cndmask_b32_e32 v11, v11, v22, vcc
	v_mov_b32_e32 v224, v4
	v_mov_b32_e32 v225, v4
	v_cmp_eq_u32_e64 s[0:1], 1, v177
	s_nop 0
	v_permlane16_swap_b32_e32 v224, v225
	v_cndmask_b32_e64 v23, v225, v224, s[0:1]
	v_mul_f32_e32 v22, v4, v24
	v_cmp_lt_i32_e32 vcc, 0, v177
	s_waitcnt lgkmcnt(0)
	v_mul_f32_e32 v23, v12, v23
	v_sub_f32_e32 v12, v22, v23
	v_add_f32_e32 v22, v22, v23
	v_cndmask_b32_e64 v22, v4, v22, s[0:1]
	v_cndmask_b32_e32 v12, v12, v22, vcc
	v_mov_b32_e32 v224, v5
	v_mov_b32_e32 v225, v5
	v_cmp_eq_u32_e64 s[0:1], 1, v177
	s_nop 0
	v_permlane16_swap_b32_e32 v224, v225
	v_cndmask_b32_e64 v23, v225, v224, s[0:1]
	v_mul_f32_e32 v22, v5, v25
	v_cmp_lt_i32_e32 vcc, 0, v177
	s_waitcnt lgkmcnt(0)
	v_mul_f32_e32 v23, v13, v23
	v_sub_f32_e32 v13, v22, v23
	v_add_f32_e32 v22, v22, v23
	v_cndmask_b32_e64 v22, v5, v22, s[0:1]
	v_cndmask_b32_e32 v13, v13, v22, vcc
	v_mov_b32_e32 v224, v6
	v_mov_b32_e32 v225, v6
	v_cmp_eq_u32_e64 s[0:1], 1, v177
	s_nop 0
	v_permlane16_swap_b32_e32 v224, v225
	v_cndmask_b32_e64 v22, v225, v224, s[0:1]
	s_waitcnt vmcnt(0)
	v_mul_f32_e32 v18, v6, v18
	v_cmp_lt_i32_e32 vcc, 0, v177
	s_waitcnt lgkmcnt(0)
	v_mul_f32_e32 v22, v14, v22
	v_sub_f32_e32 v14, v18, v22
	v_add_f32_e32 v18, v18, v22
	v_cndmask_b32_e64 v18, v6, v18, s[0:1]
	v_cndmask_b32_e32 v14, v14, v18, vcc
	v_mov_b32_e32 v224, v7
	v_mov_b32_e32 v225, v7
	v_cmp_eq_u32_e64 s[0:1], 1, v177
	s_nop 0
	v_permlane16_swap_b32_e32 v224, v225
	v_cndmask_b32_e64 v22, v225, v224, s[0:1]
	v_mul_f32_e32 v18, v7, v19
	v_cmp_lt_i32_e32 vcc, 0, v177
	s_waitcnt lgkmcnt(0)
	v_mul_f32_e32 v19, v15, v22
	v_sub_f32_e32 v15, v18, v19
	v_add_f32_e32 v18, v18, v19
	v_cndmask_b32_e64 v18, v7, v18, s[0:1]
	v_cndmask_b32_e32 v15, v15, v18, vcc
	v_mov_b32_e32 v224, v8
	v_mov_b32_e32 v225, v8
	v_cmp_eq_u32_e64 s[0:1], 1, v177
	s_nop 0
	v_permlane16_swap_b32_e32 v224, v225
	v_cndmask_b32_e64 v19, v225, v224, s[0:1]
	v_mul_f32_e32 v18, v8, v20
	v_cmp_lt_i32_e32 vcc, 0, v177
	s_waitcnt lgkmcnt(0)
	v_mul_f32_e32 v19, v16, v19
	v_sub_f32_e32 v16, v18, v19
	v_add_f32_e32 v18, v18, v19
	v_cndmask_b32_e64 v18, v8, v18, s[0:1]
	v_cndmask_b32_e32 v16, v16, v18, vcc
	v_mov_b32_e32 v224, v9
	v_mov_b32_e32 v225, v9
	v_cmp_eq_u32_e64 s[0:1], 1, v177
	s_nop 0
	v_permlane16_swap_b32_e32 v224, v225
	v_cndmask_b32_e64 v19, v225, v224, s[0:1]
	v_mul_f32_e32 v18, v9, v21
	v_cmp_lt_i32_e32 vcc, 0, v177
	s_waitcnt lgkmcnt(0)
	v_mul_f32_e32 v19, v17, v19
	v_sub_f32_e32 v17, v18, v19
	v_add_f32_e32 v18, v18, v19
	v_cndmask_b32_e64 v18, v9, v18, s[0:1]
	v_cndmask_b32_e32 v17, v17, v18, vcc
